# stack of all validated micro-edits: saddr K-loops with rotated scalar setup and trimmed MFMA path, attention pads removed and wide epilogue stores, nt in-register transposes, hoisted rmsnorm gains
# speedup vs baseline: 1.0049x; 1.0049x over previous
; #define PG8_STAGE(bufoff, gbase, voff) do { _Pragma("unroll") for (int _i = 0; _i < 2; ++_i) \
;         __builtin_amdgcn_global_load_lds((const unsigned*)((const char*)(gbase) + (voff)[_i]), (PG8_LAS unsigned*)(lds + (bufoff) + ldsw + _i * 8192), 16, 0, 0); } while (0)
; #define PG8_LDA(dst, b, h) do { _Pragma("unroll") for (int m = 0; m < 4; ++m) _Pragma("unroll") for (int k = 0; k < 2; ++k) dst[m][k] = *(const PG8_LAS bf16x8*)(lds + PG8_SA(b, h) + aoff + m * 2048 + k * 1024); } while (0)
; #define PG8_LDB(dst, b, h) do { _Pragma("unroll") for (int n = 0; n < 2; ++n) _Pragma("unroll") for (int k = 0; k < 2; ++k) dst[n][k] = *(const PG8_LAS bf16x8*)(lds + PG8_SB(b, h) + boff + n * 2048 + k * 1024); } while (0)
; #define PG8_MMA(ai, bj, At, Bt) do { __builtin_amdgcn_s_setprio(1); _Pragma("unroll") for (int m = 0; m < 4; ++m) _Pragma("unroll") for (int n = 0; n < 2; ++n) _Pragma("unroll") for (int k = 0; k < 2; ++k) \
;         acc[ai][bj][m][n] = __builtin_amdgcn_mfma_f32_16x16x32_bf16(Bt[n][k], At[m][k], acc[ai][bj][m][n], 0, 0, 0); __builtin_amdgcn_s_setprio(0); } while (0)
; #define PG8_WAIT_V(n) asm volatile("s_waitcnt vmcnt(" #n ")" ::: "memory")
; #define PG8_WAIT_L(n) asm volatile("s_waitcnt lgkmcnt(" #n ")" ::: "memory")
; template <class Epi, class Sched, bool ALIGN_EPI = false, bool SP2 = false>
; __device__ __forceinline__ void gemm_phase(PG8_LAS unsigned char* lds, const Gemm g, const Sched& S, const Epi& E) {
;     ...
;             const bool last = (t == nt - 2);
;             const char* a1 = cA + (size_t)(t + 1) * kstep;
;             const char* a2 = last ? nA : cA + (size_t)(t + 2) * kstep; const char* b2 = last ? nB : cB + (size_t)(t + 2) * kstep;
;             const char* a3 = a2 + kstep; const char* b3 = b2 + kstep;
;             if (last && has_next) S.a_ready(nxt);
;             if constexpr (SP2) {
;             PG8_LDB(B0, 0, 0); PG8_LDB(B1, 0, 1); PG8_SCHED; PG8_LDA(At, 0, 0); PG8_STAGE(PG8_SA(1, 1), a1 + hstep, voffA);
;             PG8_WAIT_V(8); PG8_WAIT_L(0); PG8_BAR; PG8_MMA(0, 0, At, B0); PG8_MMA(0, 1, At, B1); PG8_BAR; PG8_SCHED;
;             PG8_LDA(At, 0, 1); PG8_STAGE(PG8_SB(0, 0), b2, voffB); PG8_STAGE(PG8_SB(0, 1), b2 + hstep, voffB); PG8_STAGE(PG8_SA(0, 0), a2, voffA);
;             PG8_WAIT_V(8); PG8_WAIT_L(0); PG8_BAR; PG8_MMA(1, 0, At, B0); PG8_MMA(1, 1, At, B1); PG8_BAR; PG8_SCHED;
.LBB0_67:
	ds_read_b128 v[128:131], v159
	ds_read_b128 v[152:155], v159 offset:1024
	ds_read_b128 v[162:165], v159 offset:2048
	ds_read_b128 v[166:169], v159 offset:3072
	ds_read_b128 v[170:173], v160
	ds_read_b128 v[174:177], v160 offset:1024
	ds_read_b128 v[178:181], v160 offset:2048
	ds_read_b128 v[182:185], v160 offset:3072
	s_add_i32 m0, s1, 0xc000
	ds_read_b128 v[186:189], v161
	ds_read_b128 v[190:193], v161 offset:1024
	ds_read_b128 v[194:197], v161 offset:2048
	ds_read_b128 v[200:203], v161 offset:3072
	ds_read_b128 v[204:207], v161 offset:4096
	ds_read_b128 v[208:211], v161 offset:5120
	ds_read_b128 v[212:215], v161 offset:6144
	ds_read_b128 v[216:219], v161 offset:7168
	global_load_lds_dwordx4 v144, s[74:75]
	s_add_i32 m0, s1, 0xe000
	s_nop 0
	global_load_lds_dwordx4 v146, s[74:75]
	s_add_u32 s76, s74, 0xfff80080
	s_addc_u32 s77, s75, -1
	s_cmp_eq_u32 s88, 28
	s_cselect_b32 s79, s5, s77
	s_cselect_b32 s78, s14, s76
	s_cselect_b32 s77, s24, s69
	s_cselect_b32 s76, s25, s67
	s_add_i32 s89, s85, s0
	s_mov_b32 m0, s89
	s_waitcnt vmcnt(8)
	s_waitcnt lgkmcnt(0)
	s_setprio 1
	s_barrier
	v_mfma_f32_16x16x32_bf16 v[124:127], v[128:131], v[186:189], v[124:127]
	v_mfma_f32_16x16x32_bf16 v[120:123], v[162:165], v[186:189], v[120:123]
	v_mfma_f32_16x16x32_bf16 v[108:111], v[128:131], v[194:197], v[108:111]
	v_mfma_f32_16x16x32_bf16 v[104:107], v[162:165], v[194:197], v[104:107]
	v_mfma_f32_16x16x32_bf16 v[92:95], v[128:131], v[204:207], v[92:95]
	v_mfma_f32_16x16x32_bf16 v[88:91], v[162:165], v[204:207], v[88:91]
	v_mfma_f32_16x16x32_bf16 v[76:79], v[128:131], v[212:215], v[76:79]
	v_mfma_f32_16x16x32_bf16 v[72:75], v[162:165], v[212:215], v[72:75]
	v_mfma_f32_16x16x32_bf16 v[124:127], v[152:155], v[190:193], v[124:127]
	v_mfma_f32_16x16x32_bf16 v[120:123], v[166:169], v[190:193], v[120:123]
	v_mfma_f32_16x16x32_bf16 v[108:111], v[152:155], v[200:203], v[108:111]
	v_mfma_f32_16x16x32_bf16 v[104:107], v[166:169], v[200:203], v[104:107]
	v_mfma_f32_16x16x32_bf16 v[92:95], v[152:155], v[208:211], v[92:95]
	v_mfma_f32_16x16x32_bf16 v[88:91], v[166:169], v[208:211], v[88:91]
	v_mfma_f32_16x16x32_bf16 v[76:79], v[152:155], v[216:219], v[76:79]
	v_mfma_f32_16x16x32_bf16 v[72:75], v[166:169], v[216:219], v[72:75]
	v_mfma_f32_16x16x32_bf16 v[116:119], v[170:173], v[186:189], v[116:119]
	v_mfma_f32_16x16x32_bf16 v[112:115], v[178:181], v[186:189], v[112:115]
	v_mfma_f32_16x16x32_bf16 v[100:103], v[170:173], v[194:197], v[100:103]
	v_mfma_f32_16x16x32_bf16 v[96:99], v[178:181], v[194:197], v[96:99]
	v_mfma_f32_16x16x32_bf16 v[84:87], v[170:173], v[204:207], v[84:87]
	v_mfma_f32_16x16x32_bf16 v[80:83], v[178:181], v[204:207], v[80:83]
	v_mfma_f32_16x16x32_bf16 v[68:71], v[170:173], v[212:215], v[68:71]
	v_mfma_f32_16x16x32_bf16 v[64:67], v[178:181], v[212:215], v[64:67]
	v_mfma_f32_16x16x32_bf16 v[116:119], v[174:177], v[190:193], v[116:119]
	v_mfma_f32_16x16x32_bf16 v[112:115], v[182:185], v[190:193], v[112:115]
	v_mfma_f32_16x16x32_bf16 v[100:103], v[174:177], v[200:203], v[100:103]
	v_mfma_f32_16x16x32_bf16 v[96:99], v[182:185], v[200:203], v[96:99]
	v_mfma_f32_16x16x32_bf16 v[84:87], v[174:177], v[208:211], v[84:87]
	v_mfma_f32_16x16x32_bf16 v[80:83], v[182:185], v[208:211], v[80:83]
	v_mfma_f32_16x16x32_bf16 v[68:71], v[174:177], v[216:219], v[68:71]
	v_mfma_f32_16x16x32_bf16 v[64:67], v[182:185], v[216:219], v[64:67]
	s_setprio 0
	s_barrier
	ds_read_b128 v[186:189], v161 offset:16384
	ds_read_b128 v[190:193], v161 offset:17408
	ds_read_b128 v[194:197], v161 offset:18432
	ds_read_b128 v[200:203], v161 offset:19456
	ds_read_b128 v[204:207], v161 offset:20480
	ds_read_b128 v[208:211], v161 offset:21504
	ds_read_b128 v[212:215], v161 offset:22528
	ds_read_b128 v[216:219], v161 offset:23552
	global_load_lds_dwordx4 v134, s[76:77]
	s_add_i32 m0, s89, 0x2000
	s_add_u32 s96, s76, 0x80000
	s_addc_u32 s97, s77, 0
	s_add_i32 s89, s86, s0
	global_load_lds_dwordx4 v138, s[76:77]
	s_mov_b32 m0, s89
	s_nop 0
	global_load_lds_dwordx4 v134, s[96:97]
	s_add_i32 m0, s89, 0x2000
	s_nop 0
	global_load_lds_dwordx4 v138, s[96:97]
	s_mov_b32 m0, s1
	s_nop 0
	global_load_lds_dwordx4 v132, s[78:79]
	s_mov_b32 m0, s11
	s_nop 0
	global_load_lds_dwordx4 v136, s[78:79]
	s_waitcnt vmcnt(8)
	s_waitcnt lgkmcnt(0)
	s_setprio 1
	s_barrier
	v_mfma_f32_16x16x32_bf16 v[60:63], v[128:131], v[186:189], v[60:63]
	v_mfma_f32_16x16x32_bf16 v[56:59], v[162:165], v[186:189], v[56:59]
	v_mfma_f32_16x16x32_bf16 v[44:47], v[128:131], v[194:197], v[44:47]
	v_mfma_f32_16x16x32_bf16 v[40:43], v[162:165], v[194:197], v[40:43]
	v_mfma_f32_16x16x32_bf16 v[28:31], v[128:131], v[204:207], v[28:31]
	v_mfma_f32_16x16x32_bf16 v[24:27], v[162:165], v[204:207], v[24:27]
	v_mfma_f32_16x16x32_bf16 v[12:15], v[128:131], v[212:215], v[12:15]
	v_mfma_f32_16x16x32_bf16 v[8:11], v[162:165], v[212:215], v[8:11]
	v_mfma_f32_16x16x32_bf16 v[60:63], v[152:155], v[190:193], v[60:63]
	v_mfma_f32_16x16x32_bf16 v[56:59], v[166:169], v[190:193], v[56:59]
	v_mfma_f32_16x16x32_bf16 v[44:47], v[152:155], v[200:203], v[44:47]
	v_mfma_f32_16x16x32_bf16 v[40:43], v[166:169], v[200:203], v[40:43]
	v_mfma_f32_16x16x32_bf16 v[28:31], v[152:155], v[208:211], v[28:31]
	v_mfma_f32_16x16x32_bf16 v[24:27], v[166:169], v[208:211], v[24:27]
	v_mfma_f32_16x16x32_bf16 v[12:15], v[152:155], v[216:219], v[12:15]
	v_mfma_f32_16x16x32_bf16 v[8:11], v[166:169], v[216:219], v[8:11]
	v_mfma_f32_16x16x32_bf16 v[52:55], v[170:173], v[186:189], v[52:55]
	v_mfma_f32_16x16x32_bf16 v[48:51], v[178:181], v[186:189], v[48:51]
	v_mfma_f32_16x16x32_bf16 v[36:39], v[170:173], v[194:197], v[36:39]
	v_mfma_f32_16x16x32_bf16 v[32:35], v[178:181], v[194:197], v[32:35]
	v_mfma_f32_16x16x32_bf16 v[20:23], v[170:173], v[204:207], v[20:23]
	v_mfma_f32_16x16x32_bf16 v[16:19], v[178:181], v[204:207], v[16:19]
	v_mfma_f32_16x16x32_bf16 v[4:7], v[170:173], v[212:215], v[4:7]
	v_mfma_f32_16x16x32_bf16 v[0:3], v[178:181], v[212:215], v[0:3]
	v_mfma_f32_16x16x32_bf16 v[52:55], v[174:177], v[190:193], v[52:55]
	v_mfma_f32_16x16x32_bf16 v[48:51], v[182:185], v[190:193], v[48:51]
	v_mfma_f32_16x16x32_bf16 v[36:39], v[174:177], v[200:203], v[36:39]
	v_mfma_f32_16x16x32_bf16 v[32:35], v[182:185], v[200:203], v[32:35]
	v_mfma_f32_16x16x32_bf16 v[20:23], v[174:177], v[208:211], v[20:23]
	v_mfma_f32_16x16x32_bf16 v[16:19], v[182:185], v[208:211], v[16:19]
	v_mfma_f32_16x16x32_bf16 v[4:7], v[174:177], v[216:219], v[4:7]
	v_mfma_f32_16x16x32_bf16 v[0:3], v[182:185], v[216:219], v[0:3]
	s_setprio 0
	s_barrier
; #define PG8_STAGE(bufoff, gbase, voff) do { _Pragma("unroll") for (int _i = 0; _i < 2; ++_i) \
;         __builtin_amdgcn_global_load_lds((const unsigned*)((const char*)(gbase) + (voff)[_i]), (PG8_LAS unsigned*)(lds + (bufoff) + ldsw + _i * 8192), 16, 0, 0); } while (0)
; #define PG8_LDA(dst, b, h) do { _Pragma("unroll") for (int m = 0; m < 4; ++m) _Pragma("unroll") for (int k = 0; k < 2; ++k) dst[m][k] = *(const PG8_LAS bf16x8*)(lds + PG8_SA(b, h) + aoff + m * 2048 + k * 1024); } while (0)
; #define PG8_LDB(dst, b, h) do { _Pragma("unroll") for (int n = 0; n < 2; ++n) _Pragma("unroll") for (int k = 0; k < 2; ++k) dst[n][k] = *(const PG8_LAS bf16x8*)(lds + PG8_SB(b, h) + boff + n * 2048 + k * 1024); } while (0)
; #define PG8_MMA(ai, bj, At, Bt) do { __builtin_amdgcn_s_setprio(1); _Pragma("unroll") for (int m = 0; m < 4; ++m) _Pragma("unroll") for (int n = 0; n < 2; ++n) _Pragma("unroll") for (int k = 0; k < 2; ++k) \
;         acc[ai][bj][m][n] = __builtin_amdgcn_mfma_f32_16x16x32_bf16(Bt[n][k], At[m][k], acc[ai][bj][m][n], 0, 0, 0); __builtin_amdgcn_s_setprio(0); } while (0)
; #define PG8_WAIT_V(n) asm volatile("s_waitcnt vmcnt(" #n ")" ::: "memory")
; #define PG8_WAIT_L(n) asm volatile("s_waitcnt lgkmcnt(" #n ")" ::: "memory")
; #define PG8_BAR __builtin_amdgcn_s_barrier()
; #define PG8_SCHED __builtin_amdgcn_sched_barrier(0)
; template <class Epi, class Sched, bool ALIGN_EPI = false, bool SP2 = false>
; __device__ __forceinline__ void gemm_phase(PG8_LAS unsigned char* lds, const Gemm g, const Sched& S, const Epi& E) {
;     ...
;         for (int t = 0; t < nt; t += 2) {
;     ...
;             PG8_LDB(B0, 1, 0); PG8_LDB(B1, 1, 1); PG8_SCHED; PG8_LDA(At, 1, 0); PG8_STAGE(PG8_SA(0, 1), a2 + hstep, voffA);
;             PG8_WAIT_V(8); PG8_WAIT_L(0); PG8_BAR; PG8_MMA(0, 0, At, B0); PG8_MMA(0, 1, At, B1); PG8_BAR; PG8_SCHED;
;             PG8_LDA(At, 1, 1); PG8_STAGE(PG8_SB(1, 0), b3, voffB); PG8_STAGE(PG8_SB(1, 1), b3 + hstep, voffB); PG8_STAGE(PG8_SA(1, 0), a3, voffA);
;             PG8_WAIT_V(8); PG8_WAIT_L(0); PG8_BAR; PG8_MMA(1, 0, At, B0); PG8_MMA(1, 1, At, B1); PG8_BAR; PG8_SCHED;
	ds_read_b128 v[128:131], v198
	ds_read_b128 v[152:155], v198 offset:1024
	ds_read_b128 v[162:165], v198 offset:2048
	ds_read_b128 v[166:169], v198 offset:3072
	ds_read_b128 v[170:173], v199
	ds_read_b128 v[174:177], v199 offset:1024
	ds_read_b128 v[178:181], v199 offset:2048
	ds_read_b128 v[182:185], v199 offset:3072
	ds_read_b128 v[186:189], v161 offset:32768
	ds_read_b128 v[190:193], v161 offset:33792
	ds_read_b128 v[194:197], v161 offset:34816
	ds_read_b128 v[200:203], v161 offset:35840
	ds_read_b128 v[204:207], v161 offset:36864
	ds_read_b128 v[208:211], v161 offset:37888
	ds_read_b128 v[212:215], v161 offset:38912
	ds_read_b128 v[216:219], v161 offset:39936
	s_add_u32 s98, s78, 0x80000
	s_addc_u32 s99, s79, 0
	s_mov_b32 m0, s33
	s_add_u32 s100, s78, 0x80
	s_addc_u32 s101, s79, 0
	global_load_lds_dwordx4 v132, s[98:99]
	s_mov_b32 m0, s35
	s_nop 0
	global_load_lds_dwordx4 v136, s[98:99]
	s_add_i32 s89, 0, 0x18000
	s_add_i32 s94, 0, 0x1c000
	s_add_u32 s98, s76, 0x80
	s_addc_u32 s99, s77, 0
	s_add_i32 s78, s89, s0
	s_mov_b32 m0, s78
	s_waitcnt vmcnt(8)
	s_waitcnt lgkmcnt(0)
	s_setprio 1
	s_barrier
	v_mfma_f32_16x16x32_bf16 v[124:127], v[128:131], v[186:189], v[124:127]
	v_mfma_f32_16x16x32_bf16 v[120:123], v[162:165], v[186:189], v[120:123]
	v_mfma_f32_16x16x32_bf16 v[108:111], v[128:131], v[194:197], v[108:111]
	v_mfma_f32_16x16x32_bf16 v[104:107], v[162:165], v[194:197], v[104:107]
	v_mfma_f32_16x16x32_bf16 v[92:95], v[128:131], v[204:207], v[92:95]
	v_mfma_f32_16x16x32_bf16 v[88:91], v[162:165], v[204:207], v[88:91]
	v_mfma_f32_16x16x32_bf16 v[76:79], v[128:131], v[212:215], v[76:79]
	v_mfma_f32_16x16x32_bf16 v[72:75], v[162:165], v[212:215], v[72:75]
	v_mfma_f32_16x16x32_bf16 v[124:127], v[152:155], v[190:193], v[124:127]
	v_mfma_f32_16x16x32_bf16 v[120:123], v[166:169], v[190:193], v[120:123]
	v_mfma_f32_16x16x32_bf16 v[108:111], v[152:155], v[200:203], v[108:111]
	v_mfma_f32_16x16x32_bf16 v[104:107], v[166:169], v[200:203], v[104:107]
	v_mfma_f32_16x16x32_bf16 v[92:95], v[152:155], v[208:211], v[92:95]
	v_mfma_f32_16x16x32_bf16 v[88:91], v[166:169], v[208:211], v[88:91]
	v_mfma_f32_16x16x32_bf16 v[76:79], v[152:155], v[216:219], v[76:79]
	v_mfma_f32_16x16x32_bf16 v[72:75], v[166:169], v[216:219], v[72:75]
	v_mfma_f32_16x16x32_bf16 v[116:119], v[170:173], v[186:189], v[116:119]
	v_mfma_f32_16x16x32_bf16 v[112:115], v[178:181], v[186:189], v[112:115]
	v_mfma_f32_16x16x32_bf16 v[100:103], v[170:173], v[194:197], v[100:103]
	v_mfma_f32_16x16x32_bf16 v[96:99], v[178:181], v[194:197], v[96:99]
	v_mfma_f32_16x16x32_bf16 v[84:87], v[170:173], v[204:207], v[84:87]
	v_mfma_f32_16x16x32_bf16 v[80:83], v[178:181], v[204:207], v[80:83]
	v_mfma_f32_16x16x32_bf16 v[68:71], v[170:173], v[212:215], v[68:71]
	v_mfma_f32_16x16x32_bf16 v[64:67], v[178:181], v[212:215], v[64:67]
	v_mfma_f32_16x16x32_bf16 v[116:119], v[174:177], v[190:193], v[116:119]
	v_mfma_f32_16x16x32_bf16 v[112:115], v[182:185], v[190:193], v[112:115]
	v_mfma_f32_16x16x32_bf16 v[100:103], v[174:177], v[200:203], v[100:103]
	v_mfma_f32_16x16x32_bf16 v[96:99], v[182:185], v[200:203], v[96:99]
	v_mfma_f32_16x16x32_bf16 v[84:87], v[174:177], v[208:211], v[84:87]
	v_mfma_f32_16x16x32_bf16 v[80:83], v[182:185], v[208:211], v[80:83]
	v_mfma_f32_16x16x32_bf16 v[68:71], v[174:177], v[216:219], v[68:71]
	v_mfma_f32_16x16x32_bf16 v[64:67], v[182:185], v[216:219], v[64:67]
	s_setprio 0
	s_barrier
	ds_read_b128 v[186:189], v161 offset:49152
	ds_read_b128 v[190:193], v161 offset:50176
	ds_read_b128 v[194:197], v161 offset:51200
	ds_read_b128 v[200:203], v161 offset:52224
	ds_read_b128 v[204:207], v161 offset:53248
	ds_read_b128 v[208:211], v161 offset:54272
	ds_read_b128 v[212:215], v161 offset:55296
	ds_read_b128 v[216:219], v161 offset:56320
	global_load_lds_dwordx4 v134, s[98:99]
	s_add_i32 m0, s78, 0x2000
	s_add_u32 s76, s76, 0x80080
	s_addc_u32 s77, s77, 0
	s_add_i32 s78, s94, s0
	global_load_lds_dwordx4 v138, s[98:99]
	s_mov_b32 m0, s78
	s_nop 0
	global_load_lds_dwordx4 v134, s[76:77]
	s_add_i32 m0, s78, 0x2000
	s_nop 0
	global_load_lds_dwordx4 v138, s[76:77]
	s_mov_b32 m0, s80
	s_nop 0
	global_load_lds_dwordx4 v132, s[100:101]
	s_mov_b32 m0, s81
	s_nop 0
	global_load_lds_dwordx4 v136, s[100:101]
	s_add_i32 s88, s88, 2
	s_add_u32 s74, s74, 0x100
	s_addc_u32 s75, s75, 0
	s_add_u32 s67, s67, 0x100
	s_addc_u32 s69, s69, 0
	s_cmp_gt_u32 s88, 29
	s_waitcnt vmcnt(8)
	s_waitcnt lgkmcnt(0)
	s_setprio 1
	s_barrier
	v_mfma_f32_16x16x32_bf16 v[60:63], v[128:131], v[186:189], v[60:63]
	v_mfma_f32_16x16x32_bf16 v[56:59], v[162:165], v[186:189], v[56:59]
	v_mfma_f32_16x16x32_bf16 v[44:47], v[128:131], v[194:197], v[44:47]
	v_mfma_f32_16x16x32_bf16 v[40:43], v[162:165], v[194:197], v[40:43]
	v_mfma_f32_16x16x32_bf16 v[28:31], v[128:131], v[204:207], v[28:31]
	v_mfma_f32_16x16x32_bf16 v[24:27], v[162:165], v[204:207], v[24:27]
	v_mfma_f32_16x16x32_bf16 v[12:15], v[128:131], v[212:215], v[12:15]
	v_mfma_f32_16x16x32_bf16 v[8:11], v[162:165], v[212:215], v[8:11]
	v_mfma_f32_16x16x32_bf16 v[60:63], v[152:155], v[190:193], v[60:63]
	v_mfma_f32_16x16x32_bf16 v[56:59], v[166:169], v[190:193], v[56:59]
	v_mfma_f32_16x16x32_bf16 v[44:47], v[152:155], v[200:203], v[44:47]
	v_mfma_f32_16x16x32_bf16 v[40:43], v[166:169], v[200:203], v[40:43]
	v_mfma_f32_16x16x32_bf16 v[28:31], v[152:155], v[208:211], v[28:31]
	v_mfma_f32_16x16x32_bf16 v[24:27], v[166:169], v[208:211], v[24:27]
	v_mfma_f32_16x16x32_bf16 v[12:15], v[152:155], v[216:219], v[12:15]
	v_mfma_f32_16x16x32_bf16 v[8:11], v[166:169], v[216:219], v[8:11]
	v_mfma_f32_16x16x32_bf16 v[52:55], v[170:173], v[186:189], v[52:55]
	v_mfma_f32_16x16x32_bf16 v[48:51], v[178:181], v[186:189], v[48:51]
	v_mfma_f32_16x16x32_bf16 v[36:39], v[170:173], v[194:197], v[36:39]
	v_mfma_f32_16x16x32_bf16 v[32:35], v[178:181], v[194:197], v[32:35]
	v_mfma_f32_16x16x32_bf16 v[20:23], v[170:173], v[204:207], v[20:23]
	v_mfma_f32_16x16x32_bf16 v[16:19], v[178:181], v[204:207], v[16:19]
	v_mfma_f32_16x16x32_bf16 v[4:7], v[170:173], v[212:215], v[4:7]
	v_mfma_f32_16x16x32_bf16 v[0:3], v[178:181], v[212:215], v[0:3]
	v_mfma_f32_16x16x32_bf16 v[52:55], v[174:177], v[190:193], v[52:55]
	v_mfma_f32_16x16x32_bf16 v[48:51], v[182:185], v[190:193], v[48:51]
	v_mfma_f32_16x16x32_bf16 v[36:39], v[174:177], v[200:203], v[36:39]
	v_mfma_f32_16x16x32_bf16 v[32:35], v[182:185], v[200:203], v[32:35]
	v_mfma_f32_16x16x32_bf16 v[20:23], v[174:177], v[208:211], v[20:23]
	v_mfma_f32_16x16x32_bf16 v[16:19], v[182:185], v[208:211], v[16:19]
	v_mfma_f32_16x16x32_bf16 v[4:7], v[174:177], v[216:219], v[4:7]
	v_mfma_f32_16x16x32_bf16 v[0:3], v[182:185], v[216:219], v[0:3]
	s_setprio 0
	s_barrier
	s_cbranch_scc0 .LBB0_67
	s_and_b64 vcc, exec, s[60:61]
	s_cbranch_vccz .LBB0_70
	s_barrier

; #define PG8_STAGE(bufoff, gbase, voff) do { _Pragma("unroll") for (int _i = 0; _i < 2; ++_i) \
;         __builtin_amdgcn_global_load_lds((const unsigned*)((const char*)(gbase) + (voff)[_i]), (PG8_LAS unsigned*)(lds + (bufoff) + ldsw + _i * 8192), 16, 0, 0); } while (0)
; #define PG8_LDA(dst, b, h) do { _Pragma("unroll") for (int m = 0; m < 4; ++m) _Pragma("unroll") for (int k = 0; k < 2; ++k) dst[m][k] = *(const PG8_LAS bf16x8*)(lds + PG8_SA(b, h) + aoff + m * 2048 + k * 1024); } while (0)
; #define PG8_LDB(dst, b, h) do { _Pragma("unroll") for (int n = 0; n < 2; ++n) _Pragma("unroll") for (int k = 0; k < 2; ++k) dst[n][k] = *(const PG8_LAS bf16x8*)(lds + PG8_SB(b, h) + boff + n * 2048 + k * 1024); } while (0)
; #define PG8_MMA(ai, bj, At, Bt) do { __builtin_amdgcn_s_setprio(1); _Pragma("unroll") for (int m = 0; m < 4; ++m) _Pragma("unroll") for (int n = 0; n < 2; ++n) _Pragma("unroll") for (int k = 0; k < 2; ++k) \
;         acc[ai][bj][m][n] = __builtin_amdgcn_mfma_f32_16x16x32_bf16(Bt[n][k], At[m][k], acc[ai][bj][m][n], 0, 0, 0); __builtin_amdgcn_s_setprio(0); } while (0)
; #define PG8_WAIT_V(n) asm volatile("s_waitcnt vmcnt(" #n ")" ::: "memory")
; #define PG8_WAIT_L(n) asm volatile("s_waitcnt lgkmcnt(" #n ")" ::: "memory")
; template <class Epi, class Sched, bool ALIGN_EPI = false, bool SP2 = false>
; __device__ __forceinline__ void gemm_phase(PG8_LAS unsigned char* lds, const Gemm g, const Sched& S, const Epi& E) {
;     ...
;             const bool last = (t == nt - 2);
;             const char* a1 = cA + (size_t)(t + 1) * kstep;
;             const char* a2 = last ? nA : cA + (size_t)(t + 2) * kstep; const char* b2 = last ? nB : cB + (size_t)(t + 2) * kstep;
;             const char* a3 = a2 + kstep; const char* b3 = b2 + kstep;
;             if (last && has_next) S.a_ready(nxt);
;             if constexpr (SP2) {
;             PG8_LDB(B0, 0, 0); PG8_LDB(B1, 0, 1); PG8_SCHED; PG8_LDA(At, 0, 0); PG8_STAGE(PG8_SA(1, 1), a1 + hstep, voffA);
;             PG8_WAIT_V(8); PG8_WAIT_L(0); PG8_BAR; PG8_MMA(0, 0, At, B0); PG8_MMA(0, 1, At, B1); PG8_BAR; PG8_SCHED;
;             PG8_LDA(At, 0, 1); PG8_STAGE(PG8_SB(0, 0), b2, voffB); PG8_STAGE(PG8_SB(0, 1), b2 + hstep, voffB); PG8_STAGE(PG8_SA(0, 0), a2, voffA);
;             PG8_WAIT_V(8); PG8_WAIT_L(0); PG8_BAR; PG8_MMA(1, 0, At, B0); PG8_MMA(1, 1, At, B1); PG8_BAR; PG8_SCHED;
.LBB0_245:
	ds_read_b128 v[144:147], v153
	ds_read_b128 v[156:159], v153 offset:1024
	ds_read_b128 v[160:163], v153 offset:2048
	ds_read_b128 v[164:167], v153 offset:3072
	ds_read_b128 v[168:171], v154
	ds_read_b128 v[172:175], v154 offset:1024
	ds_read_b128 v[176:179], v154 offset:2048
	ds_read_b128 v[180:183], v154 offset:3072
	s_add_i32 m0, s33, 0xc000
	ds_read_b128 v[184:187], v155
	ds_read_b128 v[188:191], v155 offset:1024
	ds_read_b128 v[192:195], v155 offset:2048
	ds_read_b128 v[200:203], v155 offset:3072
	ds_read_b128 v[204:207], v155 offset:4096
	ds_read_b128 v[208:211], v155 offset:5120
	ds_read_b128 v[212:215], v155 offset:6144
	ds_read_b128 v[216:219], v155 offset:7168
	global_load_lds_dwordx4 v136, s[70:71]
	s_add_i32 m0, s33, 0xe000
	s_nop 0
	global_load_lds_dwordx4 v138, s[70:71]
	s_add_u32 s72, s70, 0xfff80080
	s_addc_u32 s73, s71, -1
	s_cmp_eq_u32 s87, 28
	s_cselect_b32 s75, s25, s73
	s_cselect_b32 s74, s63, s72
	s_cselect_b32 s73, s61, s86
	s_cselect_b32 s72, s84, s85
	s_add_i32 s88, s82, s1
	s_mov_b32 m0, s88
	s_waitcnt vmcnt(8)
	s_waitcnt lgkmcnt(0)
	s_setprio 1
	s_barrier
	v_mfma_f32_16x16x32_bf16 v[124:127], v[144:147], v[184:187], v[124:127]
	v_mfma_f32_16x16x32_bf16 v[120:123], v[160:163], v[184:187], v[120:123]
	v_mfma_f32_16x16x32_bf16 v[108:111], v[144:147], v[192:195], v[108:111]
	v_mfma_f32_16x16x32_bf16 v[104:107], v[160:163], v[192:195], v[104:107]
	v_mfma_f32_16x16x32_bf16 v[92:95], v[144:147], v[204:207], v[92:95]
	v_mfma_f32_16x16x32_bf16 v[88:91], v[160:163], v[204:207], v[88:91]
	v_mfma_f32_16x16x32_bf16 v[76:79], v[144:147], v[212:215], v[76:79]
	v_mfma_f32_16x16x32_bf16 v[72:75], v[160:163], v[212:215], v[72:75]
	v_mfma_f32_16x16x32_bf16 v[124:127], v[156:159], v[188:191], v[124:127]
	v_mfma_f32_16x16x32_bf16 v[120:123], v[164:167], v[188:191], v[120:123]
	v_mfma_f32_16x16x32_bf16 v[108:111], v[156:159], v[200:203], v[108:111]
	v_mfma_f32_16x16x32_bf16 v[104:107], v[164:167], v[200:203], v[104:107]
	v_mfma_f32_16x16x32_bf16 v[92:95], v[156:159], v[208:211], v[92:95]
	v_mfma_f32_16x16x32_bf16 v[88:91], v[164:167], v[208:211], v[88:91]
	v_mfma_f32_16x16x32_bf16 v[76:79], v[156:159], v[216:219], v[76:79]
	v_mfma_f32_16x16x32_bf16 v[72:75], v[164:167], v[216:219], v[72:75]
	v_mfma_f32_16x16x32_bf16 v[116:119], v[168:171], v[184:187], v[116:119]
	v_mfma_f32_16x16x32_bf16 v[112:115], v[176:179], v[184:187], v[112:115]
	v_mfma_f32_16x16x32_bf16 v[100:103], v[168:171], v[192:195], v[100:103]
	v_mfma_f32_16x16x32_bf16 v[96:99], v[176:179], v[192:195], v[96:99]
	v_mfma_f32_16x16x32_bf16 v[84:87], v[168:171], v[204:207], v[84:87]
	v_mfma_f32_16x16x32_bf16 v[80:83], v[176:179], v[204:207], v[80:83]
	v_mfma_f32_16x16x32_bf16 v[68:71], v[168:171], v[212:215], v[68:71]
	v_mfma_f32_16x16x32_bf16 v[64:67], v[176:179], v[212:215], v[64:67]
	v_mfma_f32_16x16x32_bf16 v[116:119], v[172:175], v[188:191], v[116:119]
	v_mfma_f32_16x16x32_bf16 v[112:115], v[180:183], v[188:191], v[112:115]
	v_mfma_f32_16x16x32_bf16 v[100:103], v[172:175], v[200:203], v[100:103]
	v_mfma_f32_16x16x32_bf16 v[96:99], v[180:183], v[200:203], v[96:99]
	v_mfma_f32_16x16x32_bf16 v[84:87], v[172:175], v[208:211], v[84:87]
	v_mfma_f32_16x16x32_bf16 v[80:83], v[180:183], v[208:211], v[80:83]
	v_mfma_f32_16x16x32_bf16 v[68:71], v[172:175], v[216:219], v[68:71]
	v_mfma_f32_16x16x32_bf16 v[64:67], v[180:183], v[216:219], v[64:67]
	s_setprio 0
	s_barrier
	ds_read_b128 v[184:187], v155 offset:16384
	ds_read_b128 v[188:191], v155 offset:17408
	ds_read_b128 v[192:195], v155 offset:18432
	ds_read_b128 v[200:203], v155 offset:19456
	ds_read_b128 v[204:207], v155 offset:20480
	ds_read_b128 v[208:211], v155 offset:21504
	ds_read_b128 v[212:215], v155 offset:22528
	ds_read_b128 v[216:219], v155 offset:23552
	global_load_lds_dwordx4 v130, s[72:73]
	s_add_i32 m0, s88, 0x2000
	s_add_u32 s88, s72, 0x80000
	s_addc_u32 s89, s73, 0
	s_add_i32 s94, s83, s1
	global_load_lds_dwordx4 v134, s[72:73]
	s_mov_b32 m0, s94
	s_nop 0
	global_load_lds_dwordx4 v130, s[88:89]
	s_add_i32 m0, s94, 0x2000
	s_nop 0
	global_load_lds_dwordx4 v134, s[88:89]
	s_mov_b32 m0, s33
	s_nop 0
	global_load_lds_dwordx4 v128, s[74:75]
	s_mov_b32 m0, s35
	s_nop 0
	global_load_lds_dwordx4 v132, s[74:75]
	s_waitcnt vmcnt(8)
	s_waitcnt lgkmcnt(0)
	s_setprio 1
	s_barrier
	v_mfma_f32_16x16x32_bf16 v[60:63], v[144:147], v[184:187], v[60:63]
	v_mfma_f32_16x16x32_bf16 v[56:59], v[160:163], v[184:187], v[56:59]
	v_mfma_f32_16x16x32_bf16 v[44:47], v[144:147], v[192:195], v[44:47]
	v_mfma_f32_16x16x32_bf16 v[40:43], v[160:163], v[192:195], v[40:43]
	v_mfma_f32_16x16x32_bf16 v[28:31], v[144:147], v[204:207], v[28:31]
	v_mfma_f32_16x16x32_bf16 v[24:27], v[160:163], v[204:207], v[24:27]
	v_mfma_f32_16x16x32_bf16 v[12:15], v[144:147], v[212:215], v[12:15]
	v_mfma_f32_16x16x32_bf16 v[8:11], v[160:163], v[212:215], v[8:11]
	v_mfma_f32_16x16x32_bf16 v[60:63], v[156:159], v[188:191], v[60:63]
	v_mfma_f32_16x16x32_bf16 v[56:59], v[164:167], v[188:191], v[56:59]
	v_mfma_f32_16x16x32_bf16 v[44:47], v[156:159], v[200:203], v[44:47]
	v_mfma_f32_16x16x32_bf16 v[40:43], v[164:167], v[200:203], v[40:43]
	v_mfma_f32_16x16x32_bf16 v[28:31], v[156:159], v[208:211], v[28:31]
	v_mfma_f32_16x16x32_bf16 v[24:27], v[164:167], v[208:211], v[24:27]
	v_mfma_f32_16x16x32_bf16 v[12:15], v[156:159], v[216:219], v[12:15]
	v_mfma_f32_16x16x32_bf16 v[8:11], v[164:167], v[216:219], v[8:11]
	v_mfma_f32_16x16x32_bf16 v[52:55], v[168:171], v[184:187], v[52:55]
	v_mfma_f32_16x16x32_bf16 v[48:51], v[176:179], v[184:187], v[48:51]
	v_mfma_f32_16x16x32_bf16 v[36:39], v[168:171], v[192:195], v[36:39]
	v_mfma_f32_16x16x32_bf16 v[32:35], v[176:179], v[192:195], v[32:35]
	v_mfma_f32_16x16x32_bf16 v[20:23], v[168:171], v[204:207], v[20:23]
	v_mfma_f32_16x16x32_bf16 v[16:19], v[176:179], v[204:207], v[16:19]
	v_mfma_f32_16x16x32_bf16 v[4:7], v[168:171], v[212:215], v[4:7]
	v_mfma_f32_16x16x32_bf16 v[0:3], v[176:179], v[212:215], v[0:3]
	v_mfma_f32_16x16x32_bf16 v[52:55], v[172:175], v[188:191], v[52:55]
	v_mfma_f32_16x16x32_bf16 v[48:51], v[180:183], v[188:191], v[48:51]
	v_mfma_f32_16x16x32_bf16 v[36:39], v[172:175], v[200:203], v[36:39]
	v_mfma_f32_16x16x32_bf16 v[32:35], v[180:183], v[200:203], v[32:35]
	v_mfma_f32_16x16x32_bf16 v[20:23], v[172:175], v[208:211], v[20:23]
	v_mfma_f32_16x16x32_bf16 v[16:19], v[180:183], v[208:211], v[16:19]
	v_mfma_f32_16x16x32_bf16 v[4:7], v[172:175], v[216:219], v[4:7]
	v_mfma_f32_16x16x32_bf16 v[0:3], v[180:183], v[216:219], v[0:3]
	s_setprio 0
	s_barrier
; #define PG8_STAGE(bufoff, gbase, voff) do { _Pragma("unroll") for (int _i = 0; _i < 2; ++_i) \
;         __builtin_amdgcn_global_load_lds((const unsigned*)((const char*)(gbase) + (voff)[_i]), (PG8_LAS unsigned*)(lds + (bufoff) + ldsw + _i * 8192), 16, 0, 0); } while (0)
; #define PG8_LDA(dst, b, h) do { _Pragma("unroll") for (int m = 0; m < 4; ++m) _Pragma("unroll") for (int k = 0; k < 2; ++k) dst[m][k] = *(const PG8_LAS bf16x8*)(lds + PG8_SA(b, h) + aoff + m * 2048 + k * 1024); } while (0)
; #define PG8_LDB(dst, b, h) do { _Pragma("unroll") for (int n = 0; n < 2; ++n) _Pragma("unroll") for (int k = 0; k < 2; ++k) dst[n][k] = *(const PG8_LAS bf16x8*)(lds + PG8_SB(b, h) + boff + n * 2048 + k * 1024); } while (0)
; #define PG8_MMA(ai, bj, At, Bt) do { __builtin_amdgcn_s_setprio(1); _Pragma("unroll") for (int m = 0; m < 4; ++m) _Pragma("unroll") for (int n = 0; n < 2; ++n) _Pragma("unroll") for (int k = 0; k < 2; ++k) \
;         acc[ai][bj][m][n] = __builtin_amdgcn_mfma_f32_16x16x32_bf16(Bt[n][k], At[m][k], acc[ai][bj][m][n], 0, 0, 0); __builtin_amdgcn_s_setprio(0); } while (0)
; #define PG8_WAIT_V(n) asm volatile("s_waitcnt vmcnt(" #n ")" ::: "memory")
; #define PG8_WAIT_L(n) asm volatile("s_waitcnt lgkmcnt(" #n ")" ::: "memory")
; #define PG8_BAR __builtin_amdgcn_s_barrier()
; #define PG8_SCHED __builtin_amdgcn_sched_barrier(0)
; template <class Epi, class Sched, bool ALIGN_EPI = false, bool SP2 = false>
; __device__ __forceinline__ void gemm_phase(PG8_LAS unsigned char* lds, const Gemm g, const Sched& S, const Epi& E) {
;     ...
;         for (int t = 0; t < nt; t += 2) {
;     ...
;             PG8_LDB(B0, 1, 0); PG8_LDB(B1, 1, 1); PG8_SCHED; PG8_LDA(At, 1, 0); PG8_STAGE(PG8_SA(0, 1), a2 + hstep, voffA);
;             PG8_WAIT_V(8); PG8_WAIT_L(0); PG8_BAR; PG8_MMA(0, 0, At, B0); PG8_MMA(0, 1, At, B1); PG8_BAR; PG8_SCHED;
;             PG8_LDA(At, 1, 1); PG8_STAGE(PG8_SB(1, 0), b3, voffB); PG8_STAGE(PG8_SB(1, 1), b3 + hstep, voffB); PG8_STAGE(PG8_SA(1, 0), a3, voffA);
;             PG8_WAIT_V(8); PG8_WAIT_L(0); PG8_BAR; PG8_MMA(1, 0, At, B0); PG8_MMA(1, 1, At, B1); PG8_BAR; PG8_SCHED;
	ds_read_b128 v[144:147], v196
	ds_read_b128 v[156:159], v196 offset:1024
	ds_read_b128 v[160:163], v196 offset:2048
	ds_read_b128 v[164:167], v196 offset:3072
	ds_read_b128 v[168:171], v197
	ds_read_b128 v[172:175], v197 offset:1024
	ds_read_b128 v[176:179], v197 offset:2048
	ds_read_b128 v[180:183], v197 offset:3072
	ds_read_b128 v[184:187], v155 offset:32768
	ds_read_b128 v[188:191], v155 offset:33792
	ds_read_b128 v[192:195], v155 offset:34816
	ds_read_b128 v[200:203], v155 offset:35840
	ds_read_b128 v[204:207], v155 offset:36864
	ds_read_b128 v[208:211], v155 offset:37888
	ds_read_b128 v[212:215], v155 offset:38912
	ds_read_b128 v[216:219], v155 offset:39936
	s_add_u32 s98, s74, 0x80000
	s_addc_u32 s99, s75, 0
	s_mov_b32 m0, s69
	s_add_u32 s100, s74, 0x80
	s_addc_u32 s101, s75, 0
	global_load_lds_dwordx4 v128, s[98:99]
	s_mov_b32 m0, s76
	s_nop 0
	global_load_lds_dwordx4 v132, s[98:99]
	s_add_i32 s88, 0, 0x18000
	s_add_i32 s89, 0, 0x1c000
	s_add_u32 s98, s72, 0x80
	s_addc_u32 s99, s73, 0
	s_add_i32 s74, s88, s1
	s_mov_b32 m0, s74
	s_waitcnt vmcnt(8)
	s_waitcnt lgkmcnt(0)
	s_setprio 1
	s_barrier
	v_mfma_f32_16x16x32_bf16 v[124:127], v[144:147], v[184:187], v[124:127]
	v_mfma_f32_16x16x32_bf16 v[120:123], v[160:163], v[184:187], v[120:123]
	v_mfma_f32_16x16x32_bf16 v[108:111], v[144:147], v[192:195], v[108:111]
	v_mfma_f32_16x16x32_bf16 v[104:107], v[160:163], v[192:195], v[104:107]
	v_mfma_f32_16x16x32_bf16 v[92:95], v[144:147], v[204:207], v[92:95]
	v_mfma_f32_16x16x32_bf16 v[88:91], v[160:163], v[204:207], v[88:91]
	v_mfma_f32_16x16x32_bf16 v[76:79], v[144:147], v[212:215], v[76:79]
	v_mfma_f32_16x16x32_bf16 v[72:75], v[160:163], v[212:215], v[72:75]
	v_mfma_f32_16x16x32_bf16 v[124:127], v[156:159], v[188:191], v[124:127]
	v_mfma_f32_16x16x32_bf16 v[120:123], v[164:167], v[188:191], v[120:123]
	v_mfma_f32_16x16x32_bf16 v[108:111], v[156:159], v[200:203], v[108:111]
	v_mfma_f32_16x16x32_bf16 v[104:107], v[164:167], v[200:203], v[104:107]
	v_mfma_f32_16x16x32_bf16 v[92:95], v[156:159], v[208:211], v[92:95]
	v_mfma_f32_16x16x32_bf16 v[88:91], v[164:167], v[208:211], v[88:91]
	v_mfma_f32_16x16x32_bf16 v[76:79], v[156:159], v[216:219], v[76:79]
	v_mfma_f32_16x16x32_bf16 v[72:75], v[164:167], v[216:219], v[72:75]
	v_mfma_f32_16x16x32_bf16 v[116:119], v[168:171], v[184:187], v[116:119]
	v_mfma_f32_16x16x32_bf16 v[112:115], v[176:179], v[184:187], v[112:115]
	v_mfma_f32_16x16x32_bf16 v[100:103], v[168:171], v[192:195], v[100:103]
	v_mfma_f32_16x16x32_bf16 v[96:99], v[176:179], v[192:195], v[96:99]
	v_mfma_f32_16x16x32_bf16 v[84:87], v[168:171], v[204:207], v[84:87]
	v_mfma_f32_16x16x32_bf16 v[80:83], v[176:179], v[204:207], v[80:83]
	v_mfma_f32_16x16x32_bf16 v[68:71], v[168:171], v[212:215], v[68:71]
	v_mfma_f32_16x16x32_bf16 v[64:67], v[176:179], v[212:215], v[64:67]
	v_mfma_f32_16x16x32_bf16 v[116:119], v[172:175], v[188:191], v[116:119]
	v_mfma_f32_16x16x32_bf16 v[112:115], v[180:183], v[188:191], v[112:115]
	v_mfma_f32_16x16x32_bf16 v[100:103], v[172:175], v[200:203], v[100:103]
	v_mfma_f32_16x16x32_bf16 v[96:99], v[180:183], v[200:203], v[96:99]
	v_mfma_f32_16x16x32_bf16 v[84:87], v[172:175], v[208:211], v[84:87]
	v_mfma_f32_16x16x32_bf16 v[80:83], v[180:183], v[208:211], v[80:83]
	v_mfma_f32_16x16x32_bf16 v[68:71], v[172:175], v[216:219], v[68:71]
	v_mfma_f32_16x16x32_bf16 v[64:67], v[180:183], v[216:219], v[64:67]
	s_setprio 0
	s_barrier
	ds_read_b128 v[184:187], v155 offset:49152
	ds_read_b128 v[188:191], v155 offset:50176
	ds_read_b128 v[192:195], v155 offset:51200
	ds_read_b128 v[200:203], v155 offset:52224
	ds_read_b128 v[204:207], v155 offset:53248
	ds_read_b128 v[208:211], v155 offset:54272
	ds_read_b128 v[212:215], v155 offset:55296
	ds_read_b128 v[216:219], v155 offset:56320
	global_load_lds_dwordx4 v130, s[98:99]
	s_add_i32 m0, s74, 0x2000
	s_add_u32 s72, s72, 0x80080
	s_addc_u32 s73, s73, 0
	s_add_i32 s74, s89, s1
	global_load_lds_dwordx4 v134, s[98:99]
	s_mov_b32 m0, s74
	s_nop 0
	global_load_lds_dwordx4 v130, s[72:73]
	s_add_i32 m0, s74, 0x2000
	s_nop 0
	global_load_lds_dwordx4 v134, s[72:73]
	s_mov_b32 m0, s78
	s_nop 0
	global_load_lds_dwordx4 v128, s[100:101]
	s_mov_b32 m0, s79
	s_nop 0
	global_load_lds_dwordx4 v132, s[100:101]
	s_add_i32 s87, s87, 2
	s_add_u32 s70, s70, 0x100
	s_addc_u32 s71, s71, 0
	s_add_u32 s85, s85, 0x100
	s_addc_u32 s86, s86, 0
	s_cmp_gt_u32 s87, 29
	s_waitcnt vmcnt(8)
	s_waitcnt lgkmcnt(0)
	s_setprio 1
	s_barrier
	v_mfma_f32_16x16x32_bf16 v[60:63], v[144:147], v[184:187], v[60:63]
	v_mfma_f32_16x16x32_bf16 v[56:59], v[160:163], v[184:187], v[56:59]
	v_mfma_f32_16x16x32_bf16 v[44:47], v[144:147], v[192:195], v[44:47]
	v_mfma_f32_16x16x32_bf16 v[40:43], v[160:163], v[192:195], v[40:43]
	v_mfma_f32_16x16x32_bf16 v[28:31], v[144:147], v[204:207], v[28:31]
	v_mfma_f32_16x16x32_bf16 v[24:27], v[160:163], v[204:207], v[24:27]
	v_mfma_f32_16x16x32_bf16 v[12:15], v[144:147], v[212:215], v[12:15]
	v_mfma_f32_16x16x32_bf16 v[8:11], v[160:163], v[212:215], v[8:11]
	v_mfma_f32_16x16x32_bf16 v[60:63], v[156:159], v[188:191], v[60:63]
	v_mfma_f32_16x16x32_bf16 v[56:59], v[164:167], v[188:191], v[56:59]
	v_mfma_f32_16x16x32_bf16 v[44:47], v[156:159], v[200:203], v[44:47]
	v_mfma_f32_16x16x32_bf16 v[40:43], v[164:167], v[200:203], v[40:43]
	v_mfma_f32_16x16x32_bf16 v[28:31], v[156:159], v[208:211], v[28:31]
	v_mfma_f32_16x16x32_bf16 v[24:27], v[164:167], v[208:211], v[24:27]
	v_mfma_f32_16x16x32_bf16 v[12:15], v[156:159], v[216:219], v[12:15]
	v_mfma_f32_16x16x32_bf16 v[8:11], v[164:167], v[216:219], v[8:11]
	v_mfma_f32_16x16x32_bf16 v[52:55], v[168:171], v[184:187], v[52:55]
	v_mfma_f32_16x16x32_bf16 v[48:51], v[176:179], v[184:187], v[48:51]
	v_mfma_f32_16x16x32_bf16 v[36:39], v[168:171], v[192:195], v[36:39]
	v_mfma_f32_16x16x32_bf16 v[32:35], v[176:179], v[192:195], v[32:35]
	v_mfma_f32_16x16x32_bf16 v[20:23], v[168:171], v[204:207], v[20:23]
	v_mfma_f32_16x16x32_bf16 v[16:19], v[176:179], v[204:207], v[16:19]
	v_mfma_f32_16x16x32_bf16 v[4:7], v[168:171], v[212:215], v[4:7]
	v_mfma_f32_16x16x32_bf16 v[0:3], v[176:179], v[212:215], v[0:3]
	v_mfma_f32_16x16x32_bf16 v[52:55], v[172:175], v[188:191], v[52:55]
	v_mfma_f32_16x16x32_bf16 v[48:51], v[180:183], v[188:191], v[48:51]
	v_mfma_f32_16x16x32_bf16 v[36:39], v[172:175], v[200:203], v[36:39]
	v_mfma_f32_16x16x32_bf16 v[32:35], v[180:183], v[200:203], v[32:35]
	v_mfma_f32_16x16x32_bf16 v[20:23], v[172:175], v[208:211], v[20:23]
	v_mfma_f32_16x16x32_bf16 v[16:19], v[180:183], v[208:211], v[16:19]
	v_mfma_f32_16x16x32_bf16 v[4:7], v[172:175], v[216:219], v[4:7]
	v_mfma_f32_16x16x32_bf16 v[0:3], v[180:183], v[216:219], v[0:3]
	s_setprio 0
	s_barrier
	s_cbranch_scc0 .LBB0_245
	s_and_b64 vcc, exec, s[14:15]
	s_cbranch_vccz .LBB0_248
	s_barrier

; #define PG8_STAGE(bufoff, gbase, voff) do { _Pragma("unroll") for (int _i = 0; _i < 2; ++_i) \
;         __builtin_amdgcn_global_load_lds((const unsigned*)((const char*)(gbase) + (voff)[_i]), (PG8_LAS unsigned*)(lds + (bufoff) + ldsw + _i * 8192), 16, 0, 0); } while (0)
; #define PG8_LDA(dst, b, h) do { _Pragma("unroll") for (int m = 0; m < 4; ++m) _Pragma("unroll") for (int k = 0; k < 2; ++k) dst[m][k] = *(const PG8_LAS bf16x8*)(lds + PG8_SA(b, h) + aoff + m * 2048 + k * 1024); } while (0)
; #define PG8_LDB(dst, b, h) do { _Pragma("unroll") for (int n = 0; n < 2; ++n) _Pragma("unroll") for (int k = 0; k < 2; ++k) dst[n][k] = *(const PG8_LAS bf16x8*)(lds + PG8_SB(b, h) + boff + n * 2048 + k * 1024); } while (0)
; #define PG8_MMA(ai, bj, At, Bt) do { __builtin_amdgcn_s_setprio(1); _Pragma("unroll") for (int m = 0; m < 4; ++m) _Pragma("unroll") for (int n = 0; n < 2; ++n) _Pragma("unroll") for (int k = 0; k < 2; ++k) \
;         acc[ai][bj][m][n] = __builtin_amdgcn_mfma_f32_16x16x32_bf16(Bt[n][k], At[m][k], acc[ai][bj][m][n], 0, 0, 0); __builtin_amdgcn_s_setprio(0); } while (0)
; #define PG8_WAIT_V(n) asm volatile("s_waitcnt vmcnt(" #n ")" ::: "memory")
; #define PG8_WAIT_L(n) asm volatile("s_waitcnt lgkmcnt(" #n ")" ::: "memory")
; template <class Epi, class Sched, bool ALIGN_EPI = false, bool SP2 = false>
; __device__ __forceinline__ void gemm_phase(PG8_LAS unsigned char* lds, const Gemm g, const Sched& S, const Epi& E) {
;     ...
;             const bool last = (t == nt - 2);
;             const char* a1 = cA + (size_t)(t + 1) * kstep;
;             const char* a2 = last ? nA : cA + (size_t)(t + 2) * kstep; const char* b2 = last ? nB : cB + (size_t)(t + 2) * kstep;
;             const char* a3 = a2 + kstep; const char* b3 = b2 + kstep;
;             if (last && has_next) S.a_ready(nxt);
;             if constexpr (SP2) {
;             PG8_LDB(B0, 0, 0); PG8_LDB(B1, 0, 1); PG8_SCHED; PG8_LDA(At, 0, 0); PG8_STAGE(PG8_SA(1, 1), a1 + hstep, voffA);
;             PG8_WAIT_V(8); PG8_WAIT_L(0); PG8_BAR; PG8_MMA(0, 0, At, B0); PG8_MMA(0, 1, At, B1); PG8_BAR; PG8_SCHED;
;             PG8_LDA(At, 0, 1); PG8_STAGE(PG8_SB(0, 0), b2, voffB); PG8_STAGE(PG8_SB(0, 1), b2 + hstep, voffB); PG8_STAGE(PG8_SA(0, 0), a2, voffA);
;             PG8_WAIT_V(8); PG8_WAIT_L(0); PG8_BAR; PG8_MMA(1, 0, At, B0); PG8_MMA(1, 1, At, B1); PG8_BAR; PG8_SCHED;
.LBB0_376:
	ds_read_b128 v[152:155], v149
	ds_read_b128 v[156:159], v149 offset:1024
	ds_read_b128 v[160:163], v149 offset:2048
	ds_read_b128 v[164:167], v149 offset:3072
	ds_read_b128 v[168:171], v150
	ds_read_b128 v[172:175], v150 offset:1024
	ds_read_b128 v[176:179], v150 offset:2048
	ds_read_b128 v[180:183], v150 offset:3072
	s_add_i32 m0, s33, 0xc000
	ds_read_b128 v[184:187], v151
	ds_read_b128 v[188:191], v151 offset:1024
	ds_read_b128 v[192:195], v151 offset:2048
	ds_read_b128 v[200:203], v151 offset:3072
	ds_read_b128 v[204:207], v151 offset:4096
	ds_read_b128 v[208:211], v151 offset:5120
	ds_read_b128 v[212:215], v151 offset:6144
	ds_read_b128 v[216:219], v151 offset:7168
	global_load_lds_dwordx4 v136, s[68:69]
	s_add_i32 m0, s33, 0xe000
	s_nop 0
	global_load_lds_dwordx4 v138, s[68:69]
	s_add_u32 s70, s68, 0xfff80080
	s_addc_u32 s71, s69, -1
	s_cmp_eq_u32 s88, 28
	s_cselect_b32 s73, s25, s71
	s_cselect_b32 s72, s61, s70
	s_cselect_b32 s71, s49, s87
	s_cselect_b32 s70, s85, s86
	s_add_i32 s89, s80, s1
	s_mov_b32 m0, s89
	s_waitcnt vmcnt(8)
	s_waitcnt lgkmcnt(0)
	s_setprio 1
	s_barrier
	v_mfma_f32_16x16x32_bf16 v[124:127], v[152:155], v[184:187], v[124:127]
	v_mfma_f32_16x16x32_bf16 v[120:123], v[160:163], v[184:187], v[120:123]
	v_mfma_f32_16x16x32_bf16 v[108:111], v[152:155], v[192:195], v[108:111]
	v_mfma_f32_16x16x32_bf16 v[104:107], v[160:163], v[192:195], v[104:107]
	v_mfma_f32_16x16x32_bf16 v[92:95], v[152:155], v[204:207], v[92:95]
	v_mfma_f32_16x16x32_bf16 v[88:91], v[160:163], v[204:207], v[88:91]
	v_mfma_f32_16x16x32_bf16 v[76:79], v[152:155], v[212:215], v[76:79]
	v_mfma_f32_16x16x32_bf16 v[72:75], v[160:163], v[212:215], v[72:75]
	v_mfma_f32_16x16x32_bf16 v[124:127], v[156:159], v[188:191], v[124:127]
	v_mfma_f32_16x16x32_bf16 v[120:123], v[164:167], v[188:191], v[120:123]
	v_mfma_f32_16x16x32_bf16 v[108:111], v[156:159], v[200:203], v[108:111]
	v_mfma_f32_16x16x32_bf16 v[104:107], v[164:167], v[200:203], v[104:107]
	v_mfma_f32_16x16x32_bf16 v[92:95], v[156:159], v[208:211], v[92:95]
	v_mfma_f32_16x16x32_bf16 v[88:91], v[164:167], v[208:211], v[88:91]
	v_mfma_f32_16x16x32_bf16 v[76:79], v[156:159], v[216:219], v[76:79]
	v_mfma_f32_16x16x32_bf16 v[72:75], v[164:167], v[216:219], v[72:75]
	v_mfma_f32_16x16x32_bf16 v[116:119], v[168:171], v[184:187], v[116:119]
	v_mfma_f32_16x16x32_bf16 v[112:115], v[176:179], v[184:187], v[112:115]
	v_mfma_f32_16x16x32_bf16 v[100:103], v[168:171], v[192:195], v[100:103]
	v_mfma_f32_16x16x32_bf16 v[96:99], v[176:179], v[192:195], v[96:99]
	v_mfma_f32_16x16x32_bf16 v[84:87], v[168:171], v[204:207], v[84:87]
	v_mfma_f32_16x16x32_bf16 v[80:83], v[176:179], v[204:207], v[80:83]
	v_mfma_f32_16x16x32_bf16 v[68:71], v[168:171], v[212:215], v[68:71]
	v_mfma_f32_16x16x32_bf16 v[64:67], v[176:179], v[212:215], v[64:67]
	v_mfma_f32_16x16x32_bf16 v[116:119], v[172:175], v[188:191], v[116:119]
	v_mfma_f32_16x16x32_bf16 v[112:115], v[180:183], v[188:191], v[112:115]
	v_mfma_f32_16x16x32_bf16 v[100:103], v[172:175], v[200:203], v[100:103]
	v_mfma_f32_16x16x32_bf16 v[96:99], v[180:183], v[200:203], v[96:99]
	v_mfma_f32_16x16x32_bf16 v[84:87], v[172:175], v[208:211], v[84:87]
	v_mfma_f32_16x16x32_bf16 v[80:83], v[180:183], v[208:211], v[80:83]
	v_mfma_f32_16x16x32_bf16 v[68:71], v[172:175], v[216:219], v[68:71]
	v_mfma_f32_16x16x32_bf16 v[64:67], v[180:183], v[216:219], v[64:67]
	s_setprio 0
	s_barrier
	ds_read_b128 v[184:187], v151 offset:16384
	ds_read_b128 v[188:191], v151 offset:17408
	ds_read_b128 v[192:195], v151 offset:18432
	ds_read_b128 v[200:203], v151 offset:19456
	ds_read_b128 v[204:207], v151 offset:20480
	ds_read_b128 v[208:211], v151 offset:21504
	ds_read_b128 v[212:215], v151 offset:22528
	ds_read_b128 v[216:219], v151 offset:23552
	global_load_lds_dwordx4 v130, s[70:71]
	s_add_i32 m0, s89, 0x2000
	s_add_u32 s96, s70, 0x80000
	s_addc_u32 s97, s71, 0
	s_add_i32 s89, s81, s1
	global_load_lds_dwordx4 v134, s[70:71]
	s_mov_b32 m0, s89
	s_nop 0
	global_load_lds_dwordx4 v130, s[96:97]
	s_add_i32 m0, s89, 0x2000
	s_nop 0
	global_load_lds_dwordx4 v134, s[96:97]
	s_mov_b32 m0, s33
	s_nop 0
	global_load_lds_dwordx4 v128, s[72:73]
	s_mov_b32 m0, s35
	s_nop 0
	global_load_lds_dwordx4 v132, s[72:73]
	s_waitcnt vmcnt(8)
	s_waitcnt lgkmcnt(0)
	s_setprio 1
	s_barrier
	v_mfma_f32_16x16x32_bf16 v[60:63], v[152:155], v[184:187], v[60:63]
	v_mfma_f32_16x16x32_bf16 v[56:59], v[160:163], v[184:187], v[56:59]
	v_mfma_f32_16x16x32_bf16 v[44:47], v[152:155], v[192:195], v[44:47]
	v_mfma_f32_16x16x32_bf16 v[40:43], v[160:163], v[192:195], v[40:43]
	v_mfma_f32_16x16x32_bf16 v[28:31], v[152:155], v[204:207], v[28:31]
	v_mfma_f32_16x16x32_bf16 v[24:27], v[160:163], v[204:207], v[24:27]
	v_mfma_f32_16x16x32_bf16 v[12:15], v[152:155], v[212:215], v[12:15]
	v_mfma_f32_16x16x32_bf16 v[8:11], v[160:163], v[212:215], v[8:11]
	v_mfma_f32_16x16x32_bf16 v[60:63], v[156:159], v[188:191], v[60:63]
	v_mfma_f32_16x16x32_bf16 v[56:59], v[164:167], v[188:191], v[56:59]
	v_mfma_f32_16x16x32_bf16 v[44:47], v[156:159], v[200:203], v[44:47]
	v_mfma_f32_16x16x32_bf16 v[40:43], v[164:167], v[200:203], v[40:43]
	v_mfma_f32_16x16x32_bf16 v[28:31], v[156:159], v[208:211], v[28:31]
	v_mfma_f32_16x16x32_bf16 v[24:27], v[164:167], v[208:211], v[24:27]
	v_mfma_f32_16x16x32_bf16 v[12:15], v[156:159], v[216:219], v[12:15]
	v_mfma_f32_16x16x32_bf16 v[8:11], v[164:167], v[216:219], v[8:11]
	v_mfma_f32_16x16x32_bf16 v[52:55], v[168:171], v[184:187], v[52:55]
	v_mfma_f32_16x16x32_bf16 v[48:51], v[176:179], v[184:187], v[48:51]
	v_mfma_f32_16x16x32_bf16 v[36:39], v[168:171], v[192:195], v[36:39]
	v_mfma_f32_16x16x32_bf16 v[32:35], v[176:179], v[192:195], v[32:35]
	v_mfma_f32_16x16x32_bf16 v[20:23], v[168:171], v[204:207], v[20:23]
	v_mfma_f32_16x16x32_bf16 v[16:19], v[176:179], v[204:207], v[16:19]
	v_mfma_f32_16x16x32_bf16 v[4:7], v[168:171], v[212:215], v[4:7]
	v_mfma_f32_16x16x32_bf16 v[0:3], v[176:179], v[212:215], v[0:3]
	v_mfma_f32_16x16x32_bf16 v[52:55], v[172:175], v[188:191], v[52:55]
	v_mfma_f32_16x16x32_bf16 v[48:51], v[180:183], v[188:191], v[48:51]
	v_mfma_f32_16x16x32_bf16 v[36:39], v[172:175], v[200:203], v[36:39]
	v_mfma_f32_16x16x32_bf16 v[32:35], v[180:183], v[200:203], v[32:35]
	v_mfma_f32_16x16x32_bf16 v[20:23], v[172:175], v[208:211], v[20:23]
	v_mfma_f32_16x16x32_bf16 v[16:19], v[180:183], v[208:211], v[16:19]
	v_mfma_f32_16x16x32_bf16 v[4:7], v[172:175], v[216:219], v[4:7]
	v_mfma_f32_16x16x32_bf16 v[0:3], v[180:183], v[216:219], v[0:3]
	s_setprio 0
	s_barrier
; #define PG8_STAGE(bufoff, gbase, voff) do { _Pragma("unroll") for (int _i = 0; _i < 2; ++_i) \
;         __builtin_amdgcn_global_load_lds((const unsigned*)((const char*)(gbase) + (voff)[_i]), (PG8_LAS unsigned*)(lds + (bufoff) + ldsw + _i * 8192), 16, 0, 0); } while (0)
; #define PG8_LDA(dst, b, h) do { _Pragma("unroll") for (int m = 0; m < 4; ++m) _Pragma("unroll") for (int k = 0; k < 2; ++k) dst[m][k] = *(const PG8_LAS bf16x8*)(lds + PG8_SA(b, h) + aoff + m * 2048 + k * 1024); } while (0)
; #define PG8_LDB(dst, b, h) do { _Pragma("unroll") for (int n = 0; n < 2; ++n) _Pragma("unroll") for (int k = 0; k < 2; ++k) dst[n][k] = *(const PG8_LAS bf16x8*)(lds + PG8_SB(b, h) + boff + n * 2048 + k * 1024); } while (0)
; #define PG8_MMA(ai, bj, At, Bt) do { __builtin_amdgcn_s_setprio(1); _Pragma("unroll") for (int m = 0; m < 4; ++m) _Pragma("unroll") for (int n = 0; n < 2; ++n) _Pragma("unroll") for (int k = 0; k < 2; ++k) \
;         acc[ai][bj][m][n] = __builtin_amdgcn_mfma_f32_16x16x32_bf16(Bt[n][k], At[m][k], acc[ai][bj][m][n], 0, 0, 0); __builtin_amdgcn_s_setprio(0); } while (0)
; #define PG8_WAIT_V(n) asm volatile("s_waitcnt vmcnt(" #n ")" ::: "memory")
; #define PG8_WAIT_L(n) asm volatile("s_waitcnt lgkmcnt(" #n ")" ::: "memory")
; #define PG8_BAR __builtin_amdgcn_s_barrier()
; #define PG8_SCHED __builtin_amdgcn_sched_barrier(0)
; template <class Epi, class Sched, bool ALIGN_EPI = false, bool SP2 = false>
; __device__ __forceinline__ void gemm_phase(PG8_LAS unsigned char* lds, const Gemm g, const Sched& S, const Epi& E) {
;     ...
;         for (int t = 0; t < nt; t += 2) {
;     ...
;             PG8_LDB(B0, 1, 0); PG8_LDB(B1, 1, 1); PG8_SCHED; PG8_LDA(At, 1, 0); PG8_STAGE(PG8_SA(0, 1), a2 + hstep, voffA);
;             PG8_WAIT_V(8); PG8_WAIT_L(0); PG8_BAR; PG8_MMA(0, 0, At, B0); PG8_MMA(0, 1, At, B1); PG8_BAR; PG8_SCHED;
;             PG8_LDA(At, 1, 1); PG8_STAGE(PG8_SB(1, 0), b3, voffB); PG8_STAGE(PG8_SB(1, 1), b3 + hstep, voffB); PG8_STAGE(PG8_SA(1, 0), a3, voffA);
;             PG8_WAIT_V(8); PG8_WAIT_L(0); PG8_BAR; PG8_MMA(1, 0, At, B0); PG8_MMA(1, 1, At, B1); PG8_BAR; PG8_SCHED;
	ds_read_b128 v[152:155], v196
	ds_read_b128 v[156:159], v196 offset:1024
	ds_read_b128 v[160:163], v196 offset:2048
	ds_read_b128 v[164:167], v196 offset:3072
	ds_read_b128 v[168:171], v197
	ds_read_b128 v[172:175], v197 offset:1024
	ds_read_b128 v[176:179], v197 offset:2048
	ds_read_b128 v[180:183], v197 offset:3072
	ds_read_b128 v[184:187], v151 offset:32768
	ds_read_b128 v[188:191], v151 offset:33792
	ds_read_b128 v[192:195], v151 offset:34816
	ds_read_b128 v[200:203], v151 offset:35840
	ds_read_b128 v[204:207], v151 offset:36864
	ds_read_b128 v[208:211], v151 offset:37888
	ds_read_b128 v[212:215], v151 offset:38912
	ds_read_b128 v[216:219], v151 offset:39936
	s_add_u32 s98, s72, 0x80000
	s_addc_u32 s99, s73, 0
	s_mov_b32 m0, s67
	s_add_u32 s100, s72, 0x80
	s_addc_u32 s101, s73, 0
	global_load_lds_dwordx4 v128, s[98:99]
	s_mov_b32 m0, s74
	s_nop 0
	global_load_lds_dwordx4 v132, s[98:99]
	s_add_i32 s89, 0, 0x18000
	s_add_i32 s94, 0, 0x1c000
	s_add_u32 s98, s70, 0x80
	s_addc_u32 s99, s71, 0
	s_add_i32 s72, s89, s1
	s_mov_b32 m0, s72
	s_waitcnt vmcnt(8)
	s_waitcnt lgkmcnt(0)
	s_setprio 1
	s_barrier
	v_mfma_f32_16x16x32_bf16 v[124:127], v[152:155], v[184:187], v[124:127]
	v_mfma_f32_16x16x32_bf16 v[120:123], v[160:163], v[184:187], v[120:123]
	v_mfma_f32_16x16x32_bf16 v[108:111], v[152:155], v[192:195], v[108:111]
	v_mfma_f32_16x16x32_bf16 v[104:107], v[160:163], v[192:195], v[104:107]
	v_mfma_f32_16x16x32_bf16 v[92:95], v[152:155], v[204:207], v[92:95]
	v_mfma_f32_16x16x32_bf16 v[88:91], v[160:163], v[204:207], v[88:91]
	v_mfma_f32_16x16x32_bf16 v[76:79], v[152:155], v[212:215], v[76:79]
	v_mfma_f32_16x16x32_bf16 v[72:75], v[160:163], v[212:215], v[72:75]
	v_mfma_f32_16x16x32_bf16 v[124:127], v[156:159], v[188:191], v[124:127]
	v_mfma_f32_16x16x32_bf16 v[120:123], v[164:167], v[188:191], v[120:123]
	v_mfma_f32_16x16x32_bf16 v[108:111], v[156:159], v[200:203], v[108:111]
	v_mfma_f32_16x16x32_bf16 v[104:107], v[164:167], v[200:203], v[104:107]
	v_mfma_f32_16x16x32_bf16 v[92:95], v[156:159], v[208:211], v[92:95]
	v_mfma_f32_16x16x32_bf16 v[88:91], v[164:167], v[208:211], v[88:91]
	v_mfma_f32_16x16x32_bf16 v[76:79], v[156:159], v[216:219], v[76:79]
	v_mfma_f32_16x16x32_bf16 v[72:75], v[164:167], v[216:219], v[72:75]
	v_mfma_f32_16x16x32_bf16 v[116:119], v[168:171], v[184:187], v[116:119]
	v_mfma_f32_16x16x32_bf16 v[112:115], v[176:179], v[184:187], v[112:115]
	v_mfma_f32_16x16x32_bf16 v[100:103], v[168:171], v[192:195], v[100:103]
	v_mfma_f32_16x16x32_bf16 v[96:99], v[176:179], v[192:195], v[96:99]
	v_mfma_f32_16x16x32_bf16 v[84:87], v[168:171], v[204:207], v[84:87]
	v_mfma_f32_16x16x32_bf16 v[80:83], v[176:179], v[204:207], v[80:83]
	v_mfma_f32_16x16x32_bf16 v[68:71], v[168:171], v[212:215], v[68:71]
	v_mfma_f32_16x16x32_bf16 v[64:67], v[176:179], v[212:215], v[64:67]
	v_mfma_f32_16x16x32_bf16 v[116:119], v[172:175], v[188:191], v[116:119]
	v_mfma_f32_16x16x32_bf16 v[112:115], v[180:183], v[188:191], v[112:115]
	v_mfma_f32_16x16x32_bf16 v[100:103], v[172:175], v[200:203], v[100:103]
	v_mfma_f32_16x16x32_bf16 v[96:99], v[180:183], v[200:203], v[96:99]
	v_mfma_f32_16x16x32_bf16 v[84:87], v[172:175], v[208:211], v[84:87]
	v_mfma_f32_16x16x32_bf16 v[80:83], v[180:183], v[208:211], v[80:83]
	v_mfma_f32_16x16x32_bf16 v[68:71], v[172:175], v[216:219], v[68:71]
	v_mfma_f32_16x16x32_bf16 v[64:67], v[180:183], v[216:219], v[64:67]
	s_setprio 0
	s_barrier
	ds_read_b128 v[184:187], v151 offset:49152
	ds_read_b128 v[188:191], v151 offset:50176
	ds_read_b128 v[192:195], v151 offset:51200
	ds_read_b128 v[200:203], v151 offset:52224
	ds_read_b128 v[204:207], v151 offset:53248
	ds_read_b128 v[208:211], v151 offset:54272
	ds_read_b128 v[212:215], v151 offset:55296
	ds_read_b128 v[216:219], v151 offset:56320
	global_load_lds_dwordx4 v130, s[98:99]
	s_add_i32 m0, s72, 0x2000
	s_add_u32 s70, s70, 0x80080
	s_addc_u32 s71, s71, 0
	s_add_i32 s72, s94, s1
	global_load_lds_dwordx4 v134, s[98:99]
	s_mov_b32 m0, s72
	s_nop 0
	global_load_lds_dwordx4 v130, s[70:71]
	s_add_i32 m0, s72, 0x2000
	s_nop 0
	global_load_lds_dwordx4 v134, s[70:71]
	s_mov_b32 m0, s76
	s_nop 0
	global_load_lds_dwordx4 v128, s[100:101]
	s_mov_b32 m0, s77
	s_nop 0
	global_load_lds_dwordx4 v132, s[100:101]
	s_add_i32 s88, s88, 2
	s_add_u32 s68, s68, 0x100
	s_addc_u32 s69, s69, 0
	s_add_u32 s86, s86, 0x100
	s_addc_u32 s87, s87, 0
	s_cmp_gt_u32 s88, 29
	s_waitcnt vmcnt(8)
	s_waitcnt lgkmcnt(0)
	s_setprio 1
	s_barrier
	v_mfma_f32_16x16x32_bf16 v[60:63], v[152:155], v[184:187], v[60:63]
	v_mfma_f32_16x16x32_bf16 v[56:59], v[160:163], v[184:187], v[56:59]
	v_mfma_f32_16x16x32_bf16 v[44:47], v[152:155], v[192:195], v[44:47]
	v_mfma_f32_16x16x32_bf16 v[40:43], v[160:163], v[192:195], v[40:43]
	v_mfma_f32_16x16x32_bf16 v[28:31], v[152:155], v[204:207], v[28:31]
	v_mfma_f32_16x16x32_bf16 v[24:27], v[160:163], v[204:207], v[24:27]
	v_mfma_f32_16x16x32_bf16 v[12:15], v[152:155], v[212:215], v[12:15]
	v_mfma_f32_16x16x32_bf16 v[8:11], v[160:163], v[212:215], v[8:11]
	v_mfma_f32_16x16x32_bf16 v[60:63], v[156:159], v[188:191], v[60:63]
	v_mfma_f32_16x16x32_bf16 v[56:59], v[164:167], v[188:191], v[56:59]
	v_mfma_f32_16x16x32_bf16 v[44:47], v[156:159], v[200:203], v[44:47]
	v_mfma_f32_16x16x32_bf16 v[40:43], v[164:167], v[200:203], v[40:43]
	v_mfma_f32_16x16x32_bf16 v[28:31], v[156:159], v[208:211], v[28:31]
	v_mfma_f32_16x16x32_bf16 v[24:27], v[164:167], v[208:211], v[24:27]
	v_mfma_f32_16x16x32_bf16 v[12:15], v[156:159], v[216:219], v[12:15]
	v_mfma_f32_16x16x32_bf16 v[8:11], v[164:167], v[216:219], v[8:11]
	v_mfma_f32_16x16x32_bf16 v[52:55], v[168:171], v[184:187], v[52:55]
	v_mfma_f32_16x16x32_bf16 v[48:51], v[176:179], v[184:187], v[48:51]
	v_mfma_f32_16x16x32_bf16 v[36:39], v[168:171], v[192:195], v[36:39]
	v_mfma_f32_16x16x32_bf16 v[32:35], v[176:179], v[192:195], v[32:35]
	v_mfma_f32_16x16x32_bf16 v[20:23], v[168:171], v[204:207], v[20:23]
	v_mfma_f32_16x16x32_bf16 v[16:19], v[176:179], v[204:207], v[16:19]
	v_mfma_f32_16x16x32_bf16 v[4:7], v[168:171], v[212:215], v[4:7]
	v_mfma_f32_16x16x32_bf16 v[0:3], v[176:179], v[212:215], v[0:3]
	v_mfma_f32_16x16x32_bf16 v[52:55], v[172:175], v[188:191], v[52:55]
	v_mfma_f32_16x16x32_bf16 v[48:51], v[180:183], v[188:191], v[48:51]
	v_mfma_f32_16x16x32_bf16 v[36:39], v[172:175], v[200:203], v[36:39]
	v_mfma_f32_16x16x32_bf16 v[32:35], v[180:183], v[200:203], v[32:35]
	v_mfma_f32_16x16x32_bf16 v[20:23], v[172:175], v[208:211], v[20:23]
	v_mfma_f32_16x16x32_bf16 v[16:19], v[180:183], v[208:211], v[16:19]
	v_mfma_f32_16x16x32_bf16 v[4:7], v[172:175], v[216:219], v[4:7]
	v_mfma_f32_16x16x32_bf16 v[0:3], v[180:183], v[216:219], v[0:3]
	s_setprio 0
	s_barrier
	s_cbranch_scc0 .LBB0_376
	s_and_b64 vcc, exec, s[14:15]
	s_cbranch_vccz .LBB0_379
	s_barrier

; #define PG8_STAGE(bufoff, gbase, voff) do { _Pragma("unroll") for (int _i = 0; _i < 2; ++_i) \
;         __builtin_amdgcn_global_load_lds((const unsigned*)((const char*)(gbase) + (voff)[_i]), (PG8_LAS unsigned*)(lds + (bufoff) + ldsw + _i * 8192), 16, 0, 0); } while (0)
; #define PG8_LDA(dst, b, h) do { _Pragma("unroll") for (int m = 0; m < 4; ++m) _Pragma("unroll") for (int k = 0; k < 2; ++k) dst[m][k] = *(const PG8_LAS bf16x8*)(lds + PG8_SA(b, h) + aoff + m * 2048 + k * 1024); } while (0)
; #define PG8_LDB(dst, b, h) do { _Pragma("unroll") for (int n = 0; n < 2; ++n) _Pragma("unroll") for (int k = 0; k < 2; ++k) dst[n][k] = *(const PG8_LAS bf16x8*)(lds + PG8_SB(b, h) + boff + n * 2048 + k * 1024); } while (0)
; #define PG8_MMA(ai, bj, At, Bt) do { __builtin_amdgcn_s_setprio(1); _Pragma("unroll") for (int m = 0; m < 4; ++m) _Pragma("unroll") for (int n = 0; n < 2; ++n) _Pragma("unroll") for (int k = 0; k < 2; ++k) \
;         acc[ai][bj][m][n] = __builtin_amdgcn_mfma_f32_16x16x32_bf16(Bt[n][k], At[m][k], acc[ai][bj][m][n], 0, 0, 0); __builtin_amdgcn_s_setprio(0); } while (0)
; #define PG8_WAIT_V(n) asm volatile("s_waitcnt vmcnt(" #n ")" ::: "memory")
; #define PG8_WAIT_L(n) asm volatile("s_waitcnt lgkmcnt(" #n ")" ::: "memory")
; template <class Epi, class Sched, bool ALIGN_EPI = false, bool SP2 = false>
; __device__ __forceinline__ void gemm_phase(PG8_LAS unsigned char* lds, const Gemm g, const Sched& S, const Epi& E) {
;     ...
;             const bool last = (t == nt - 2);
;             const char* a1 = cA + (size_t)(t + 1) * kstep;
;             const char* a2 = last ? nA : cA + (size_t)(t + 2) * kstep; const char* b2 = last ? nB : cB + (size_t)(t + 2) * kstep;
;             const char* a3 = a2 + kstep; const char* b3 = b2 + kstep;
;             if (last && has_next) S.a_ready(nxt);
;             if constexpr (SP2) {
;             PG8_LDB(B0, 0, 0); PG8_LDB(B1, 0, 1); PG8_SCHED; PG8_LDA(At, 0, 0); PG8_STAGE(PG8_SA(1, 1), a1 + hstep, voffA);
;             PG8_WAIT_V(8); PG8_WAIT_L(0); PG8_BAR; PG8_MMA(0, 0, At, B0); PG8_MMA(0, 1, At, B1); PG8_BAR; PG8_SCHED;
;             PG8_LDA(At, 0, 1); PG8_STAGE(PG8_SB(0, 0), b2, voffB); PG8_STAGE(PG8_SB(0, 1), b2 + hstep, voffB); PG8_STAGE(PG8_SA(0, 0), a2, voffA);
;             PG8_WAIT_V(8); PG8_WAIT_L(0); PG8_BAR; PG8_MMA(1, 0, At, B0); PG8_MMA(1, 1, At, B1); PG8_BAR; PG8_SCHED;
.LBB0_452:
	ds_read_b128 v[128:131], v202
	ds_read_b128 v[132:135], v202 offset:1024
	ds_read_b128 v[136:139], v202 offset:2048
	ds_read_b128 v[140:143], v202 offset:3072
	ds_read_b128 v[144:147], v203
	ds_read_b128 v[148:151], v203 offset:1024
	ds_read_b128 v[152:155], v203 offset:2048
	ds_read_b128 v[156:159], v203 offset:3072
	s_add_i32 m0, s33, 0xc000
	ds_read_b128 v[160:163], v204
	ds_read_b128 v[164:167], v204 offset:1024
	ds_read_b128 v[184:187], v204 offset:2048
	ds_read_b128 v[188:191], v204 offset:3072
	ds_read_b128 v[192:195], v204 offset:4096
	ds_read_b128 v[206:209], v204 offset:5120
	ds_read_b128 v[210:213], v204 offset:6144
	ds_read_b128 v[214:217], v204 offset:7168
	global_load_lds_dwordx4 v176, s[70:71]
	s_add_i32 m0, s33, 0xe000
	s_nop 0
	global_load_lds_dwordx4 v178, s[70:71]
	s_add_u32 s72, s70, 0xffe00080
	s_addc_u32 s73, s71, -1
	s_cmpk_eq_i32 s87, 0x7c
	s_cselect_b32 s75, s25, s73
	s_cselect_b32 s74, s63, s72
	s_cselect_b32 s73, s61, s86
	s_cselect_b32 s72, s84, s85
	s_add_i32 s88, s82, s1
	s_mov_b32 m0, s88
	s_waitcnt vmcnt(8)
	s_waitcnt lgkmcnt(0)
	s_setprio 1
	s_barrier
	v_mfma_f32_16x16x32_bf16 v[124:127], v[128:131], v[160:163], v[124:127]
	v_mfma_f32_16x16x32_bf16 v[120:123], v[136:139], v[160:163], v[120:123]
	v_mfma_f32_16x16x32_bf16 v[116:119], v[128:131], v[184:187], v[116:119]
	v_mfma_f32_16x16x32_bf16 v[108:111], v[136:139], v[184:187], v[108:111]
	v_mfma_f32_16x16x32_bf16 v[92:95], v[128:131], v[192:195], v[92:95]
	v_mfma_f32_16x16x32_bf16 v[88:91], v[136:139], v[192:195], v[88:91]
	v_mfma_f32_16x16x32_bf16 v[76:79], v[128:131], v[210:213], v[76:79]
	v_mfma_f32_16x16x32_bf16 v[72:75], v[136:139], v[210:213], v[72:75]
	v_mfma_f32_16x16x32_bf16 v[124:127], v[132:135], v[164:167], v[124:127]
	v_mfma_f32_16x16x32_bf16 v[120:123], v[140:143], v[164:167], v[120:123]
	v_mfma_f32_16x16x32_bf16 v[116:119], v[132:135], v[188:191], v[116:119]
	v_mfma_f32_16x16x32_bf16 v[108:111], v[140:143], v[188:191], v[108:111]
	v_mfma_f32_16x16x32_bf16 v[92:95], v[132:135], v[206:209], v[92:95]
	v_mfma_f32_16x16x32_bf16 v[88:91], v[140:143], v[206:209], v[88:91]
	v_mfma_f32_16x16x32_bf16 v[76:79], v[132:135], v[214:217], v[76:79]
	v_mfma_f32_16x16x32_bf16 v[72:75], v[140:143], v[214:217], v[72:75]
	v_mfma_f32_16x16x32_bf16 v[112:115], v[144:147], v[160:163], v[112:115]
	v_mfma_f32_16x16x32_bf16 v[104:107], v[152:155], v[160:163], v[104:107]
	v_mfma_f32_16x16x32_bf16 v[100:103], v[144:147], v[184:187], v[100:103]
	v_mfma_f32_16x16x32_bf16 v[96:99], v[152:155], v[184:187], v[96:99]
	v_mfma_f32_16x16x32_bf16 v[84:87], v[144:147], v[192:195], v[84:87]
	v_mfma_f32_16x16x32_bf16 v[80:83], v[152:155], v[192:195], v[80:83]
	v_mfma_f32_16x16x32_bf16 v[68:71], v[144:147], v[210:213], v[68:71]
	v_mfma_f32_16x16x32_bf16 v[64:67], v[152:155], v[210:213], v[64:67]
	v_mfma_f32_16x16x32_bf16 v[112:115], v[148:151], v[164:167], v[112:115]
	v_mfma_f32_16x16x32_bf16 v[104:107], v[156:159], v[164:167], v[104:107]
	v_mfma_f32_16x16x32_bf16 v[100:103], v[148:151], v[188:191], v[100:103]
	v_mfma_f32_16x16x32_bf16 v[96:99], v[156:159], v[188:191], v[96:99]
	v_mfma_f32_16x16x32_bf16 v[84:87], v[148:151], v[206:209], v[84:87]
	v_mfma_f32_16x16x32_bf16 v[80:83], v[156:159], v[206:209], v[80:83]
	v_mfma_f32_16x16x32_bf16 v[68:71], v[148:151], v[214:217], v[68:71]
	v_mfma_f32_16x16x32_bf16 v[64:67], v[156:159], v[214:217], v[64:67]
	s_setprio 0
	s_barrier
	ds_read_b128 v[160:163], v204 offset:16384
	ds_read_b128 v[164:167], v204 offset:17408
	ds_read_b128 v[184:187], v204 offset:18432
	ds_read_b128 v[188:191], v204 offset:19456
	ds_read_b128 v[192:195], v204 offset:20480
	ds_read_b128 v[206:209], v204 offset:21504
	ds_read_b128 v[210:213], v204 offset:22528
	ds_read_b128 v[214:217], v204 offset:23552
	global_load_lds_dwordx4 v170, s[72:73]
	s_add_i32 m0, s88, 0x2000
	s_add_u32 s88, s72, 0x200000
	s_addc_u32 s89, s73, 0
	s_add_i32 s94, s83, s1
	global_load_lds_dwordx4 v174, s[72:73]
	s_mov_b32 m0, s94
	s_nop 0
	global_load_lds_dwordx4 v170, s[88:89]
	s_add_i32 m0, s94, 0x2000
	s_nop 0
	global_load_lds_dwordx4 v174, s[88:89]
	s_mov_b32 m0, s33
	s_nop 0
	global_load_lds_dwordx4 v168, s[74:75]
	s_mov_b32 m0, s35
	s_nop 0
	global_load_lds_dwordx4 v172, s[74:75]
	s_waitcnt vmcnt(8)
	s_waitcnt lgkmcnt(0)
	s_setprio 1
	s_barrier
	v_mfma_f32_16x16x32_bf16 v[60:63], v[128:131], v[160:163], v[60:63]
	v_mfma_f32_16x16x32_bf16 v[56:59], v[136:139], v[160:163], v[56:59]
	v_mfma_f32_16x16x32_bf16 v[44:47], v[128:131], v[184:187], v[44:47]
	v_mfma_f32_16x16x32_bf16 v[40:43], v[136:139], v[184:187], v[40:43]
	v_mfma_f32_16x16x32_bf16 v[28:31], v[128:131], v[192:195], v[28:31]
	v_mfma_f32_16x16x32_bf16 v[24:27], v[136:139], v[192:195], v[24:27]
	v_mfma_f32_16x16x32_bf16 v[12:15], v[128:131], v[210:213], v[12:15]
	v_mfma_f32_16x16x32_bf16 v[8:11], v[136:139], v[210:213], v[8:11]
	v_mfma_f32_16x16x32_bf16 v[60:63], v[132:135], v[164:167], v[60:63]
	v_mfma_f32_16x16x32_bf16 v[56:59], v[140:143], v[164:167], v[56:59]
	v_mfma_f32_16x16x32_bf16 v[44:47], v[132:135], v[188:191], v[44:47]
	v_mfma_f32_16x16x32_bf16 v[40:43], v[140:143], v[188:191], v[40:43]
	v_mfma_f32_16x16x32_bf16 v[28:31], v[132:135], v[206:209], v[28:31]
	v_mfma_f32_16x16x32_bf16 v[24:27], v[140:143], v[206:209], v[24:27]
	v_mfma_f32_16x16x32_bf16 v[12:15], v[132:135], v[214:217], v[12:15]
	v_mfma_f32_16x16x32_bf16 v[8:11], v[140:143], v[214:217], v[8:11]
	v_mfma_f32_16x16x32_bf16 v[52:55], v[144:147], v[160:163], v[52:55]
	v_mfma_f32_16x16x32_bf16 v[48:51], v[152:155], v[160:163], v[48:51]
	v_mfma_f32_16x16x32_bf16 v[36:39], v[144:147], v[184:187], v[36:39]
	v_mfma_f32_16x16x32_bf16 v[32:35], v[152:155], v[184:187], v[32:35]
	v_mfma_f32_16x16x32_bf16 v[20:23], v[144:147], v[192:195], v[20:23]
	v_mfma_f32_16x16x32_bf16 v[16:19], v[152:155], v[192:195], v[16:19]
	v_mfma_f32_16x16x32_bf16 v[4:7], v[144:147], v[210:213], v[4:7]
	v_mfma_f32_16x16x32_bf16 v[0:3], v[152:155], v[210:213], v[0:3]
	v_mfma_f32_16x16x32_bf16 v[52:55], v[148:151], v[164:167], v[52:55]
	v_mfma_f32_16x16x32_bf16 v[48:51], v[156:159], v[164:167], v[48:51]
	v_mfma_f32_16x16x32_bf16 v[36:39], v[148:151], v[188:191], v[36:39]
	v_mfma_f32_16x16x32_bf16 v[32:35], v[156:159], v[188:191], v[32:35]
	v_mfma_f32_16x16x32_bf16 v[20:23], v[148:151], v[206:209], v[20:23]
	v_mfma_f32_16x16x32_bf16 v[16:19], v[156:159], v[206:209], v[16:19]
	v_mfma_f32_16x16x32_bf16 v[4:7], v[148:151], v[214:217], v[4:7]
	v_mfma_f32_16x16x32_bf16 v[0:3], v[156:159], v[214:217], v[0:3]
	s_setprio 0
	s_barrier
; #define PG8_STAGE(bufoff, gbase, voff) do { _Pragma("unroll") for (int _i = 0; _i < 2; ++_i) \
;         __builtin_amdgcn_global_load_lds((const unsigned*)((const char*)(gbase) + (voff)[_i]), (PG8_LAS unsigned*)(lds + (bufoff) + ldsw + _i * 8192), 16, 0, 0); } while (0)
; #define PG8_LDA(dst, b, h) do { _Pragma("unroll") for (int m = 0; m < 4; ++m) _Pragma("unroll") for (int k = 0; k < 2; ++k) dst[m][k] = *(const PG8_LAS bf16x8*)(lds + PG8_SA(b, h) + aoff + m * 2048 + k * 1024); } while (0)
; #define PG8_LDB(dst, b, h) do { _Pragma("unroll") for (int n = 0; n < 2; ++n) _Pragma("unroll") for (int k = 0; k < 2; ++k) dst[n][k] = *(const PG8_LAS bf16x8*)(lds + PG8_SB(b, h) + boff + n * 2048 + k * 1024); } while (0)
; #define PG8_MMA(ai, bj, At, Bt) do { __builtin_amdgcn_s_setprio(1); _Pragma("unroll") for (int m = 0; m < 4; ++m) _Pragma("unroll") for (int n = 0; n < 2; ++n) _Pragma("unroll") for (int k = 0; k < 2; ++k) \
;         acc[ai][bj][m][n] = __builtin_amdgcn_mfma_f32_16x16x32_bf16(Bt[n][k], At[m][k], acc[ai][bj][m][n], 0, 0, 0); __builtin_amdgcn_s_setprio(0); } while (0)
; #define PG8_WAIT_V(n) asm volatile("s_waitcnt vmcnt(" #n ")" ::: "memory")
; #define PG8_WAIT_L(n) asm volatile("s_waitcnt lgkmcnt(" #n ")" ::: "memory")
; #define PG8_BAR __builtin_amdgcn_s_barrier()
; #define PG8_SCHED __builtin_amdgcn_sched_barrier(0)
; template <class Epi, class Sched, bool ALIGN_EPI = false, bool SP2 = false>
; __device__ __forceinline__ void gemm_phase(PG8_LAS unsigned char* lds, const Gemm g, const Sched& S, const Epi& E) {
;     ...
;         for (int t = 0; t < nt; t += 2) {
;     ...
;             PG8_LDB(B0, 1, 0); PG8_LDB(B1, 1, 1); PG8_SCHED; PG8_LDA(At, 1, 0); PG8_STAGE(PG8_SA(0, 1), a2 + hstep, voffA);
;             PG8_WAIT_V(8); PG8_WAIT_L(0); PG8_BAR; PG8_MMA(0, 0, At, B0); PG8_MMA(0, 1, At, B1); PG8_BAR; PG8_SCHED;
;             PG8_LDA(At, 1, 1); PG8_STAGE(PG8_SB(1, 0), b3, voffB); PG8_STAGE(PG8_SB(1, 1), b3 + hstep, voffB); PG8_STAGE(PG8_SA(1, 0), a3, voffA);
;             PG8_WAIT_V(8); PG8_WAIT_L(0); PG8_BAR; PG8_MMA(1, 0, At, B0); PG8_MMA(1, 1, At, B1); PG8_BAR; PG8_SCHED;
	ds_read_b128 v[128:131], v218
	ds_read_b128 v[132:135], v218 offset:1024
	ds_read_b128 v[136:139], v218 offset:2048
	ds_read_b128 v[140:143], v218 offset:3072
	ds_read_b128 v[144:147], v219
	ds_read_b128 v[148:151], v219 offset:1024
	ds_read_b128 v[152:155], v219 offset:2048
	ds_read_b128 v[156:159], v219 offset:3072
	ds_read_b128 v[160:163], v204 offset:32768
	ds_read_b128 v[164:167], v204 offset:33792
	ds_read_b128 v[184:187], v204 offset:34816
	ds_read_b128 v[188:191], v204 offset:35840
	ds_read_b128 v[192:195], v204 offset:36864
	ds_read_b128 v[206:209], v204 offset:37888
	ds_read_b128 v[210:213], v204 offset:38912
	ds_read_b128 v[214:217], v204 offset:39936
	s_add_u32 s98, s74, 0x200000
	s_addc_u32 s99, s75, 0
	s_mov_b32 m0, s69
	s_add_u32 s100, s74, 0x80
	s_addc_u32 s101, s75, 0
	global_load_lds_dwordx4 v168, s[98:99]
	s_mov_b32 m0, s76
	s_nop 0
	global_load_lds_dwordx4 v172, s[98:99]
	s_add_i32 s88, 0, 0x18000
	s_add_i32 s89, 0, 0x1c000
	s_add_u32 s98, s72, 0x80
	s_addc_u32 s99, s73, 0
	s_add_i32 s74, s88, s1
	s_mov_b32 m0, s74
	s_waitcnt vmcnt(8)
	s_waitcnt lgkmcnt(0)
	s_setprio 1
	s_barrier
	v_mfma_f32_16x16x32_bf16 v[124:127], v[128:131], v[160:163], v[124:127]
	v_mfma_f32_16x16x32_bf16 v[120:123], v[136:139], v[160:163], v[120:123]
	v_mfma_f32_16x16x32_bf16 v[116:119], v[128:131], v[184:187], v[116:119]
	v_mfma_f32_16x16x32_bf16 v[108:111], v[136:139], v[184:187], v[108:111]
	v_mfma_f32_16x16x32_bf16 v[92:95], v[128:131], v[192:195], v[92:95]
	v_mfma_f32_16x16x32_bf16 v[88:91], v[136:139], v[192:195], v[88:91]
	v_mfma_f32_16x16x32_bf16 v[76:79], v[128:131], v[210:213], v[76:79]
	v_mfma_f32_16x16x32_bf16 v[72:75], v[136:139], v[210:213], v[72:75]
	v_mfma_f32_16x16x32_bf16 v[124:127], v[132:135], v[164:167], v[124:127]
	v_mfma_f32_16x16x32_bf16 v[120:123], v[140:143], v[164:167], v[120:123]
	v_mfma_f32_16x16x32_bf16 v[116:119], v[132:135], v[188:191], v[116:119]
	v_mfma_f32_16x16x32_bf16 v[108:111], v[140:143], v[188:191], v[108:111]
	v_mfma_f32_16x16x32_bf16 v[92:95], v[132:135], v[206:209], v[92:95]
	v_mfma_f32_16x16x32_bf16 v[88:91], v[140:143], v[206:209], v[88:91]
	v_mfma_f32_16x16x32_bf16 v[76:79], v[132:135], v[214:217], v[76:79]
	v_mfma_f32_16x16x32_bf16 v[72:75], v[140:143], v[214:217], v[72:75]
	v_mfma_f32_16x16x32_bf16 v[112:115], v[144:147], v[160:163], v[112:115]
	v_mfma_f32_16x16x32_bf16 v[104:107], v[152:155], v[160:163], v[104:107]
	v_mfma_f32_16x16x32_bf16 v[100:103], v[144:147], v[184:187], v[100:103]
	v_mfma_f32_16x16x32_bf16 v[96:99], v[152:155], v[184:187], v[96:99]
	v_mfma_f32_16x16x32_bf16 v[84:87], v[144:147], v[192:195], v[84:87]
	v_mfma_f32_16x16x32_bf16 v[80:83], v[152:155], v[192:195], v[80:83]
	v_mfma_f32_16x16x32_bf16 v[68:71], v[144:147], v[210:213], v[68:71]
	v_mfma_f32_16x16x32_bf16 v[64:67], v[152:155], v[210:213], v[64:67]
	v_mfma_f32_16x16x32_bf16 v[112:115], v[148:151], v[164:167], v[112:115]
	v_mfma_f32_16x16x32_bf16 v[104:107], v[156:159], v[164:167], v[104:107]
	v_mfma_f32_16x16x32_bf16 v[100:103], v[148:151], v[188:191], v[100:103]
	v_mfma_f32_16x16x32_bf16 v[96:99], v[156:159], v[188:191], v[96:99]
	v_mfma_f32_16x16x32_bf16 v[84:87], v[148:151], v[206:209], v[84:87]
	v_mfma_f32_16x16x32_bf16 v[80:83], v[156:159], v[206:209], v[80:83]
	v_mfma_f32_16x16x32_bf16 v[68:71], v[148:151], v[214:217], v[68:71]
	v_mfma_f32_16x16x32_bf16 v[64:67], v[156:159], v[214:217], v[64:67]
	s_setprio 0
	s_barrier
	ds_read_b128 v[160:163], v204 offset:49152
	ds_read_b128 v[164:167], v204 offset:50176
	ds_read_b128 v[184:187], v204 offset:51200
	ds_read_b128 v[188:191], v204 offset:52224
	ds_read_b128 v[192:195], v204 offset:53248
	ds_read_b128 v[206:209], v204 offset:54272
	ds_read_b128 v[210:213], v204 offset:55296
	ds_read_b128 v[214:217], v204 offset:56320
	global_load_lds_dwordx4 v170, s[98:99]
	s_add_i32 m0, s74, 0x2000
	s_add_u32 s72, s72, 0x200080
	s_addc_u32 s73, s73, 0
	s_add_i32 s74, s89, s1
	global_load_lds_dwordx4 v174, s[98:99]
	s_mov_b32 m0, s74
	s_nop 0
	global_load_lds_dwordx4 v170, s[72:73]
	s_add_i32 m0, s74, 0x2000
	s_nop 0
	global_load_lds_dwordx4 v174, s[72:73]
	s_mov_b32 m0, s78
	s_nop 0
	global_load_lds_dwordx4 v168, s[100:101]
	s_mov_b32 m0, s79
	s_nop 0
	global_load_lds_dwordx4 v172, s[100:101]
	s_add_i32 s87, s87, 2
	s_add_u32 s70, s70, 0x100
	s_addc_u32 s71, s71, 0
	s_add_u32 s85, s85, 0x100
	s_addc_u32 s86, s86, 0
	s_cmpk_gt_u32 s87, 0x7d
	s_waitcnt vmcnt(8)
	s_waitcnt lgkmcnt(0)
	s_setprio 1
	s_barrier
	v_mfma_f32_16x16x32_bf16 v[60:63], v[128:131], v[160:163], v[60:63]
	v_mfma_f32_16x16x32_bf16 v[56:59], v[136:139], v[160:163], v[56:59]
	v_mfma_f32_16x16x32_bf16 v[44:47], v[128:131], v[184:187], v[44:47]
	v_mfma_f32_16x16x32_bf16 v[40:43], v[136:139], v[184:187], v[40:43]
	v_mfma_f32_16x16x32_bf16 v[28:31], v[128:131], v[192:195], v[28:31]
	v_mfma_f32_16x16x32_bf16 v[24:27], v[136:139], v[192:195], v[24:27]
	v_mfma_f32_16x16x32_bf16 v[12:15], v[128:131], v[210:213], v[12:15]
	v_mfma_f32_16x16x32_bf16 v[8:11], v[136:139], v[210:213], v[8:11]
	v_mfma_f32_16x16x32_bf16 v[60:63], v[132:135], v[164:167], v[60:63]
	v_mfma_f32_16x16x32_bf16 v[56:59], v[140:143], v[164:167], v[56:59]
	v_mfma_f32_16x16x32_bf16 v[44:47], v[132:135], v[188:191], v[44:47]
	v_mfma_f32_16x16x32_bf16 v[40:43], v[140:143], v[188:191], v[40:43]
	v_mfma_f32_16x16x32_bf16 v[28:31], v[132:135], v[206:209], v[28:31]
	v_mfma_f32_16x16x32_bf16 v[24:27], v[140:143], v[206:209], v[24:27]
	v_mfma_f32_16x16x32_bf16 v[12:15], v[132:135], v[214:217], v[12:15]
	v_mfma_f32_16x16x32_bf16 v[8:11], v[140:143], v[214:217], v[8:11]
	v_mfma_f32_16x16x32_bf16 v[52:55], v[144:147], v[160:163], v[52:55]
	v_mfma_f32_16x16x32_bf16 v[48:51], v[152:155], v[160:163], v[48:51]
	v_mfma_f32_16x16x32_bf16 v[36:39], v[144:147], v[184:187], v[36:39]
	v_mfma_f32_16x16x32_bf16 v[32:35], v[152:155], v[184:187], v[32:35]
	v_mfma_f32_16x16x32_bf16 v[20:23], v[144:147], v[192:195], v[20:23]
	v_mfma_f32_16x16x32_bf16 v[16:19], v[152:155], v[192:195], v[16:19]
	v_mfma_f32_16x16x32_bf16 v[4:7], v[144:147], v[210:213], v[4:7]
	v_mfma_f32_16x16x32_bf16 v[0:3], v[152:155], v[210:213], v[0:3]
	v_mfma_f32_16x16x32_bf16 v[52:55], v[148:151], v[164:167], v[52:55]
	v_mfma_f32_16x16x32_bf16 v[48:51], v[156:159], v[164:167], v[48:51]
	v_mfma_f32_16x16x32_bf16 v[36:39], v[148:151], v[188:191], v[36:39]
	v_mfma_f32_16x16x32_bf16 v[32:35], v[156:159], v[188:191], v[32:35]
	v_mfma_f32_16x16x32_bf16 v[20:23], v[148:151], v[206:209], v[20:23]
	v_mfma_f32_16x16x32_bf16 v[16:19], v[156:159], v[206:209], v[16:19]
	v_mfma_f32_16x16x32_bf16 v[4:7], v[148:151], v[214:217], v[4:7]
	v_mfma_f32_16x16x32_bf16 v[0:3], v[156:159], v[214:217], v[0:3]
	s_setprio 0
	s_barrier
	s_cbranch_scc0 .LBB0_452
	s_and_b64 vcc, exec, s[36:37]
	s_cbranch_vccz .LBB0_455
	s_barrier

; #define PG8_STAGE(bufoff, gbase, voff) do { _Pragma("unroll") for (int _i = 0; _i < 2; ++_i) \
;         __builtin_amdgcn_global_load_lds((const unsigned*)((const char*)(gbase) + (voff)[_i]), (PG8_LAS unsigned*)(lds + (bufoff) + ldsw + _i * 8192), 16, 0, 0); } while (0)
; #define PG8_LDA(dst, b, h) do { _Pragma("unroll") for (int m = 0; m < 4; ++m) _Pragma("unroll") for (int k = 0; k < 2; ++k) dst[m][k] = *(const PG8_LAS bf16x8*)(lds + PG8_SA(b, h) + aoff + m * 2048 + k * 1024); } while (0)
; #define PG8_LDB(dst, b, h) do { _Pragma("unroll") for (int n = 0; n < 2; ++n) _Pragma("unroll") for (int k = 0; k < 2; ++k) dst[n][k] = *(const PG8_LAS bf16x8*)(lds + PG8_SB(b, h) + boff + n * 2048 + k * 1024); } while (0)
; #define PG8_MMA(ai, bj, At, Bt) do { __builtin_amdgcn_s_setprio(1); _Pragma("unroll") for (int m = 0; m < 4; ++m) _Pragma("unroll") for (int n = 0; n < 2; ++n) _Pragma("unroll") for (int k = 0; k < 2; ++k) \
;         acc[ai][bj][m][n] = __builtin_amdgcn_mfma_f32_16x16x32_bf16(Bt[n][k], At[m][k], acc[ai][bj][m][n], 0, 0, 0); __builtin_amdgcn_s_setprio(0); } while (0)
; #define PG8_WAIT_V(n) asm volatile("s_waitcnt vmcnt(" #n ")" ::: "memory")
; #define PG8_WAIT_L(n) asm volatile("s_waitcnt lgkmcnt(" #n ")" ::: "memory")
; template <class Epi, class Sched, bool ALIGN_EPI = false, bool SP2 = false>
; __device__ __forceinline__ void gemm_phase(PG8_LAS unsigned char* lds, const Gemm g, const Sched& S, const Epi& E) {
;     ...
;             const bool last = (t == nt - 2);
;             const char* a1 = cA + (size_t)(t + 1) * kstep;
;             const char* a2 = last ? nA : cA + (size_t)(t + 2) * kstep; const char* b2 = last ? nB : cB + (size_t)(t + 2) * kstep;
;             const char* a3 = a2 + kstep; const char* b3 = b2 + kstep;
;             if (last && has_next) S.a_ready(nxt);
;             if constexpr (SP2) {
;             PG8_LDB(B0, 0, 0); PG8_LDB(B1, 0, 1); PG8_SCHED; PG8_LDA(At, 0, 0); PG8_STAGE(PG8_SA(1, 1), a1 + hstep, voffA);
;             PG8_WAIT_V(8); PG8_WAIT_L(0); PG8_BAR; PG8_MMA(0, 0, At, B0); PG8_MMA(0, 1, At, B1); PG8_BAR; PG8_SCHED;
;             PG8_LDA(At, 0, 1); PG8_STAGE(PG8_SB(0, 0), b2, voffB); PG8_STAGE(PG8_SB(0, 1), b2 + hstep, voffB); PG8_STAGE(PG8_SA(0, 0), a2, voffA);
;             PG8_WAIT_V(8); PG8_WAIT_L(0); PG8_BAR; PG8_MMA(1, 0, At, B0); PG8_MMA(1, 1, At, B1); PG8_BAR; PG8_SCHED;
.LBB0_528:
	ds_read_b128 v[152:155], v149
	ds_read_b128 v[156:159], v149 offset:1024
	ds_read_b128 v[160:163], v149 offset:2048
	ds_read_b128 v[164:167], v149 offset:3072
	ds_read_b128 v[168:171], v150
	ds_read_b128 v[172:175], v150 offset:1024
	ds_read_b128 v[176:179], v150 offset:2048
	ds_read_b128 v[180:183], v150 offset:3072
	s_add_i32 m0, s14, 0xc000
	ds_read_b128 v[184:187], v151
	ds_read_b128 v[188:191], v151 offset:1024
	ds_read_b128 v[192:195], v151 offset:2048
	ds_read_b128 v[200:203], v151 offset:3072
	ds_read_b128 v[204:207], v151 offset:4096
	ds_read_b128 v[208:211], v151 offset:5120
	ds_read_b128 v[212:215], v151 offset:6144
	ds_read_b128 v[216:219], v151 offset:7168
	global_load_lds_dwordx4 v136, s[70:71]
	s_add_i32 m0, s14, 0xe000
	s_nop 0
	global_load_lds_dwordx4 v138, s[70:71]
	s_add_u32 s72, s70, 0xfff80080
	s_addc_u32 s73, s71, -1
	s_cmp_eq_u32 s86, 28
	s_cselect_b32 s75, s25, s73
	s_cselect_b32 s74, s63, s72
	s_cselect_b32 s73, s61, s85
	s_cselect_b32 s72, s83, s84
	s_add_i32 s87, s80, s1
	s_mov_b32 m0, s87
	s_waitcnt vmcnt(8)
	s_waitcnt lgkmcnt(0)
	s_setprio 1
	s_barrier
	v_mfma_f32_16x16x32_bf16 v[124:127], v[152:155], v[184:187], v[124:127]
	v_mfma_f32_16x16x32_bf16 v[120:123], v[160:163], v[184:187], v[120:123]
	v_mfma_f32_16x16x32_bf16 v[108:111], v[152:155], v[192:195], v[108:111]
	v_mfma_f32_16x16x32_bf16 v[104:107], v[160:163], v[192:195], v[104:107]
	v_mfma_f32_16x16x32_bf16 v[92:95], v[152:155], v[204:207], v[92:95]
	v_mfma_f32_16x16x32_bf16 v[88:91], v[160:163], v[204:207], v[88:91]
	v_mfma_f32_16x16x32_bf16 v[76:79], v[152:155], v[212:215], v[76:79]
	v_mfma_f32_16x16x32_bf16 v[72:75], v[160:163], v[212:215], v[72:75]
	v_mfma_f32_16x16x32_bf16 v[124:127], v[156:159], v[188:191], v[124:127]
	v_mfma_f32_16x16x32_bf16 v[120:123], v[164:167], v[188:191], v[120:123]
	v_mfma_f32_16x16x32_bf16 v[108:111], v[156:159], v[200:203], v[108:111]
	v_mfma_f32_16x16x32_bf16 v[104:107], v[164:167], v[200:203], v[104:107]
	v_mfma_f32_16x16x32_bf16 v[92:95], v[156:159], v[208:211], v[92:95]
	v_mfma_f32_16x16x32_bf16 v[88:91], v[164:167], v[208:211], v[88:91]
	v_mfma_f32_16x16x32_bf16 v[76:79], v[156:159], v[216:219], v[76:79]
	v_mfma_f32_16x16x32_bf16 v[72:75], v[164:167], v[216:219], v[72:75]
	v_mfma_f32_16x16x32_bf16 v[116:119], v[168:171], v[184:187], v[116:119]
	v_mfma_f32_16x16x32_bf16 v[112:115], v[176:179], v[184:187], v[112:115]
	v_mfma_f32_16x16x32_bf16 v[100:103], v[168:171], v[192:195], v[100:103]
	v_mfma_f32_16x16x32_bf16 v[96:99], v[176:179], v[192:195], v[96:99]
	v_mfma_f32_16x16x32_bf16 v[84:87], v[168:171], v[204:207], v[84:87]
	v_mfma_f32_16x16x32_bf16 v[80:83], v[176:179], v[204:207], v[80:83]
	v_mfma_f32_16x16x32_bf16 v[68:71], v[168:171], v[212:215], v[68:71]
	v_mfma_f32_16x16x32_bf16 v[64:67], v[176:179], v[212:215], v[64:67]
	v_mfma_f32_16x16x32_bf16 v[116:119], v[172:175], v[188:191], v[116:119]
	v_mfma_f32_16x16x32_bf16 v[112:115], v[180:183], v[188:191], v[112:115]
	v_mfma_f32_16x16x32_bf16 v[100:103], v[172:175], v[200:203], v[100:103]
	v_mfma_f32_16x16x32_bf16 v[96:99], v[180:183], v[200:203], v[96:99]
	v_mfma_f32_16x16x32_bf16 v[84:87], v[172:175], v[208:211], v[84:87]
	v_mfma_f32_16x16x32_bf16 v[80:83], v[180:183], v[208:211], v[80:83]
	v_mfma_f32_16x16x32_bf16 v[68:71], v[172:175], v[216:219], v[68:71]
	v_mfma_f32_16x16x32_bf16 v[64:67], v[180:183], v[216:219], v[64:67]
	s_setprio 0
	s_barrier
	ds_read_b128 v[184:187], v151 offset:16384
	ds_read_b128 v[188:191], v151 offset:17408
	ds_read_b128 v[192:195], v151 offset:18432
	ds_read_b128 v[200:203], v151 offset:19456
	ds_read_b128 v[204:207], v151 offset:20480
	ds_read_b128 v[208:211], v151 offset:21504
	ds_read_b128 v[212:215], v151 offset:22528
	ds_read_b128 v[216:219], v151 offset:23552
	global_load_lds_dwordx4 v130, s[72:73]
	s_add_i32 m0, s87, 0x2000
	s_add_u32 s88, s72, 0x80000
	s_addc_u32 s89, s73, 0
	s_add_i32 s87, s81, s1
	global_load_lds_dwordx4 v134, s[72:73]
	s_mov_b32 m0, s87
	s_nop 0
	global_load_lds_dwordx4 v130, s[88:89]
	s_add_i32 m0, s87, 0x2000
	s_nop 0
	global_load_lds_dwordx4 v134, s[88:89]
	s_mov_b32 m0, s14
	s_nop 0
	global_load_lds_dwordx4 v128, s[74:75]
	s_mov_b32 m0, s15
	s_nop 0
	global_load_lds_dwordx4 v132, s[74:75]
	s_waitcnt vmcnt(8)
	s_waitcnt lgkmcnt(0)
	s_setprio 1
	s_barrier
	v_mfma_f32_16x16x32_bf16 v[60:63], v[152:155], v[184:187], v[60:63]
	v_mfma_f32_16x16x32_bf16 v[56:59], v[160:163], v[184:187], v[56:59]
	v_mfma_f32_16x16x32_bf16 v[44:47], v[152:155], v[192:195], v[44:47]
	v_mfma_f32_16x16x32_bf16 v[40:43], v[160:163], v[192:195], v[40:43]
	v_mfma_f32_16x16x32_bf16 v[28:31], v[152:155], v[204:207], v[28:31]
	v_mfma_f32_16x16x32_bf16 v[24:27], v[160:163], v[204:207], v[24:27]
	v_mfma_f32_16x16x32_bf16 v[12:15], v[152:155], v[212:215], v[12:15]
	v_mfma_f32_16x16x32_bf16 v[8:11], v[160:163], v[212:215], v[8:11]
	v_mfma_f32_16x16x32_bf16 v[60:63], v[156:159], v[188:191], v[60:63]
	v_mfma_f32_16x16x32_bf16 v[56:59], v[164:167], v[188:191], v[56:59]
	v_mfma_f32_16x16x32_bf16 v[44:47], v[156:159], v[200:203], v[44:47]
	v_mfma_f32_16x16x32_bf16 v[40:43], v[164:167], v[200:203], v[40:43]
	v_mfma_f32_16x16x32_bf16 v[28:31], v[156:159], v[208:211], v[28:31]
	v_mfma_f32_16x16x32_bf16 v[24:27], v[164:167], v[208:211], v[24:27]
	v_mfma_f32_16x16x32_bf16 v[12:15], v[156:159], v[216:219], v[12:15]
	v_mfma_f32_16x16x32_bf16 v[8:11], v[164:167], v[216:219], v[8:11]
	v_mfma_f32_16x16x32_bf16 v[52:55], v[168:171], v[184:187], v[52:55]
	v_mfma_f32_16x16x32_bf16 v[48:51], v[176:179], v[184:187], v[48:51]
	v_mfma_f32_16x16x32_bf16 v[36:39], v[168:171], v[192:195], v[36:39]
	v_mfma_f32_16x16x32_bf16 v[32:35], v[176:179], v[192:195], v[32:35]
	v_mfma_f32_16x16x32_bf16 v[20:23], v[168:171], v[204:207], v[20:23]
	v_mfma_f32_16x16x32_bf16 v[16:19], v[176:179], v[204:207], v[16:19]
	v_mfma_f32_16x16x32_bf16 v[4:7], v[168:171], v[212:215], v[4:7]
	v_mfma_f32_16x16x32_bf16 v[0:3], v[176:179], v[212:215], v[0:3]
	v_mfma_f32_16x16x32_bf16 v[52:55], v[172:175], v[188:191], v[52:55]
	v_mfma_f32_16x16x32_bf16 v[48:51], v[180:183], v[188:191], v[48:51]
	v_mfma_f32_16x16x32_bf16 v[36:39], v[172:175], v[200:203], v[36:39]
	v_mfma_f32_16x16x32_bf16 v[32:35], v[180:183], v[200:203], v[32:35]
	v_mfma_f32_16x16x32_bf16 v[20:23], v[172:175], v[208:211], v[20:23]
	v_mfma_f32_16x16x32_bf16 v[16:19], v[180:183], v[208:211], v[16:19]
	v_mfma_f32_16x16x32_bf16 v[4:7], v[172:175], v[216:219], v[4:7]
	v_mfma_f32_16x16x32_bf16 v[0:3], v[180:183], v[216:219], v[0:3]
	s_setprio 0
	s_barrier
; #define PG8_STAGE(bufoff, gbase, voff) do { _Pragma("unroll") for (int _i = 0; _i < 2; ++_i) \
;         __builtin_amdgcn_global_load_lds((const unsigned*)((const char*)(gbase) + (voff)[_i]), (PG8_LAS unsigned*)(lds + (bufoff) + ldsw + _i * 8192), 16, 0, 0); } while (0)
; #define PG8_LDA(dst, b, h) do { _Pragma("unroll") for (int m = 0; m < 4; ++m) _Pragma("unroll") for (int k = 0; k < 2; ++k) dst[m][k] = *(const PG8_LAS bf16x8*)(lds + PG8_SA(b, h) + aoff + m * 2048 + k * 1024); } while (0)
; #define PG8_LDB(dst, b, h) do { _Pragma("unroll") for (int n = 0; n < 2; ++n) _Pragma("unroll") for (int k = 0; k < 2; ++k) dst[n][k] = *(const PG8_LAS bf16x8*)(lds + PG8_SB(b, h) + boff + n * 2048 + k * 1024); } while (0)
; #define PG8_MMA(ai, bj, At, Bt) do { __builtin_amdgcn_s_setprio(1); _Pragma("unroll") for (int m = 0; m < 4; ++m) _Pragma("unroll") for (int n = 0; n < 2; ++n) _Pragma("unroll") for (int k = 0; k < 2; ++k) \
;         acc[ai][bj][m][n] = __builtin_amdgcn_mfma_f32_16x16x32_bf16(Bt[n][k], At[m][k], acc[ai][bj][m][n], 0, 0, 0); __builtin_amdgcn_s_setprio(0); } while (0)
; #define PG8_WAIT_V(n) asm volatile("s_waitcnt vmcnt(" #n ")" ::: "memory")
; #define PG8_WAIT_L(n) asm volatile("s_waitcnt lgkmcnt(" #n ")" ::: "memory")
; #define PG8_BAR __builtin_amdgcn_s_barrier()
; #define PG8_SCHED __builtin_amdgcn_sched_barrier(0)
; template <class Epi, class Sched, bool ALIGN_EPI = false, bool SP2 = false>
; __device__ __forceinline__ void gemm_phase(PG8_LAS unsigned char* lds, const Gemm g, const Sched& S, const Epi& E) {
;     ...
;         for (int t = 0; t < nt; t += 2) {
;     ...
;             PG8_LDB(B0, 1, 0); PG8_LDB(B1, 1, 1); PG8_SCHED; PG8_LDA(At, 1, 0); PG8_STAGE(PG8_SA(0, 1), a2 + hstep, voffA);
;             PG8_WAIT_V(8); PG8_WAIT_L(0); PG8_BAR; PG8_MMA(0, 0, At, B0); PG8_MMA(0, 1, At, B1); PG8_BAR; PG8_SCHED;
;             PG8_LDA(At, 1, 1); PG8_STAGE(PG8_SB(1, 0), b3, voffB); PG8_STAGE(PG8_SB(1, 1), b3 + hstep, voffB); PG8_STAGE(PG8_SA(1, 0), a3, voffA);
;             PG8_WAIT_V(8); PG8_WAIT_L(0); PG8_BAR; PG8_MMA(1, 0, At, B0); PG8_MMA(1, 1, At, B1); PG8_BAR; PG8_SCHED;
	ds_read_b128 v[152:155], v196
	ds_read_b128 v[156:159], v196 offset:1024
	ds_read_b128 v[160:163], v196 offset:2048
	ds_read_b128 v[164:167], v196 offset:3072
	ds_read_b128 v[168:171], v197
	ds_read_b128 v[172:175], v197 offset:1024
	ds_read_b128 v[176:179], v197 offset:2048
	ds_read_b128 v[180:183], v197 offset:3072
	ds_read_b128 v[184:187], v151 offset:32768
	ds_read_b128 v[188:191], v151 offset:33792
	ds_read_b128 v[192:195], v151 offset:34816
	ds_read_b128 v[200:203], v151 offset:35840
	ds_read_b128 v[204:207], v151 offset:36864
	ds_read_b128 v[208:211], v151 offset:37888
	ds_read_b128 v[212:215], v151 offset:38912
	ds_read_b128 v[216:219], v151 offset:39936
	s_add_u32 s98, s74, 0x80000
	s_addc_u32 s99, s75, 0
	s_mov_b32 m0, s33
	s_add_u32 s100, s74, 0x80
	s_addc_u32 s101, s75, 0
	global_load_lds_dwordx4 v128, s[98:99]
	s_mov_b32 m0, s35
	s_nop 0
	global_load_lds_dwordx4 v132, s[98:99]
	s_add_i32 s87, 0, 0x18000
	s_add_i32 s88, 0, 0x1c000
	s_add_u32 s98, s72, 0x80
	s_addc_u32 s99, s73, 0
	s_add_i32 s74, s87, s1
	s_mov_b32 m0, s74
	s_waitcnt vmcnt(8)
	s_waitcnt lgkmcnt(0)
	s_setprio 1
	s_barrier
	v_mfma_f32_16x16x32_bf16 v[124:127], v[152:155], v[184:187], v[124:127]
	v_mfma_f32_16x16x32_bf16 v[120:123], v[160:163], v[184:187], v[120:123]
	v_mfma_f32_16x16x32_bf16 v[108:111], v[152:155], v[192:195], v[108:111]
	v_mfma_f32_16x16x32_bf16 v[104:107], v[160:163], v[192:195], v[104:107]
	v_mfma_f32_16x16x32_bf16 v[92:95], v[152:155], v[204:207], v[92:95]
	v_mfma_f32_16x16x32_bf16 v[88:91], v[160:163], v[204:207], v[88:91]
	v_mfma_f32_16x16x32_bf16 v[76:79], v[152:155], v[212:215], v[76:79]
	v_mfma_f32_16x16x32_bf16 v[72:75], v[160:163], v[212:215], v[72:75]
	v_mfma_f32_16x16x32_bf16 v[124:127], v[156:159], v[188:191], v[124:127]
	v_mfma_f32_16x16x32_bf16 v[120:123], v[164:167], v[188:191], v[120:123]
	v_mfma_f32_16x16x32_bf16 v[108:111], v[156:159], v[200:203], v[108:111]
	v_mfma_f32_16x16x32_bf16 v[104:107], v[164:167], v[200:203], v[104:107]
	v_mfma_f32_16x16x32_bf16 v[92:95], v[156:159], v[208:211], v[92:95]
	v_mfma_f32_16x16x32_bf16 v[88:91], v[164:167], v[208:211], v[88:91]
	v_mfma_f32_16x16x32_bf16 v[76:79], v[156:159], v[216:219], v[76:79]
	v_mfma_f32_16x16x32_bf16 v[72:75], v[164:167], v[216:219], v[72:75]
	v_mfma_f32_16x16x32_bf16 v[116:119], v[168:171], v[184:187], v[116:119]
	v_mfma_f32_16x16x32_bf16 v[112:115], v[176:179], v[184:187], v[112:115]
	v_mfma_f32_16x16x32_bf16 v[100:103], v[168:171], v[192:195], v[100:103]
	v_mfma_f32_16x16x32_bf16 v[96:99], v[176:179], v[192:195], v[96:99]
	v_mfma_f32_16x16x32_bf16 v[84:87], v[168:171], v[204:207], v[84:87]
	v_mfma_f32_16x16x32_bf16 v[80:83], v[176:179], v[204:207], v[80:83]
	v_mfma_f32_16x16x32_bf16 v[68:71], v[168:171], v[212:215], v[68:71]
	v_mfma_f32_16x16x32_bf16 v[64:67], v[176:179], v[212:215], v[64:67]
	v_mfma_f32_16x16x32_bf16 v[116:119], v[172:175], v[188:191], v[116:119]
	v_mfma_f32_16x16x32_bf16 v[112:115], v[180:183], v[188:191], v[112:115]
	v_mfma_f32_16x16x32_bf16 v[100:103], v[172:175], v[200:203], v[100:103]
	v_mfma_f32_16x16x32_bf16 v[96:99], v[180:183], v[200:203], v[96:99]
	v_mfma_f32_16x16x32_bf16 v[84:87], v[172:175], v[208:211], v[84:87]
	v_mfma_f32_16x16x32_bf16 v[80:83], v[180:183], v[208:211], v[80:83]
	v_mfma_f32_16x16x32_bf16 v[68:71], v[172:175], v[216:219], v[68:71]
	v_mfma_f32_16x16x32_bf16 v[64:67], v[180:183], v[216:219], v[64:67]
	s_setprio 0
	s_barrier
	ds_read_b128 v[184:187], v151 offset:49152
	ds_read_b128 v[188:191], v151 offset:50176
	ds_read_b128 v[192:195], v151 offset:51200
	ds_read_b128 v[200:203], v151 offset:52224
	ds_read_b128 v[204:207], v151 offset:53248
	ds_read_b128 v[208:211], v151 offset:54272
	ds_read_b128 v[212:215], v151 offset:55296
	ds_read_b128 v[216:219], v151 offset:56320
	global_load_lds_dwordx4 v130, s[98:99]
	s_add_i32 m0, s74, 0x2000
	s_add_u32 s72, s72, 0x80080
	s_addc_u32 s73, s73, 0
	s_add_i32 s74, s88, s1
	global_load_lds_dwordx4 v134, s[98:99]
	s_mov_b32 m0, s74
	s_nop 0
	global_load_lds_dwordx4 v130, s[72:73]
	s_add_i32 m0, s74, 0x2000
	s_nop 0
	global_load_lds_dwordx4 v134, s[72:73]
	s_mov_b32 m0, s76
	s_nop 0
	global_load_lds_dwordx4 v128, s[100:101]
	s_mov_b32 m0, s77
	s_nop 0
	global_load_lds_dwordx4 v132, s[100:101]
	s_add_i32 s86, s86, 2
	s_add_u32 s70, s70, 0x100
	s_addc_u32 s71, s71, 0
	s_add_u32 s84, s84, 0x100
	s_addc_u32 s85, s85, 0
	s_cmp_gt_u32 s86, 29
	s_waitcnt vmcnt(8)
	s_waitcnt lgkmcnt(0)
	s_setprio 1
	s_barrier
	v_mfma_f32_16x16x32_bf16 v[60:63], v[152:155], v[184:187], v[60:63]
	v_mfma_f32_16x16x32_bf16 v[56:59], v[160:163], v[184:187], v[56:59]
	v_mfma_f32_16x16x32_bf16 v[44:47], v[152:155], v[192:195], v[44:47]
	v_mfma_f32_16x16x32_bf16 v[40:43], v[160:163], v[192:195], v[40:43]
	v_mfma_f32_16x16x32_bf16 v[28:31], v[152:155], v[204:207], v[28:31]
	v_mfma_f32_16x16x32_bf16 v[24:27], v[160:163], v[204:207], v[24:27]
	v_mfma_f32_16x16x32_bf16 v[12:15], v[152:155], v[212:215], v[12:15]
	v_mfma_f32_16x16x32_bf16 v[8:11], v[160:163], v[212:215], v[8:11]
	v_mfma_f32_16x16x32_bf16 v[60:63], v[156:159], v[188:191], v[60:63]
	v_mfma_f32_16x16x32_bf16 v[56:59], v[164:167], v[188:191], v[56:59]
	v_mfma_f32_16x16x32_bf16 v[44:47], v[156:159], v[200:203], v[44:47]
	v_mfma_f32_16x16x32_bf16 v[40:43], v[164:167], v[200:203], v[40:43]
	v_mfma_f32_16x16x32_bf16 v[28:31], v[156:159], v[208:211], v[28:31]
	v_mfma_f32_16x16x32_bf16 v[24:27], v[164:167], v[208:211], v[24:27]
	v_mfma_f32_16x16x32_bf16 v[12:15], v[156:159], v[216:219], v[12:15]
	v_mfma_f32_16x16x32_bf16 v[8:11], v[164:167], v[216:219], v[8:11]
	v_mfma_f32_16x16x32_bf16 v[52:55], v[168:171], v[184:187], v[52:55]
	v_mfma_f32_16x16x32_bf16 v[48:51], v[176:179], v[184:187], v[48:51]
	v_mfma_f32_16x16x32_bf16 v[36:39], v[168:171], v[192:195], v[36:39]
	v_mfma_f32_16x16x32_bf16 v[32:35], v[176:179], v[192:195], v[32:35]
	v_mfma_f32_16x16x32_bf16 v[20:23], v[168:171], v[204:207], v[20:23]
	v_mfma_f32_16x16x32_bf16 v[16:19], v[176:179], v[204:207], v[16:19]
	v_mfma_f32_16x16x32_bf16 v[4:7], v[168:171], v[212:215], v[4:7]
	v_mfma_f32_16x16x32_bf16 v[0:3], v[176:179], v[212:215], v[0:3]
	v_mfma_f32_16x16x32_bf16 v[52:55], v[172:175], v[188:191], v[52:55]
	v_mfma_f32_16x16x32_bf16 v[48:51], v[180:183], v[188:191], v[48:51]
	v_mfma_f32_16x16x32_bf16 v[36:39], v[172:175], v[200:203], v[36:39]
	v_mfma_f32_16x16x32_bf16 v[32:35], v[180:183], v[200:203], v[32:35]
	v_mfma_f32_16x16x32_bf16 v[20:23], v[172:175], v[208:211], v[20:23]
	v_mfma_f32_16x16x32_bf16 v[16:19], v[180:183], v[208:211], v[16:19]
	v_mfma_f32_16x16x32_bf16 v[4:7], v[172:175], v[216:219], v[4:7]
	v_mfma_f32_16x16x32_bf16 v[0:3], v[180:183], v[216:219], v[0:3]
	s_setprio 0
	s_barrier
	s_cbranch_scc0 .LBB0_528
	s_and_b64 vcc, exec, s[44:45]
	s_cbranch_vccz .LBB0_531
	s_barrier

; #define PG8_STAGE(bufoff, gbase, voff) do { _Pragma("unroll") for (int _i = 0; _i < 2; ++_i) \
;         __builtin_amdgcn_global_load_lds((const unsigned*)((const char*)(gbase) + (voff)[_i]), (PG8_LAS unsigned*)(lds + (bufoff) + ldsw + _i * 8192), 16, 0, 0); } while (0)
; #define PG8_LDA(dst, b, h) do { _Pragma("unroll") for (int m = 0; m < 4; ++m) _Pragma("unroll") for (int k = 0; k < 2; ++k) dst[m][k] = *(const PG8_LAS bf16x8*)(lds + PG8_SA(b, h) + aoff + m * 2048 + k * 1024); } while (0)
; #define PG8_LDB(dst, b, h) do { _Pragma("unroll") for (int n = 0; n < 2; ++n) _Pragma("unroll") for (int k = 0; k < 2; ++k) dst[n][k] = *(const PG8_LAS bf16x8*)(lds + PG8_SB(b, h) + boff + n * 2048 + k * 1024); } while (0)
; #define PG8_MMA(ai, bj, At, Bt) do { __builtin_amdgcn_s_setprio(1); _Pragma("unroll") for (int m = 0; m < 4; ++m) _Pragma("unroll") for (int n = 0; n < 2; ++n) _Pragma("unroll") for (int k = 0; k < 2; ++k) \
;         acc[ai][bj][m][n] = __builtin_amdgcn_mfma_f32_16x16x32_bf16(Bt[n][k], At[m][k], acc[ai][bj][m][n], 0, 0, 0); __builtin_amdgcn_s_setprio(0); } while (0)
; #define PG8_WAIT_V(n) asm volatile("s_waitcnt vmcnt(" #n ")" ::: "memory")
; #define PG8_WAIT_L(n) asm volatile("s_waitcnt lgkmcnt(" #n ")" ::: "memory")
; template <class Epi, class Sched, bool ALIGN_EPI = false, bool SP2 = false>
; __device__ __forceinline__ void gemm_phase(PG8_LAS unsigned char* lds, const Gemm g, const Sched& S, const Epi& E) {
;     ...
;             const bool last = (t == nt - 2);
;             const char* a1 = cA + (size_t)(t + 1) * kstep;
;             const char* a2 = last ? nA : cA + (size_t)(t + 2) * kstep; const char* b2 = last ? nB : cB + (size_t)(t + 2) * kstep;
;             const char* a3 = a2 + kstep; const char* b3 = b2 + kstep;
;             if (last && has_next) S.a_ready(nxt);
;             if constexpr (SP2) {
;             PG8_LDB(B0, 0, 0); PG8_LDB(B1, 0, 1); PG8_SCHED; PG8_LDA(At, 0, 0); PG8_STAGE(PG8_SA(1, 1), a1 + hstep, voffA);
;             PG8_WAIT_V(8); PG8_WAIT_L(0); PG8_BAR; PG8_MMA(0, 0, At, B0); PG8_MMA(0, 1, At, B1); PG8_BAR; PG8_SCHED;
;             PG8_LDA(At, 0, 1); PG8_STAGE(PG8_SB(0, 0), b2, voffB); PG8_STAGE(PG8_SB(0, 1), b2 + hstep, voffB); PG8_STAGE(PG8_SA(0, 0), a2, voffA);
;             PG8_WAIT_V(8); PG8_WAIT_L(0); PG8_BAR; PG8_MMA(1, 0, At, B0); PG8_MMA(1, 1, At, B1); PG8_BAR; PG8_SCHED;
.LBB0_604:
	ds_read_b128 v[128:131], v202
	ds_read_b128 v[132:135], v202 offset:1024
	ds_read_b128 v[136:139], v202 offset:2048
	ds_read_b128 v[140:143], v202 offset:3072
	ds_read_b128 v[144:147], v203
	ds_read_b128 v[148:151], v203 offset:1024
	ds_read_b128 v[152:155], v203 offset:2048
	ds_read_b128 v[156:159], v203 offset:3072
	s_add_i32 m0, s4, 0xc000
	ds_read_b128 v[160:163], v204
	ds_read_b128 v[164:167], v204 offset:1024
	ds_read_b128 v[184:187], v204 offset:2048
	ds_read_b128 v[188:191], v204 offset:3072
	ds_read_b128 v[192:195], v204 offset:4096
	ds_read_b128 v[206:209], v204 offset:5120
	ds_read_b128 v[210:213], v204 offset:6144
	ds_read_b128 v[214:217], v204 offset:7168
	global_load_lds_dwordx4 v176, s[72:73]
	s_add_i32 m0, s4, 0xe000
	s_nop 0
	global_load_lds_dwordx4 v178, s[72:73]
	s_add_u32 s74, s72, 0xffe00080
	s_addc_u32 s75, s73, -1
	s_cmpk_eq_i32 s85, 0x7c
	s_cselect_b32 s77, s25, s75
	s_cselect_b32 s76, s65, s74
	s_cselect_b32 s75, s63, s84
	s_cselect_b32 s74, s82, s83
	s_add_i32 s86, s80, s1
	s_mov_b32 m0, s86
	s_waitcnt vmcnt(8)
	s_waitcnt lgkmcnt(0)
	s_setprio 1
	s_barrier
	v_mfma_f32_16x16x32_bf16 v[124:127], v[128:131], v[160:163], v[124:127]
	v_mfma_f32_16x16x32_bf16 v[120:123], v[136:139], v[160:163], v[120:123]
	v_mfma_f32_16x16x32_bf16 v[116:119], v[128:131], v[184:187], v[116:119]
	v_mfma_f32_16x16x32_bf16 v[108:111], v[136:139], v[184:187], v[108:111]
	v_mfma_f32_16x16x32_bf16 v[92:95], v[128:131], v[192:195], v[92:95]
	v_mfma_f32_16x16x32_bf16 v[88:91], v[136:139], v[192:195], v[88:91]
	v_mfma_f32_16x16x32_bf16 v[76:79], v[128:131], v[210:213], v[76:79]
	v_mfma_f32_16x16x32_bf16 v[72:75], v[136:139], v[210:213], v[72:75]
	v_mfma_f32_16x16x32_bf16 v[124:127], v[132:135], v[164:167], v[124:127]
	v_mfma_f32_16x16x32_bf16 v[120:123], v[140:143], v[164:167], v[120:123]
	v_mfma_f32_16x16x32_bf16 v[116:119], v[132:135], v[188:191], v[116:119]
	v_mfma_f32_16x16x32_bf16 v[108:111], v[140:143], v[188:191], v[108:111]
	v_mfma_f32_16x16x32_bf16 v[92:95], v[132:135], v[206:209], v[92:95]
	v_mfma_f32_16x16x32_bf16 v[88:91], v[140:143], v[206:209], v[88:91]
	v_mfma_f32_16x16x32_bf16 v[76:79], v[132:135], v[214:217], v[76:79]
	v_mfma_f32_16x16x32_bf16 v[72:75], v[140:143], v[214:217], v[72:75]
	v_mfma_f32_16x16x32_bf16 v[112:115], v[144:147], v[160:163], v[112:115]
	v_mfma_f32_16x16x32_bf16 v[104:107], v[152:155], v[160:163], v[104:107]
	v_mfma_f32_16x16x32_bf16 v[100:103], v[144:147], v[184:187], v[100:103]
	v_mfma_f32_16x16x32_bf16 v[96:99], v[152:155], v[184:187], v[96:99]
	v_mfma_f32_16x16x32_bf16 v[84:87], v[144:147], v[192:195], v[84:87]
	v_mfma_f32_16x16x32_bf16 v[80:83], v[152:155], v[192:195], v[80:83]
	v_mfma_f32_16x16x32_bf16 v[68:71], v[144:147], v[210:213], v[68:71]
	v_mfma_f32_16x16x32_bf16 v[64:67], v[152:155], v[210:213], v[64:67]
	v_mfma_f32_16x16x32_bf16 v[112:115], v[148:151], v[164:167], v[112:115]
	v_mfma_f32_16x16x32_bf16 v[104:107], v[156:159], v[164:167], v[104:107]
	v_mfma_f32_16x16x32_bf16 v[100:103], v[148:151], v[188:191], v[100:103]
	v_mfma_f32_16x16x32_bf16 v[96:99], v[156:159], v[188:191], v[96:99]
	v_mfma_f32_16x16x32_bf16 v[84:87], v[148:151], v[206:209], v[84:87]
	v_mfma_f32_16x16x32_bf16 v[80:83], v[156:159], v[206:209], v[80:83]
	v_mfma_f32_16x16x32_bf16 v[68:71], v[148:151], v[214:217], v[68:71]
	v_mfma_f32_16x16x32_bf16 v[64:67], v[156:159], v[214:217], v[64:67]
	s_setprio 0
	s_barrier
	ds_read_b128 v[160:163], v204 offset:16384
	ds_read_b128 v[164:167], v204 offset:17408
	ds_read_b128 v[184:187], v204 offset:18432
	ds_read_b128 v[188:191], v204 offset:19456
	ds_read_b128 v[192:195], v204 offset:20480
	ds_read_b128 v[206:209], v204 offset:21504
	ds_read_b128 v[210:213], v204 offset:22528
	ds_read_b128 v[214:217], v204 offset:23552
	global_load_lds_dwordx4 v170, s[74:75]
	s_add_i32 m0, s86, 0x2000
	s_add_u32 s86, s74, 0x200000
	s_addc_u32 s87, s75, 0
	s_add_i32 s88, s81, s1
	global_load_lds_dwordx4 v174, s[74:75]
	s_mov_b32 m0, s88
	s_nop 0
	global_load_lds_dwordx4 v170, s[86:87]
	s_add_i32 m0, s88, 0x2000
	s_nop 0
	global_load_lds_dwordx4 v174, s[86:87]
	s_mov_b32 m0, s4
	s_nop 0
	global_load_lds_dwordx4 v168, s[76:77]
	s_mov_b32 m0, s5
	s_nop 0
	global_load_lds_dwordx4 v172, s[76:77]
	s_waitcnt vmcnt(8)
	s_waitcnt lgkmcnt(0)
	s_setprio 1
	s_barrier
	v_mfma_f32_16x16x32_bf16 v[60:63], v[128:131], v[160:163], v[60:63]
	v_mfma_f32_16x16x32_bf16 v[56:59], v[136:139], v[160:163], v[56:59]
	v_mfma_f32_16x16x32_bf16 v[44:47], v[128:131], v[184:187], v[44:47]
	v_mfma_f32_16x16x32_bf16 v[40:43], v[136:139], v[184:187], v[40:43]
	v_mfma_f32_16x16x32_bf16 v[28:31], v[128:131], v[192:195], v[28:31]
	v_mfma_f32_16x16x32_bf16 v[24:27], v[136:139], v[192:195], v[24:27]
	v_mfma_f32_16x16x32_bf16 v[12:15], v[128:131], v[210:213], v[12:15]
	v_mfma_f32_16x16x32_bf16 v[8:11], v[136:139], v[210:213], v[8:11]
	v_mfma_f32_16x16x32_bf16 v[60:63], v[132:135], v[164:167], v[60:63]
	v_mfma_f32_16x16x32_bf16 v[56:59], v[140:143], v[164:167], v[56:59]
	v_mfma_f32_16x16x32_bf16 v[44:47], v[132:135], v[188:191], v[44:47]
	v_mfma_f32_16x16x32_bf16 v[40:43], v[140:143], v[188:191], v[40:43]
	v_mfma_f32_16x16x32_bf16 v[28:31], v[132:135], v[206:209], v[28:31]
	v_mfma_f32_16x16x32_bf16 v[24:27], v[140:143], v[206:209], v[24:27]
	v_mfma_f32_16x16x32_bf16 v[12:15], v[132:135], v[214:217], v[12:15]
	v_mfma_f32_16x16x32_bf16 v[8:11], v[140:143], v[214:217], v[8:11]
	v_mfma_f32_16x16x32_bf16 v[52:55], v[144:147], v[160:163], v[52:55]
	v_mfma_f32_16x16x32_bf16 v[48:51], v[152:155], v[160:163], v[48:51]
	v_mfma_f32_16x16x32_bf16 v[36:39], v[144:147], v[184:187], v[36:39]
	v_mfma_f32_16x16x32_bf16 v[32:35], v[152:155], v[184:187], v[32:35]
	v_mfma_f32_16x16x32_bf16 v[20:23], v[144:147], v[192:195], v[20:23]
	v_mfma_f32_16x16x32_bf16 v[16:19], v[152:155], v[192:195], v[16:19]
	v_mfma_f32_16x16x32_bf16 v[4:7], v[144:147], v[210:213], v[4:7]
	v_mfma_f32_16x16x32_bf16 v[0:3], v[152:155], v[210:213], v[0:3]
	v_mfma_f32_16x16x32_bf16 v[52:55], v[148:151], v[164:167], v[52:55]
	v_mfma_f32_16x16x32_bf16 v[48:51], v[156:159], v[164:167], v[48:51]
	v_mfma_f32_16x16x32_bf16 v[36:39], v[148:151], v[188:191], v[36:39]
	v_mfma_f32_16x16x32_bf16 v[32:35], v[156:159], v[188:191], v[32:35]
	v_mfma_f32_16x16x32_bf16 v[20:23], v[148:151], v[206:209], v[20:23]
	v_mfma_f32_16x16x32_bf16 v[16:19], v[156:159], v[206:209], v[16:19]
	v_mfma_f32_16x16x32_bf16 v[4:7], v[148:151], v[214:217], v[4:7]
	v_mfma_f32_16x16x32_bf16 v[0:3], v[156:159], v[214:217], v[0:3]
	s_setprio 0
	s_barrier
; #define PG8_STAGE(bufoff, gbase, voff) do { _Pragma("unroll") for (int _i = 0; _i < 2; ++_i) \
;         __builtin_amdgcn_global_load_lds((const unsigned*)((const char*)(gbase) + (voff)[_i]), (PG8_LAS unsigned*)(lds + (bufoff) + ldsw + _i * 8192), 16, 0, 0); } while (0)
; #define PG8_LDA(dst, b, h) do { _Pragma("unroll") for (int m = 0; m < 4; ++m) _Pragma("unroll") for (int k = 0; k < 2; ++k) dst[m][k] = *(const PG8_LAS bf16x8*)(lds + PG8_SA(b, h) + aoff + m * 2048 + k * 1024); } while (0)
; #define PG8_LDB(dst, b, h) do { _Pragma("unroll") for (int n = 0; n < 2; ++n) _Pragma("unroll") for (int k = 0; k < 2; ++k) dst[n][k] = *(const PG8_LAS bf16x8*)(lds + PG8_SB(b, h) + boff + n * 2048 + k * 1024); } while (0)
; #define PG8_MMA(ai, bj, At, Bt) do { __builtin_amdgcn_s_setprio(1); _Pragma("unroll") for (int m = 0; m < 4; ++m) _Pragma("unroll") for (int n = 0; n < 2; ++n) _Pragma("unroll") for (int k = 0; k < 2; ++k) \
;         acc[ai][bj][m][n] = __builtin_amdgcn_mfma_f32_16x16x32_bf16(Bt[n][k], At[m][k], acc[ai][bj][m][n], 0, 0, 0); __builtin_amdgcn_s_setprio(0); } while (0)
; #define PG8_WAIT_V(n) asm volatile("s_waitcnt vmcnt(" #n ")" ::: "memory")
; #define PG8_WAIT_L(n) asm volatile("s_waitcnt lgkmcnt(" #n ")" ::: "memory")
; #define PG8_BAR __builtin_amdgcn_s_barrier()
; #define PG8_SCHED __builtin_amdgcn_sched_barrier(0)
; template <class Epi, class Sched, bool ALIGN_EPI = false, bool SP2 = false>
; __device__ __forceinline__ void gemm_phase(PG8_LAS unsigned char* lds, const Gemm g, const Sched& S, const Epi& E) {
;     ...
;         for (int t = 0; t < nt; t += 2) {
;     ...
;             PG8_LDB(B0, 1, 0); PG8_LDB(B1, 1, 1); PG8_SCHED; PG8_LDA(At, 1, 0); PG8_STAGE(PG8_SA(0, 1), a2 + hstep, voffA);
;             PG8_WAIT_V(8); PG8_WAIT_L(0); PG8_BAR; PG8_MMA(0, 0, At, B0); PG8_MMA(0, 1, At, B1); PG8_BAR; PG8_SCHED;
;             PG8_LDA(At, 1, 1); PG8_STAGE(PG8_SB(1, 0), b3, voffB); PG8_STAGE(PG8_SB(1, 1), b3 + hstep, voffB); PG8_STAGE(PG8_SA(1, 0), a3, voffA);
;             PG8_WAIT_V(8); PG8_WAIT_L(0); PG8_BAR; PG8_MMA(1, 0, At, B0); PG8_MMA(1, 1, At, B1); PG8_BAR; PG8_SCHED;
	ds_read_b128 v[128:131], v218
	ds_read_b128 v[132:135], v218 offset:1024
	ds_read_b128 v[136:139], v218 offset:2048
	ds_read_b128 v[140:143], v218 offset:3072
	ds_read_b128 v[144:147], v219
	ds_read_b128 v[148:151], v219 offset:1024
	ds_read_b128 v[152:155], v219 offset:2048
	ds_read_b128 v[156:159], v219 offset:3072
	ds_read_b128 v[160:163], v204 offset:32768
	ds_read_b128 v[164:167], v204 offset:33792
	ds_read_b128 v[184:187], v204 offset:34816
	ds_read_b128 v[188:191], v204 offset:35840
	ds_read_b128 v[192:195], v204 offset:36864
	ds_read_b128 v[206:209], v204 offset:37888
	ds_read_b128 v[210:213], v204 offset:38912
	ds_read_b128 v[214:217], v204 offset:39936
	s_add_u32 s98, s76, 0x200000
	s_addc_u32 s99, s77, 0
	s_mov_b32 m0, s14
	s_add_u32 s100, s76, 0x80
	s_addc_u32 s101, s77, 0
	global_load_lds_dwordx4 v168, s[98:99]
	s_mov_b32 m0, s15
	s_nop 0
	global_load_lds_dwordx4 v172, s[98:99]
	s_add_i32 s86, 0, 0x18000
	s_add_i32 s87, 0, 0x1c000
	s_add_u32 s98, s74, 0x80
	s_addc_u32 s99, s75, 0
	s_add_i32 s76, s86, s1
	s_mov_b32 m0, s76
	s_waitcnt vmcnt(8)
	s_waitcnt lgkmcnt(0)
	s_setprio 1
	s_barrier
	v_mfma_f32_16x16x32_bf16 v[124:127], v[128:131], v[160:163], v[124:127]
	v_mfma_f32_16x16x32_bf16 v[120:123], v[136:139], v[160:163], v[120:123]
	v_mfma_f32_16x16x32_bf16 v[116:119], v[128:131], v[184:187], v[116:119]
	v_mfma_f32_16x16x32_bf16 v[108:111], v[136:139], v[184:187], v[108:111]
	v_mfma_f32_16x16x32_bf16 v[92:95], v[128:131], v[192:195], v[92:95]
	v_mfma_f32_16x16x32_bf16 v[88:91], v[136:139], v[192:195], v[88:91]
	v_mfma_f32_16x16x32_bf16 v[76:79], v[128:131], v[210:213], v[76:79]
	v_mfma_f32_16x16x32_bf16 v[72:75], v[136:139], v[210:213], v[72:75]
	v_mfma_f32_16x16x32_bf16 v[124:127], v[132:135], v[164:167], v[124:127]
	v_mfma_f32_16x16x32_bf16 v[120:123], v[140:143], v[164:167], v[120:123]
	v_mfma_f32_16x16x32_bf16 v[116:119], v[132:135], v[188:191], v[116:119]
	v_mfma_f32_16x16x32_bf16 v[108:111], v[140:143], v[188:191], v[108:111]
	v_mfma_f32_16x16x32_bf16 v[92:95], v[132:135], v[206:209], v[92:95]
	v_mfma_f32_16x16x32_bf16 v[88:91], v[140:143], v[206:209], v[88:91]
	v_mfma_f32_16x16x32_bf16 v[76:79], v[132:135], v[214:217], v[76:79]
	v_mfma_f32_16x16x32_bf16 v[72:75], v[140:143], v[214:217], v[72:75]
	v_mfma_f32_16x16x32_bf16 v[112:115], v[144:147], v[160:163], v[112:115]
	v_mfma_f32_16x16x32_bf16 v[104:107], v[152:155], v[160:163], v[104:107]
	v_mfma_f32_16x16x32_bf16 v[100:103], v[144:147], v[184:187], v[100:103]
	v_mfma_f32_16x16x32_bf16 v[96:99], v[152:155], v[184:187], v[96:99]
	v_mfma_f32_16x16x32_bf16 v[84:87], v[144:147], v[192:195], v[84:87]
	v_mfma_f32_16x16x32_bf16 v[80:83], v[152:155], v[192:195], v[80:83]
	v_mfma_f32_16x16x32_bf16 v[68:71], v[144:147], v[210:213], v[68:71]
	v_mfma_f32_16x16x32_bf16 v[64:67], v[152:155], v[210:213], v[64:67]
	v_mfma_f32_16x16x32_bf16 v[112:115], v[148:151], v[164:167], v[112:115]
	v_mfma_f32_16x16x32_bf16 v[104:107], v[156:159], v[164:167], v[104:107]
	v_mfma_f32_16x16x32_bf16 v[100:103], v[148:151], v[188:191], v[100:103]
	v_mfma_f32_16x16x32_bf16 v[96:99], v[156:159], v[188:191], v[96:99]
	v_mfma_f32_16x16x32_bf16 v[84:87], v[148:151], v[206:209], v[84:87]
	v_mfma_f32_16x16x32_bf16 v[80:83], v[156:159], v[206:209], v[80:83]
	v_mfma_f32_16x16x32_bf16 v[68:71], v[148:151], v[214:217], v[68:71]
	v_mfma_f32_16x16x32_bf16 v[64:67], v[156:159], v[214:217], v[64:67]
	s_setprio 0
	s_barrier
	ds_read_b128 v[160:163], v204 offset:49152
	ds_read_b128 v[164:167], v204 offset:50176
	ds_read_b128 v[184:187], v204 offset:51200
	ds_read_b128 v[188:191], v204 offset:52224
	ds_read_b128 v[192:195], v204 offset:53248
	ds_read_b128 v[206:209], v204 offset:54272
	ds_read_b128 v[210:213], v204 offset:55296
	ds_read_b128 v[214:217], v204 offset:56320
	global_load_lds_dwordx4 v170, s[98:99]
	s_add_i32 m0, s76, 0x2000
	s_add_u32 s74, s74, 0x200080
	s_addc_u32 s75, s75, 0
	s_add_i32 s76, s87, s1
	global_load_lds_dwordx4 v174, s[98:99]
	s_mov_b32 m0, s76
	s_nop 0
	global_load_lds_dwordx4 v170, s[74:75]
	s_add_i32 m0, s76, 0x2000
	s_nop 0
	global_load_lds_dwordx4 v174, s[74:75]
	s_mov_b32 m0, s35
	s_nop 0
	global_load_lds_dwordx4 v168, s[100:101]
	s_mov_b32 m0, s71
	s_nop 0
	global_load_lds_dwordx4 v172, s[100:101]
	s_add_i32 s85, s85, 2
	s_add_u32 s72, s72, 0x100
	s_addc_u32 s73, s73, 0
	s_add_u32 s83, s83, 0x100
	s_addc_u32 s84, s84, 0
	s_cmpk_gt_u32 s85, 0x7d
	s_waitcnt vmcnt(8)
	s_waitcnt lgkmcnt(0)
	s_setprio 1
	s_barrier
	v_mfma_f32_16x16x32_bf16 v[60:63], v[128:131], v[160:163], v[60:63]
	v_mfma_f32_16x16x32_bf16 v[56:59], v[136:139], v[160:163], v[56:59]
	v_mfma_f32_16x16x32_bf16 v[44:47], v[128:131], v[184:187], v[44:47]
	v_mfma_f32_16x16x32_bf16 v[40:43], v[136:139], v[184:187], v[40:43]
	v_mfma_f32_16x16x32_bf16 v[28:31], v[128:131], v[192:195], v[28:31]
	v_mfma_f32_16x16x32_bf16 v[24:27], v[136:139], v[192:195], v[24:27]
	v_mfma_f32_16x16x32_bf16 v[12:15], v[128:131], v[210:213], v[12:15]
	v_mfma_f32_16x16x32_bf16 v[8:11], v[136:139], v[210:213], v[8:11]
	v_mfma_f32_16x16x32_bf16 v[60:63], v[132:135], v[164:167], v[60:63]
	v_mfma_f32_16x16x32_bf16 v[56:59], v[140:143], v[164:167], v[56:59]
	v_mfma_f32_16x16x32_bf16 v[44:47], v[132:135], v[188:191], v[44:47]
	v_mfma_f32_16x16x32_bf16 v[40:43], v[140:143], v[188:191], v[40:43]
	v_mfma_f32_16x16x32_bf16 v[28:31], v[132:135], v[206:209], v[28:31]
	v_mfma_f32_16x16x32_bf16 v[24:27], v[140:143], v[206:209], v[24:27]
	v_mfma_f32_16x16x32_bf16 v[12:15], v[132:135], v[214:217], v[12:15]
	v_mfma_f32_16x16x32_bf16 v[8:11], v[140:143], v[214:217], v[8:11]
	v_mfma_f32_16x16x32_bf16 v[52:55], v[144:147], v[160:163], v[52:55]
	v_mfma_f32_16x16x32_bf16 v[48:51], v[152:155], v[160:163], v[48:51]
	v_mfma_f32_16x16x32_bf16 v[36:39], v[144:147], v[184:187], v[36:39]
	v_mfma_f32_16x16x32_bf16 v[32:35], v[152:155], v[184:187], v[32:35]
	v_mfma_f32_16x16x32_bf16 v[20:23], v[144:147], v[192:195], v[20:23]
	v_mfma_f32_16x16x32_bf16 v[16:19], v[152:155], v[192:195], v[16:19]
	v_mfma_f32_16x16x32_bf16 v[4:7], v[144:147], v[210:213], v[4:7]
	v_mfma_f32_16x16x32_bf16 v[0:3], v[152:155], v[210:213], v[0:3]
	v_mfma_f32_16x16x32_bf16 v[52:55], v[148:151], v[164:167], v[52:55]
	v_mfma_f32_16x16x32_bf16 v[48:51], v[156:159], v[164:167], v[48:51]
	v_mfma_f32_16x16x32_bf16 v[36:39], v[148:151], v[188:191], v[36:39]
	v_mfma_f32_16x16x32_bf16 v[32:35], v[156:159], v[188:191], v[32:35]
	v_mfma_f32_16x16x32_bf16 v[20:23], v[148:151], v[206:209], v[20:23]
	v_mfma_f32_16x16x32_bf16 v[16:19], v[156:159], v[206:209], v[16:19]
	v_mfma_f32_16x16x32_bf16 v[4:7], v[148:151], v[214:217], v[4:7]
	v_mfma_f32_16x16x32_bf16 v[0:3], v[156:159], v[214:217], v[0:3]
	s_setprio 0
	s_barrier
	s_cbranch_scc0 .LBB0_604
	s_and_b64 vcc, exec, s[48:49]
	s_cbranch_vccz .LBB0_607
	s_barrier

; #define PG8_STAGE(bufoff, gbase, voff) do { _Pragma("unroll") for (int _i = 0; _i < 2; ++_i) \
;         __builtin_amdgcn_global_load_lds((const unsigned*)((const char*)(gbase) + (voff)[_i]), (PG8_LAS unsigned*)(lds + (bufoff) + ldsw + _i * 8192), 16, 0, 0); } while (0)
; #define PG8_LDA(dst, b, h) do { _Pragma("unroll") for (int m = 0; m < 4; ++m) _Pragma("unroll") for (int k = 0; k < 2; ++k) dst[m][k] = *(const PG8_LAS bf16x8*)(lds + PG8_SA(b, h) + aoff + m * 2048 + k * 1024); } while (0)
; #define PG8_LDB(dst, b, h) do { _Pragma("unroll") for (int n = 0; n < 2; ++n) _Pragma("unroll") for (int k = 0; k < 2; ++k) dst[n][k] = *(const PG8_LAS bf16x8*)(lds + PG8_SB(b, h) + boff + n * 2048 + k * 1024); } while (0)
; #define PG8_MMA(ai, bj, At, Bt) do { __builtin_amdgcn_s_setprio(1); _Pragma("unroll") for (int m = 0; m < 4; ++m) _Pragma("unroll") for (int n = 0; n < 2; ++n) _Pragma("unroll") for (int k = 0; k < 2; ++k) \
;         acc[ai][bj][m][n] = __builtin_amdgcn_mfma_f32_16x16x32_bf16(Bt[n][k], At[m][k], acc[ai][bj][m][n], 0, 0, 0); __builtin_amdgcn_s_setprio(0); } while (0)
; #define PG8_WAIT_V(n) asm volatile("s_waitcnt vmcnt(" #n ")" ::: "memory")
; #define PG8_WAIT_L(n) asm volatile("s_waitcnt lgkmcnt(" #n ")" ::: "memory")
; template <class Epi, class Sched, bool ALIGN_EPI = false, bool SP2 = false>
; __device__ __forceinline__ void gemm_phase(PG8_LAS unsigned char* lds, const Gemm g, const Sched& S, const Epi& E) {
;     ...
;             const bool last = (t == nt - 2);
;             const char* a1 = cA + (size_t)(t + 1) * kstep;
;             const char* a2 = last ? nA : cA + (size_t)(t + 2) * kstep; const char* b2 = last ? nB : cB + (size_t)(t + 2) * kstep;
;             const char* a3 = a2 + kstep; const char* b3 = b2 + kstep;
;             if (last && has_next) S.a_ready(nxt);
;             if constexpr (SP2) {
;             PG8_LDB(B0, 0, 0); PG8_LDB(B1, 0, 1); PG8_SCHED; PG8_LDA(At, 0, 0); PG8_STAGE(PG8_SA(1, 1), a1 + hstep, voffA);
;             PG8_WAIT_V(8); PG8_WAIT_L(0); PG8_BAR; PG8_MMA(0, 0, At, B0); PG8_MMA(0, 1, At, B1); PG8_BAR; PG8_SCHED;
;             PG8_LDA(At, 0, 1); PG8_STAGE(PG8_SB(0, 0), b2, voffB); PG8_STAGE(PG8_SB(0, 1), b2 + hstep, voffB); PG8_STAGE(PG8_SA(0, 0), a2, voffA);
;             PG8_WAIT_V(8); PG8_WAIT_L(0); PG8_BAR; PG8_MMA(1, 0, At, B0); PG8_MMA(1, 1, At, B1); PG8_BAR; PG8_SCHED;
.LBB0_735:
	ds_read_b128 v[156:159], v151
	ds_read_b128 v[160:163], v151 offset:1024
	ds_read_b128 v[164:167], v151 offset:2048
	ds_read_b128 v[168:171], v151 offset:3072
	ds_read_b128 v[172:175], v152
	ds_read_b128 v[176:179], v152 offset:1024
	ds_read_b128 v[180:183], v152 offset:2048
	ds_read_b128 v[184:187], v152 offset:3072
	s_add_i32 m0, s4, 0xc000
	ds_read_b128 v[188:191], v153
	ds_read_b128 v[192:195], v153 offset:1024
	ds_read_b128 v[200:203], v153 offset:2048
	ds_read_b128 v[204:207], v153 offset:3072
	ds_read_b128 v[208:211], v153 offset:4096
	ds_read_b128 v[212:215], v153 offset:5120
	ds_read_b128 v[216:219], v153 offset:6144
	ds_read_b128 v[220:223], v153 offset:7168
	global_load_lds_dwordx4 v138, s[68:69]
	s_add_i32 m0, s4, 0xe000
	s_nop 0
	global_load_lds_dwordx4 v140, s[68:69]
	s_add_u32 s70, s68, 0xfff80080
	s_addc_u32 s71, s69, -1
	s_cmp_eq_u32 s82, 28
	s_cselect_b32 s73, s25, s71
	s_cselect_b32 s72, s61, s70
	s_cselect_b32 s71, s49, s81
	s_cselect_b32 s70, s79, s80
	s_add_i32 s83, s77, s1
	s_mov_b32 m0, s83
	s_waitcnt vmcnt(8)
	s_waitcnt lgkmcnt(0)
	s_setprio 1
	s_barrier
	v_mfma_f32_16x16x32_bf16 v[124:127], v[156:159], v[188:191], v[124:127]
	v_mfma_f32_16x16x32_bf16 v[120:123], v[164:167], v[188:191], v[120:123]
	v_mfma_f32_16x16x32_bf16 v[108:111], v[156:159], v[200:203], v[108:111]
	v_mfma_f32_16x16x32_bf16 v[104:107], v[164:167], v[200:203], v[104:107]
	v_mfma_f32_16x16x32_bf16 v[96:99], v[156:159], v[208:211], v[96:99]
	v_mfma_f32_16x16x32_bf16 v[88:91], v[164:167], v[208:211], v[88:91]
	v_mfma_f32_16x16x32_bf16 v[80:83], v[156:159], v[216:219], v[80:83]
	v_mfma_f32_16x16x32_bf16 v[72:75], v[164:167], v[216:219], v[72:75]
	v_mfma_f32_16x16x32_bf16 v[124:127], v[160:163], v[192:195], v[124:127]
	v_mfma_f32_16x16x32_bf16 v[120:123], v[168:171], v[192:195], v[120:123]
	v_mfma_f32_16x16x32_bf16 v[108:111], v[160:163], v[204:207], v[108:111]
	v_mfma_f32_16x16x32_bf16 v[104:107], v[168:171], v[204:207], v[104:107]
	v_mfma_f32_16x16x32_bf16 v[96:99], v[160:163], v[212:215], v[96:99]
	v_mfma_f32_16x16x32_bf16 v[88:91], v[168:171], v[212:215], v[88:91]
	v_mfma_f32_16x16x32_bf16 v[80:83], v[160:163], v[220:223], v[80:83]
	v_mfma_f32_16x16x32_bf16 v[72:75], v[168:171], v[220:223], v[72:75]
	v_mfma_f32_16x16x32_bf16 v[116:119], v[172:175], v[188:191], v[116:119]
	v_mfma_f32_16x16x32_bf16 v[112:115], v[180:183], v[188:191], v[112:115]
	v_mfma_f32_16x16x32_bf16 v[100:103], v[172:175], v[200:203], v[100:103]
	v_mfma_f32_16x16x32_bf16 v[92:95], v[180:183], v[200:203], v[92:95]
	v_mfma_f32_16x16x32_bf16 v[84:87], v[172:175], v[208:211], v[84:87]
	v_mfma_f32_16x16x32_bf16 v[76:79], v[180:183], v[208:211], v[76:79]
	v_mfma_f32_16x16x32_bf16 v[68:71], v[172:175], v[216:219], v[68:71]
	v_mfma_f32_16x16x32_bf16 v[64:67], v[180:183], v[216:219], v[64:67]
	v_mfma_f32_16x16x32_bf16 v[116:119], v[176:179], v[192:195], v[116:119]
	v_mfma_f32_16x16x32_bf16 v[112:115], v[184:187], v[192:195], v[112:115]
	v_mfma_f32_16x16x32_bf16 v[100:103], v[176:179], v[204:207], v[100:103]
	v_mfma_f32_16x16x32_bf16 v[92:95], v[184:187], v[204:207], v[92:95]
	v_mfma_f32_16x16x32_bf16 v[84:87], v[176:179], v[212:215], v[84:87]
	v_mfma_f32_16x16x32_bf16 v[76:79], v[184:187], v[212:215], v[76:79]
	v_mfma_f32_16x16x32_bf16 v[68:71], v[176:179], v[220:223], v[68:71]
	v_mfma_f32_16x16x32_bf16 v[64:67], v[184:187], v[220:223], v[64:67]
	s_setprio 0
	s_barrier
	ds_read_b128 v[188:191], v153 offset:16384
	ds_read_b128 v[192:195], v153 offset:17408
	ds_read_b128 v[200:203], v153 offset:18432
	ds_read_b128 v[204:207], v153 offset:19456
	ds_read_b128 v[208:211], v153 offset:20480
	ds_read_b128 v[212:215], v153 offset:21504
	ds_read_b128 v[216:219], v153 offset:22528
	ds_read_b128 v[220:223], v153 offset:23552
	global_load_lds_dwordx4 v130, s[70:71]
	s_add_i32 m0, s83, 0x2000
	s_add_u32 s84, s70, 0x80000
	s_addc_u32 s85, s71, 0
	s_add_i32 s83, s78, s1
	global_load_lds_dwordx4 v134, s[70:71]
	s_mov_b32 m0, s83
	s_nop 0
	global_load_lds_dwordx4 v130, s[84:85]
	s_add_i32 m0, s83, 0x2000
	s_nop 0
	global_load_lds_dwordx4 v134, s[84:85]
	s_mov_b32 m0, s4
	s_nop 0
	global_load_lds_dwordx4 v128, s[72:73]
	s_mov_b32 m0, s5
	s_nop 0
	global_load_lds_dwordx4 v132, s[72:73]
	s_waitcnt vmcnt(8)
	s_waitcnt lgkmcnt(0)
	s_setprio 1
	s_barrier
	v_mfma_f32_16x16x32_bf16 v[60:63], v[156:159], v[188:191], v[60:63]
	v_mfma_f32_16x16x32_bf16 v[56:59], v[164:167], v[188:191], v[56:59]
	v_mfma_f32_16x16x32_bf16 v[44:47], v[156:159], v[200:203], v[44:47]
	v_mfma_f32_16x16x32_bf16 v[40:43], v[164:167], v[200:203], v[40:43]
	v_mfma_f32_16x16x32_bf16 v[32:35], v[156:159], v[208:211], v[32:35]
	v_mfma_f32_16x16x32_bf16 v[24:27], v[164:167], v[208:211], v[24:27]
	v_mfma_f32_16x16x32_bf16 v[16:19], v[156:159], v[216:219], v[16:19]
	v_mfma_f32_16x16x32_bf16 v[8:11], v[164:167], v[216:219], v[8:11]
	v_mfma_f32_16x16x32_bf16 v[60:63], v[160:163], v[192:195], v[60:63]
	v_mfma_f32_16x16x32_bf16 v[56:59], v[168:171], v[192:195], v[56:59]
	v_mfma_f32_16x16x32_bf16 v[44:47], v[160:163], v[204:207], v[44:47]
	v_mfma_f32_16x16x32_bf16 v[40:43], v[168:171], v[204:207], v[40:43]
	v_mfma_f32_16x16x32_bf16 v[32:35], v[160:163], v[212:215], v[32:35]
	v_mfma_f32_16x16x32_bf16 v[24:27], v[168:171], v[212:215], v[24:27]
	v_mfma_f32_16x16x32_bf16 v[16:19], v[160:163], v[220:223], v[16:19]
	v_mfma_f32_16x16x32_bf16 v[8:11], v[168:171], v[220:223], v[8:11]
	v_mfma_f32_16x16x32_bf16 v[52:55], v[172:175], v[188:191], v[52:55]
	v_mfma_f32_16x16x32_bf16 v[48:51], v[180:183], v[188:191], v[48:51]
	v_mfma_f32_16x16x32_bf16 v[36:39], v[172:175], v[200:203], v[36:39]
	v_mfma_f32_16x16x32_bf16 v[28:31], v[180:183], v[200:203], v[28:31]
	v_mfma_f32_16x16x32_bf16 v[20:23], v[172:175], v[208:211], v[20:23]
	v_mfma_f32_16x16x32_bf16 v[12:15], v[180:183], v[208:211], v[12:15]
	v_mfma_f32_16x16x32_bf16 v[4:7], v[172:175], v[216:219], v[4:7]
	v_mfma_f32_16x16x32_bf16 v[0:3], v[180:183], v[216:219], v[0:3]
	v_mfma_f32_16x16x32_bf16 v[52:55], v[176:179], v[192:195], v[52:55]
	v_mfma_f32_16x16x32_bf16 v[48:51], v[184:187], v[192:195], v[48:51]
	v_mfma_f32_16x16x32_bf16 v[36:39], v[176:179], v[204:207], v[36:39]
	v_mfma_f32_16x16x32_bf16 v[28:31], v[184:187], v[204:207], v[28:31]
	v_mfma_f32_16x16x32_bf16 v[20:23], v[176:179], v[212:215], v[20:23]
	v_mfma_f32_16x16x32_bf16 v[12:15], v[184:187], v[212:215], v[12:15]
	v_mfma_f32_16x16x32_bf16 v[4:7], v[176:179], v[220:223], v[4:7]
	v_mfma_f32_16x16x32_bf16 v[0:3], v[184:187], v[220:223], v[0:3]
	s_setprio 0
	s_barrier
; #define PG8_STAGE(bufoff, gbase, voff) do { _Pragma("unroll") for (int _i = 0; _i < 2; ++_i) \
;         __builtin_amdgcn_global_load_lds((const unsigned*)((const char*)(gbase) + (voff)[_i]), (PG8_LAS unsigned*)(lds + (bufoff) + ldsw + _i * 8192), 16, 0, 0); } while (0)
; #define PG8_LDA(dst, b, h) do { _Pragma("unroll") for (int m = 0; m < 4; ++m) _Pragma("unroll") for (int k = 0; k < 2; ++k) dst[m][k] = *(const PG8_LAS bf16x8*)(lds + PG8_SA(b, h) + aoff + m * 2048 + k * 1024); } while (0)
; #define PG8_LDB(dst, b, h) do { _Pragma("unroll") for (int n = 0; n < 2; ++n) _Pragma("unroll") for (int k = 0; k < 2; ++k) dst[n][k] = *(const PG8_LAS bf16x8*)(lds + PG8_SB(b, h) + boff + n * 2048 + k * 1024); } while (0)
; #define PG8_MMA(ai, bj, At, Bt) do { __builtin_amdgcn_s_setprio(1); _Pragma("unroll") for (int m = 0; m < 4; ++m) _Pragma("unroll") for (int n = 0; n < 2; ++n) _Pragma("unroll") for (int k = 0; k < 2; ++k) \
;         acc[ai][bj][m][n] = __builtin_amdgcn_mfma_f32_16x16x32_bf16(Bt[n][k], At[m][k], acc[ai][bj][m][n], 0, 0, 0); __builtin_amdgcn_s_setprio(0); } while (0)
; #define PG8_WAIT_V(n) asm volatile("s_waitcnt vmcnt(" #n ")" ::: "memory")
; #define PG8_WAIT_L(n) asm volatile("s_waitcnt lgkmcnt(" #n ")" ::: "memory")
; #define PG8_BAR __builtin_amdgcn_s_barrier()
; #define PG8_SCHED __builtin_amdgcn_sched_barrier(0)
; template <class Epi, class Sched, bool ALIGN_EPI = false, bool SP2 = false>
; __device__ __forceinline__ void gemm_phase(PG8_LAS unsigned char* lds, const Gemm g, const Sched& S, const Epi& E) {
;     ...
;             PG8_LDB(B0, 1, 0); PG8_LDB(B1, 1, 1); PG8_SCHED; PG8_LDA(At, 1, 0); PG8_STAGE(PG8_SA(0, 1), a2 + hstep, voffA);
;             PG8_WAIT_V(8); PG8_WAIT_L(0); PG8_BAR; PG8_MMA(0, 0, At, B0); PG8_MMA(0, 1, At, B1); PG8_BAR; PG8_SCHED;
;             PG8_LDA(At, 1, 1); PG8_STAGE(PG8_SB(1, 0), b3, voffB); PG8_STAGE(PG8_SB(1, 1), b3 + hstep, voffB); PG8_STAGE(PG8_SA(1, 0), a3, voffA);
;             PG8_WAIT_V(8); PG8_WAIT_L(0); PG8_BAR; PG8_MMA(1, 0, At, B0); PG8_MMA(1, 1, At, B1); PG8_BAR; PG8_SCHED;
	ds_read_b128 v[156:159], v196
	ds_read_b128 v[160:163], v196 offset:1024
	ds_read_b128 v[164:167], v196 offset:2048
	ds_read_b128 v[168:171], v196 offset:3072
	ds_read_b128 v[172:175], v197
	ds_read_b128 v[176:179], v197 offset:1024
	ds_read_b128 v[180:183], v197 offset:2048
	ds_read_b128 v[184:187], v197 offset:3072
	ds_read_b128 v[188:191], v153 offset:32768
	ds_read_b128 v[192:195], v153 offset:33792
	ds_read_b128 v[200:203], v153 offset:34816
	ds_read_b128 v[204:207], v153 offset:35840
	ds_read_b128 v[208:211], v153 offset:36864
	ds_read_b128 v[212:215], v153 offset:37888
	ds_read_b128 v[216:219], v153 offset:38912
	ds_read_b128 v[220:223], v153 offset:39936
	s_add_u32 s98, s72, 0x80000
	s_addc_u32 s99, s73, 0
	s_mov_b32 m0, s14
	s_add_u32 s100, s72, 0x80
	s_addc_u32 s101, s73, 0
	global_load_lds_dwordx4 v128, s[98:99]
	s_mov_b32 m0, s15
	s_nop 0
	global_load_lds_dwordx4 v132, s[98:99]
	s_add_i32 s83, 0, 0x18000
	s_add_i32 s84, 0, 0x1c000
	s_add_u32 s98, s70, 0x80
	s_addc_u32 s99, s71, 0
	s_add_i32 s72, s83, s1
	s_mov_b32 m0, s72
	s_waitcnt vmcnt(8)
	s_waitcnt lgkmcnt(0)
	s_setprio 1
	s_barrier
	v_mfma_f32_16x16x32_bf16 v[124:127], v[156:159], v[188:191], v[124:127]
	v_mfma_f32_16x16x32_bf16 v[120:123], v[164:167], v[188:191], v[120:123]
	v_mfma_f32_16x16x32_bf16 v[108:111], v[156:159], v[200:203], v[108:111]
	v_mfma_f32_16x16x32_bf16 v[104:107], v[164:167], v[200:203], v[104:107]
	v_mfma_f32_16x16x32_bf16 v[96:99], v[156:159], v[208:211], v[96:99]
	v_mfma_f32_16x16x32_bf16 v[88:91], v[164:167], v[208:211], v[88:91]
	v_mfma_f32_16x16x32_bf16 v[80:83], v[156:159], v[216:219], v[80:83]
	v_mfma_f32_16x16x32_bf16 v[72:75], v[164:167], v[216:219], v[72:75]
	v_mfma_f32_16x16x32_bf16 v[124:127], v[160:163], v[192:195], v[124:127]
	v_mfma_f32_16x16x32_bf16 v[120:123], v[168:171], v[192:195], v[120:123]
	v_mfma_f32_16x16x32_bf16 v[108:111], v[160:163], v[204:207], v[108:111]
	v_mfma_f32_16x16x32_bf16 v[104:107], v[168:171], v[204:207], v[104:107]
	v_mfma_f32_16x16x32_bf16 v[96:99], v[160:163], v[212:215], v[96:99]
	v_mfma_f32_16x16x32_bf16 v[88:91], v[168:171], v[212:215], v[88:91]
	v_mfma_f32_16x16x32_bf16 v[80:83], v[160:163], v[220:223], v[80:83]
	v_mfma_f32_16x16x32_bf16 v[72:75], v[168:171], v[220:223], v[72:75]
	v_mfma_f32_16x16x32_bf16 v[116:119], v[172:175], v[188:191], v[116:119]
	v_mfma_f32_16x16x32_bf16 v[112:115], v[180:183], v[188:191], v[112:115]
	v_mfma_f32_16x16x32_bf16 v[100:103], v[172:175], v[200:203], v[100:103]
	v_mfma_f32_16x16x32_bf16 v[92:95], v[180:183], v[200:203], v[92:95]
	v_mfma_f32_16x16x32_bf16 v[84:87], v[172:175], v[208:211], v[84:87]
	v_mfma_f32_16x16x32_bf16 v[76:79], v[180:183], v[208:211], v[76:79]
	v_mfma_f32_16x16x32_bf16 v[68:71], v[172:175], v[216:219], v[68:71]
	v_mfma_f32_16x16x32_bf16 v[64:67], v[180:183], v[216:219], v[64:67]
	v_mfma_f32_16x16x32_bf16 v[116:119], v[176:179], v[192:195], v[116:119]
	v_mfma_f32_16x16x32_bf16 v[112:115], v[184:187], v[192:195], v[112:115]
	v_mfma_f32_16x16x32_bf16 v[100:103], v[176:179], v[204:207], v[100:103]
	v_mfma_f32_16x16x32_bf16 v[92:95], v[184:187], v[204:207], v[92:95]
	v_mfma_f32_16x16x32_bf16 v[84:87], v[176:179], v[212:215], v[84:87]
	v_mfma_f32_16x16x32_bf16 v[76:79], v[184:187], v[212:215], v[76:79]
	v_mfma_f32_16x16x32_bf16 v[68:71], v[176:179], v[220:223], v[68:71]
	v_mfma_f32_16x16x32_bf16 v[64:67], v[184:187], v[220:223], v[64:67]
	s_setprio 0
	s_barrier
	ds_read_b128 v[188:191], v153 offset:49152
	ds_read_b128 v[192:195], v153 offset:50176
	ds_read_b128 v[200:203], v153 offset:51200
	ds_read_b128 v[204:207], v153 offset:52224
	ds_read_b128 v[208:211], v153 offset:53248
	ds_read_b128 v[212:215], v153 offset:54272
	ds_read_b128 v[216:219], v153 offset:55296
	ds_read_b128 v[220:223], v153 offset:56320
	global_load_lds_dwordx4 v130, s[98:99]
	s_add_i32 m0, s72, 0x2000
	s_add_u32 s70, s70, 0x80080
	s_addc_u32 s71, s71, 0
	s_add_i32 s72, s84, s1
	global_load_lds_dwordx4 v134, s[98:99]
	s_mov_b32 m0, s72
	s_nop 0
	global_load_lds_dwordx4 v130, s[70:71]
	s_add_i32 m0, s72, 0x2000
	s_nop 0
	global_load_lds_dwordx4 v134, s[70:71]
	s_mov_b32 m0, s67
	s_nop 0
	global_load_lds_dwordx4 v128, s[100:101]
	s_mov_b32 m0, s74
	s_nop 0
	global_load_lds_dwordx4 v132, s[100:101]
	s_add_i32 s82, s82, 2
	s_add_u32 s68, s68, 0x100
	s_addc_u32 s69, s69, 0
	s_add_u32 s80, s80, 0x100
	s_addc_u32 s81, s81, 0
	s_cmp_gt_u32 s82, 29
	s_waitcnt vmcnt(8)
	s_waitcnt lgkmcnt(0)
	s_setprio 1
	s_barrier
	v_mfma_f32_16x16x32_bf16 v[60:63], v[156:159], v[188:191], v[60:63]
	v_mfma_f32_16x16x32_bf16 v[56:59], v[164:167], v[188:191], v[56:59]
	v_mfma_f32_16x16x32_bf16 v[44:47], v[156:159], v[200:203], v[44:47]
	v_mfma_f32_16x16x32_bf16 v[40:43], v[164:167], v[200:203], v[40:43]
	v_mfma_f32_16x16x32_bf16 v[32:35], v[156:159], v[208:211], v[32:35]
	v_mfma_f32_16x16x32_bf16 v[24:27], v[164:167], v[208:211], v[24:27]
	v_mfma_f32_16x16x32_bf16 v[16:19], v[156:159], v[216:219], v[16:19]
	v_mfma_f32_16x16x32_bf16 v[8:11], v[164:167], v[216:219], v[8:11]
	v_mfma_f32_16x16x32_bf16 v[60:63], v[160:163], v[192:195], v[60:63]
	v_mfma_f32_16x16x32_bf16 v[56:59], v[168:171], v[192:195], v[56:59]
	v_mfma_f32_16x16x32_bf16 v[44:47], v[160:163], v[204:207], v[44:47]
	v_mfma_f32_16x16x32_bf16 v[40:43], v[168:171], v[204:207], v[40:43]
	v_mfma_f32_16x16x32_bf16 v[32:35], v[160:163], v[212:215], v[32:35]
	v_mfma_f32_16x16x32_bf16 v[24:27], v[168:171], v[212:215], v[24:27]
	v_mfma_f32_16x16x32_bf16 v[16:19], v[160:163], v[220:223], v[16:19]
	v_mfma_f32_16x16x32_bf16 v[8:11], v[168:171], v[220:223], v[8:11]
	v_mfma_f32_16x16x32_bf16 v[52:55], v[172:175], v[188:191], v[52:55]
	v_mfma_f32_16x16x32_bf16 v[48:51], v[180:183], v[188:191], v[48:51]
	v_mfma_f32_16x16x32_bf16 v[36:39], v[172:175], v[200:203], v[36:39]
	v_mfma_f32_16x16x32_bf16 v[28:31], v[180:183], v[200:203], v[28:31]
	v_mfma_f32_16x16x32_bf16 v[20:23], v[172:175], v[208:211], v[20:23]
	v_mfma_f32_16x16x32_bf16 v[12:15], v[180:183], v[208:211], v[12:15]
	v_mfma_f32_16x16x32_bf16 v[4:7], v[172:175], v[216:219], v[4:7]
	v_mfma_f32_16x16x32_bf16 v[0:3], v[180:183], v[216:219], v[0:3]
	v_mfma_f32_16x16x32_bf16 v[52:55], v[176:179], v[192:195], v[52:55]
	v_mfma_f32_16x16x32_bf16 v[48:51], v[184:187], v[192:195], v[48:51]
	v_mfma_f32_16x16x32_bf16 v[36:39], v[176:179], v[204:207], v[36:39]
	v_mfma_f32_16x16x32_bf16 v[28:31], v[184:187], v[204:207], v[28:31]
	v_mfma_f32_16x16x32_bf16 v[20:23], v[176:179], v[212:215], v[20:23]
	v_mfma_f32_16x16x32_bf16 v[12:15], v[184:187], v[212:215], v[12:15]
	v_mfma_f32_16x16x32_bf16 v[4:7], v[176:179], v[220:223], v[4:7]
	v_mfma_f32_16x16x32_bf16 v[0:3], v[184:187], v[220:223], v[0:3]
	s_setprio 0
	s_barrier
	s_cbranch_scc0 .LBB0_735
	s_and_b64 vcc, exec, s[38:39]
	s_cbranch_vccz .LBB0_738
	s_barrier

; #define PG8_STAGE(bufoff, gbase, voff) do { _Pragma("unroll") for (int _i = 0; _i < 2; ++_i) \
;         __builtin_amdgcn_global_load_lds((const unsigned*)((const char*)(gbase) + (voff)[_i]), (PG8_LAS unsigned*)(lds + (bufoff) + ldsw + _i * 8192), 16, 0, 0); } while (0)
; #define PG8_LDA(dst, b, h) do { _Pragma("unroll") for (int m = 0; m < 4; ++m) _Pragma("unroll") for (int k = 0; k < 2; ++k) dst[m][k] = *(const PG8_LAS bf16x8*)(lds + PG8_SA(b, h) + aoff + m * 2048 + k * 1024); } while (0)
; #define PG8_LDB(dst, b, h) do { _Pragma("unroll") for (int n = 0; n < 2; ++n) _Pragma("unroll") for (int k = 0; k < 2; ++k) dst[n][k] = *(const PG8_LAS bf16x8*)(lds + PG8_SB(b, h) + boff + n * 2048 + k * 1024); } while (0)
; #define PG8_MMA(ai, bj, At, Bt) do { __builtin_amdgcn_s_setprio(1); _Pragma("unroll") for (int m = 0; m < 4; ++m) _Pragma("unroll") for (int n = 0; n < 2; ++n) _Pragma("unroll") for (int k = 0; k < 2; ++k) \
;         acc[ai][bj][m][n] = __builtin_amdgcn_mfma_f32_16x16x32_bf16(Bt[n][k], At[m][k], acc[ai][bj][m][n], 0, 0, 0); __builtin_amdgcn_s_setprio(0); } while (0)
; #define PG8_WAIT_V(n) asm volatile("s_waitcnt vmcnt(" #n ")" ::: "memory")
; #define PG8_WAIT_L(n) asm volatile("s_waitcnt lgkmcnt(" #n ")" ::: "memory")
; template <class Epi, class Sched, bool ALIGN_EPI = false, bool SP2 = false>
; __device__ __forceinline__ void gemm_phase(PG8_LAS unsigned char* lds, const Gemm g, const Sched& S, const Epi& E) {
;     ...
;             const bool last = (t == nt - 2);
;             const char* a1 = cA + (size_t)(t + 1) * kstep;
;             const char* a2 = last ? nA : cA + (size_t)(t + 2) * kstep; const char* b2 = last ? nB : cB + (size_t)(t + 2) * kstep;
;             const char* a3 = a2 + kstep; const char* b3 = b2 + kstep;
;             if (last && has_next) S.a_ready(nxt);
;             if constexpr (SP2) {
;             PG8_LDB(B0, 0, 0); PG8_LDB(B1, 0, 1); PG8_SCHED; PG8_LDA(At, 0, 0); PG8_STAGE(PG8_SA(1, 1), a1 + hstep, voffA);
;             PG8_WAIT_V(8); PG8_WAIT_L(0); PG8_BAR; PG8_MMA(0, 0, At, B0); PG8_MMA(0, 1, At, B1); PG8_BAR; PG8_SCHED;
;             PG8_LDA(At, 0, 1); PG8_STAGE(PG8_SB(0, 0), b2, voffB); PG8_STAGE(PG8_SB(0, 1), b2 + hstep, voffB); PG8_STAGE(PG8_SA(0, 0), a2, voffA);
;             PG8_WAIT_V(8); PG8_WAIT_L(0); PG8_BAR; PG8_MMA(1, 0, At, B0); PG8_MMA(1, 1, At, B1); PG8_BAR; PG8_SCHED;
.LBB0_759:
	ds_read_b128 v[152:155], v149
	ds_read_b128 v[156:159], v149 offset:1024
	ds_read_b128 v[160:163], v149 offset:2048
	ds_read_b128 v[164:167], v149 offset:3072
	ds_read_b128 v[168:171], v150
	ds_read_b128 v[172:175], v150 offset:1024
	ds_read_b128 v[176:179], v150 offset:2048
	ds_read_b128 v[180:183], v150 offset:3072
	s_add_i32 m0, s6, 0xc000
	ds_read_b128 v[184:187], v151
	ds_read_b128 v[188:191], v151 offset:1024
	ds_read_b128 v[192:195], v151 offset:2048
	ds_read_b128 v[200:203], v151 offset:3072
	ds_read_b128 v[204:207], v151 offset:4096
	ds_read_b128 v[208:211], v151 offset:5120
	ds_read_b128 v[212:215], v151 offset:6144
	ds_read_b128 v[216:219], v151 offset:7168
	global_load_lds_dwordx4 v138, s[68:69]
	s_add_i32 m0, s6, 0xe000
	s_nop 0
	global_load_lds_dwordx4 v140, s[68:69]
	s_add_u32 s70, s68, 0xfff80080
	s_addc_u32 s71, s69, -1
	s_cmp_eq_u32 s83, 28
	s_cselect_b32 s73, s25, s71
	s_cselect_b32 s72, s61, s70
	s_cselect_b32 s71, s49, s82
	s_cselect_b32 s70, s80, s81
	s_add_i32 s84, s78, s5
	s_mov_b32 m0, s84
	s_waitcnt vmcnt(8)
	s_waitcnt lgkmcnt(0)
	s_setprio 1
	s_barrier
	v_mfma_f32_16x16x32_bf16 v[124:127], v[152:155], v[184:187], v[124:127]
	v_mfma_f32_16x16x32_bf16 v[120:123], v[160:163], v[184:187], v[120:123]
	v_mfma_f32_16x16x32_bf16 v[112:115], v[152:155], v[192:195], v[112:115]
	v_mfma_f32_16x16x32_bf16 v[104:107], v[160:163], v[192:195], v[104:107]
	v_mfma_f32_16x16x32_bf16 v[100:103], v[152:155], v[204:207], v[100:103]
	v_mfma_f32_16x16x32_bf16 v[92:95], v[160:163], v[204:207], v[92:95]
	v_mfma_f32_16x16x32_bf16 v[84:87], v[152:155], v[212:215], v[84:87]
	v_mfma_f32_16x16x32_bf16 v[76:79], v[160:163], v[212:215], v[76:79]
	v_mfma_f32_16x16x32_bf16 v[124:127], v[156:159], v[188:191], v[124:127]
	v_mfma_f32_16x16x32_bf16 v[120:123], v[164:167], v[188:191], v[120:123]
	v_mfma_f32_16x16x32_bf16 v[112:115], v[156:159], v[200:203], v[112:115]
	v_mfma_f32_16x16x32_bf16 v[104:107], v[164:167], v[200:203], v[104:107]
	v_mfma_f32_16x16x32_bf16 v[100:103], v[156:159], v[208:211], v[100:103]
	v_mfma_f32_16x16x32_bf16 v[92:95], v[164:167], v[208:211], v[92:95]
	v_mfma_f32_16x16x32_bf16 v[84:87], v[156:159], v[216:219], v[84:87]
	v_mfma_f32_16x16x32_bf16 v[76:79], v[164:167], v[216:219], v[76:79]
	v_mfma_f32_16x16x32_bf16 v[116:119], v[168:171], v[184:187], v[116:119]
	v_mfma_f32_16x16x32_bf16 v[108:111], v[176:179], v[184:187], v[108:111]
	v_mfma_f32_16x16x32_bf16 v[96:99], v[168:171], v[192:195], v[96:99]
	v_mfma_f32_16x16x32_bf16 v[88:91], v[176:179], v[192:195], v[88:91]
	v_mfma_f32_16x16x32_bf16 v[80:83], v[168:171], v[204:207], v[80:83]
	v_mfma_f32_16x16x32_bf16 v[72:75], v[176:179], v[204:207], v[72:75]
	v_mfma_f32_16x16x32_bf16 v[68:71], v[168:171], v[212:215], v[68:71]
	v_mfma_f32_16x16x32_bf16 v[64:67], v[176:179], v[212:215], v[64:67]
	v_mfma_f32_16x16x32_bf16 v[116:119], v[172:175], v[188:191], v[116:119]
	v_mfma_f32_16x16x32_bf16 v[108:111], v[180:183], v[188:191], v[108:111]
	v_mfma_f32_16x16x32_bf16 v[96:99], v[172:175], v[200:203], v[96:99]
	v_mfma_f32_16x16x32_bf16 v[88:91], v[180:183], v[200:203], v[88:91]
	v_mfma_f32_16x16x32_bf16 v[80:83], v[172:175], v[208:211], v[80:83]
	v_mfma_f32_16x16x32_bf16 v[72:75], v[180:183], v[208:211], v[72:75]
	v_mfma_f32_16x16x32_bf16 v[68:71], v[172:175], v[216:219], v[68:71]
	v_mfma_f32_16x16x32_bf16 v[64:67], v[180:183], v[216:219], v[64:67]
	s_setprio 0
	s_barrier
	ds_read_b128 v[184:187], v151 offset:16384
	ds_read_b128 v[188:191], v151 offset:17408
	ds_read_b128 v[192:195], v151 offset:18432
	ds_read_b128 v[200:203], v151 offset:19456
	ds_read_b128 v[204:207], v151 offset:20480
	ds_read_b128 v[208:211], v151 offset:21504
	ds_read_b128 v[212:215], v151 offset:22528
	ds_read_b128 v[216:219], v151 offset:23552
	global_load_lds_dwordx4 v130, s[70:71]
	s_add_i32 m0, s84, 0x2000
	s_add_u32 s84, s70, 0x80000
	s_addc_u32 s85, s71, 0
	s_add_i32 s86, s79, s5
	global_load_lds_dwordx4 v134, s[70:71]
	s_mov_b32 m0, s86
	s_nop 0
	global_load_lds_dwordx4 v130, s[84:85]
	s_add_i32 m0, s86, 0x2000
	s_nop 0
	global_load_lds_dwordx4 v134, s[84:85]
	s_mov_b32 m0, s6
	s_nop 0
	global_load_lds_dwordx4 v128, s[72:73]
	s_mov_b32 m0, s7
	s_nop 0
	global_load_lds_dwordx4 v132, s[72:73]
	s_waitcnt vmcnt(8)
	s_waitcnt lgkmcnt(0)
	s_setprio 1
	s_barrier
	v_mfma_f32_16x16x32_bf16 v[60:63], v[152:155], v[184:187], v[60:63]
	v_mfma_f32_16x16x32_bf16 v[56:59], v[160:163], v[184:187], v[56:59]
	v_mfma_f32_16x16x32_bf16 v[52:55], v[152:155], v[192:195], v[52:55]
	v_mfma_f32_16x16x32_bf16 v[44:47], v[160:163], v[192:195], v[44:47]
	v_mfma_f32_16x16x32_bf16 v[36:39], v[152:155], v[204:207], v[36:39]
	v_mfma_f32_16x16x32_bf16 v[28:31], v[160:163], v[204:207], v[28:31]
	v_mfma_f32_16x16x32_bf16 v[20:23], v[152:155], v[212:215], v[20:23]
	v_mfma_f32_16x16x32_bf16 v[12:15], v[160:163], v[212:215], v[12:15]
	v_mfma_f32_16x16x32_bf16 v[60:63], v[156:159], v[188:191], v[60:63]
	v_mfma_f32_16x16x32_bf16 v[56:59], v[164:167], v[188:191], v[56:59]
	v_mfma_f32_16x16x32_bf16 v[52:55], v[156:159], v[200:203], v[52:55]
	v_mfma_f32_16x16x32_bf16 v[44:47], v[164:167], v[200:203], v[44:47]
	v_mfma_f32_16x16x32_bf16 v[36:39], v[156:159], v[208:211], v[36:39]
	v_mfma_f32_16x16x32_bf16 v[28:31], v[164:167], v[208:211], v[28:31]
	v_mfma_f32_16x16x32_bf16 v[20:23], v[156:159], v[216:219], v[20:23]
	v_mfma_f32_16x16x32_bf16 v[12:15], v[164:167], v[216:219], v[12:15]
	v_mfma_f32_16x16x32_bf16 v[48:51], v[168:171], v[184:187], v[48:51]
	v_mfma_f32_16x16x32_bf16 v[40:43], v[176:179], v[184:187], v[40:43]
	v_mfma_f32_16x16x32_bf16 v[32:35], v[168:171], v[192:195], v[32:35]
	v_mfma_f32_16x16x32_bf16 v[24:27], v[176:179], v[192:195], v[24:27]
	v_mfma_f32_16x16x32_bf16 v[16:19], v[168:171], v[204:207], v[16:19]
	v_mfma_f32_16x16x32_bf16 v[8:11], v[176:179], v[204:207], v[8:11]
	v_mfma_f32_16x16x32_bf16 v[4:7], v[168:171], v[212:215], v[4:7]
	v_mfma_f32_16x16x32_bf16 v[0:3], v[176:179], v[212:215], v[0:3]
	v_mfma_f32_16x16x32_bf16 v[48:51], v[172:175], v[188:191], v[48:51]
	v_mfma_f32_16x16x32_bf16 v[40:43], v[180:183], v[188:191], v[40:43]
	v_mfma_f32_16x16x32_bf16 v[32:35], v[172:175], v[200:203], v[32:35]
	v_mfma_f32_16x16x32_bf16 v[24:27], v[180:183], v[200:203], v[24:27]
	v_mfma_f32_16x16x32_bf16 v[16:19], v[172:175], v[208:211], v[16:19]
	v_mfma_f32_16x16x32_bf16 v[8:11], v[180:183], v[208:211], v[8:11]
	v_mfma_f32_16x16x32_bf16 v[4:7], v[172:175], v[216:219], v[4:7]
	v_mfma_f32_16x16x32_bf16 v[0:3], v[180:183], v[216:219], v[0:3]
	s_setprio 0
	s_barrier
; #define PG8_STAGE(bufoff, gbase, voff) do { _Pragma("unroll") for (int _i = 0; _i < 2; ++_i) \
;         __builtin_amdgcn_global_load_lds((const unsigned*)((const char*)(gbase) + (voff)[_i]), (PG8_LAS unsigned*)(lds + (bufoff) + ldsw + _i * 8192), 16, 0, 0); } while (0)
; #define PG8_LDA(dst, b, h) do { _Pragma("unroll") for (int m = 0; m < 4; ++m) _Pragma("unroll") for (int k = 0; k < 2; ++k) dst[m][k] = *(const PG8_LAS bf16x8*)(lds + PG8_SA(b, h) + aoff + m * 2048 + k * 1024); } while (0)
; #define PG8_LDB(dst, b, h) do { _Pragma("unroll") for (int n = 0; n < 2; ++n) _Pragma("unroll") for (int k = 0; k < 2; ++k) dst[n][k] = *(const PG8_LAS bf16x8*)(lds + PG8_SB(b, h) + boff + n * 2048 + k * 1024); } while (0)
; #define PG8_MMA(ai, bj, At, Bt) do { __builtin_amdgcn_s_setprio(1); _Pragma("unroll") for (int m = 0; m < 4; ++m) _Pragma("unroll") for (int n = 0; n < 2; ++n) _Pragma("unroll") for (int k = 0; k < 2; ++k) \
;         acc[ai][bj][m][n] = __builtin_amdgcn_mfma_f32_16x16x32_bf16(Bt[n][k], At[m][k], acc[ai][bj][m][n], 0, 0, 0); __builtin_amdgcn_s_setprio(0); } while (0)
; #define PG8_WAIT_V(n) asm volatile("s_waitcnt vmcnt(" #n ")" ::: "memory")
; #define PG8_WAIT_L(n) asm volatile("s_waitcnt lgkmcnt(" #n ")" ::: "memory")
; #define PG8_BAR __builtin_amdgcn_s_barrier()
; #define PG8_SCHED __builtin_amdgcn_sched_barrier(0)
; template <class Epi, class Sched, bool ALIGN_EPI = false, bool SP2 = false>
; __device__ __forceinline__ void gemm_phase(PG8_LAS unsigned char* lds, const Gemm g, const Sched& S, const Epi& E) {
;     ...
;             PG8_LDB(B0, 1, 0); PG8_LDB(B1, 1, 1); PG8_SCHED; PG8_LDA(At, 1, 0); PG8_STAGE(PG8_SA(0, 1), a2 + hstep, voffA);
;             PG8_WAIT_V(8); PG8_WAIT_L(0); PG8_BAR; PG8_MMA(0, 0, At, B0); PG8_MMA(0, 1, At, B1); PG8_BAR; PG8_SCHED;
;             PG8_LDA(At, 1, 1); PG8_STAGE(PG8_SB(1, 0), b3, voffB); PG8_STAGE(PG8_SB(1, 1), b3 + hstep, voffB); PG8_STAGE(PG8_SA(1, 0), a3, voffA);
;             PG8_WAIT_V(8); PG8_WAIT_L(0); PG8_BAR; PG8_MMA(1, 0, At, B0); PG8_MMA(1, 1, At, B1); PG8_BAR; PG8_SCHED;
	ds_read_b128 v[152:155], v198
	ds_read_b128 v[156:159], v198 offset:1024
	ds_read_b128 v[160:163], v198 offset:2048
	ds_read_b128 v[164:167], v198 offset:3072
	ds_read_b128 v[168:171], v199
	ds_read_b128 v[172:175], v199 offset:1024
	ds_read_b128 v[176:179], v199 offset:2048
	ds_read_b128 v[180:183], v199 offset:3072
	ds_read_b128 v[184:187], v151 offset:32768
	ds_read_b128 v[188:191], v151 offset:33792
	ds_read_b128 v[192:195], v151 offset:34816
	ds_read_b128 v[200:203], v151 offset:35840
	ds_read_b128 v[204:207], v151 offset:36864
	ds_read_b128 v[208:211], v151 offset:37888
	ds_read_b128 v[212:215], v151 offset:38912
	ds_read_b128 v[216:219], v151 offset:39936
	s_add_u32 s98, s72, 0x80000
	s_addc_u32 s99, s73, 0
	s_mov_b32 m0, s14
	s_add_u32 s100, s72, 0x80
	s_addc_u32 s101, s73, 0
	global_load_lds_dwordx4 v128, s[98:99]
	s_mov_b32 m0, s15
	s_nop 0
	global_load_lds_dwordx4 v132, s[98:99]
	s_add_i32 s84, 0, 0x18000
	s_add_i32 s85, 0, 0x1c000
	s_add_u32 s98, s70, 0x80
	s_addc_u32 s99, s71, 0
	s_add_i32 s72, s84, s5
	s_mov_b32 m0, s72
	s_waitcnt vmcnt(8)
	s_waitcnt lgkmcnt(0)
	s_setprio 1
	s_barrier
	v_mfma_f32_16x16x32_bf16 v[124:127], v[152:155], v[184:187], v[124:127]
	v_mfma_f32_16x16x32_bf16 v[120:123], v[160:163], v[184:187], v[120:123]
	v_mfma_f32_16x16x32_bf16 v[112:115], v[152:155], v[192:195], v[112:115]
	v_mfma_f32_16x16x32_bf16 v[104:107], v[160:163], v[192:195], v[104:107]
	v_mfma_f32_16x16x32_bf16 v[100:103], v[152:155], v[204:207], v[100:103]
	v_mfma_f32_16x16x32_bf16 v[92:95], v[160:163], v[204:207], v[92:95]
	v_mfma_f32_16x16x32_bf16 v[84:87], v[152:155], v[212:215], v[84:87]
	v_mfma_f32_16x16x32_bf16 v[76:79], v[160:163], v[212:215], v[76:79]
	v_mfma_f32_16x16x32_bf16 v[124:127], v[156:159], v[188:191], v[124:127]
	v_mfma_f32_16x16x32_bf16 v[120:123], v[164:167], v[188:191], v[120:123]
	v_mfma_f32_16x16x32_bf16 v[112:115], v[156:159], v[200:203], v[112:115]
	v_mfma_f32_16x16x32_bf16 v[104:107], v[164:167], v[200:203], v[104:107]
	v_mfma_f32_16x16x32_bf16 v[100:103], v[156:159], v[208:211], v[100:103]
	v_mfma_f32_16x16x32_bf16 v[92:95], v[164:167], v[208:211], v[92:95]
	v_mfma_f32_16x16x32_bf16 v[84:87], v[156:159], v[216:219], v[84:87]
	v_mfma_f32_16x16x32_bf16 v[76:79], v[164:167], v[216:219], v[76:79]
	v_mfma_f32_16x16x32_bf16 v[116:119], v[168:171], v[184:187], v[116:119]
	v_mfma_f32_16x16x32_bf16 v[108:111], v[176:179], v[184:187], v[108:111]
	v_mfma_f32_16x16x32_bf16 v[96:99], v[168:171], v[192:195], v[96:99]
	v_mfma_f32_16x16x32_bf16 v[88:91], v[176:179], v[192:195], v[88:91]
	v_mfma_f32_16x16x32_bf16 v[80:83], v[168:171], v[204:207], v[80:83]
	v_mfma_f32_16x16x32_bf16 v[72:75], v[176:179], v[204:207], v[72:75]
	v_mfma_f32_16x16x32_bf16 v[68:71], v[168:171], v[212:215], v[68:71]
	v_mfma_f32_16x16x32_bf16 v[64:67], v[176:179], v[212:215], v[64:67]
	v_mfma_f32_16x16x32_bf16 v[116:119], v[172:175], v[188:191], v[116:119]
	v_mfma_f32_16x16x32_bf16 v[108:111], v[180:183], v[188:191], v[108:111]
	v_mfma_f32_16x16x32_bf16 v[96:99], v[172:175], v[200:203], v[96:99]
	v_mfma_f32_16x16x32_bf16 v[88:91], v[180:183], v[200:203], v[88:91]
	v_mfma_f32_16x16x32_bf16 v[80:83], v[172:175], v[208:211], v[80:83]
	v_mfma_f32_16x16x32_bf16 v[72:75], v[180:183], v[208:211], v[72:75]
	v_mfma_f32_16x16x32_bf16 v[68:71], v[172:175], v[216:219], v[68:71]
	v_mfma_f32_16x16x32_bf16 v[64:67], v[180:183], v[216:219], v[64:67]
	s_setprio 0
	s_barrier
	ds_read_b128 v[184:187], v151 offset:49152
	ds_read_b128 v[188:191], v151 offset:50176
	ds_read_b128 v[192:195], v151 offset:51200
	ds_read_b128 v[200:203], v151 offset:52224
	ds_read_b128 v[204:207], v151 offset:53248
	ds_read_b128 v[208:211], v151 offset:54272
	ds_read_b128 v[212:215], v151 offset:55296
	ds_read_b128 v[216:219], v151 offset:56320
	global_load_lds_dwordx4 v130, s[98:99]
	s_add_i32 m0, s72, 0x2000
	s_add_u32 s70, s70, 0x80080
	s_addc_u32 s71, s71, 0
	s_add_i32 s72, s85, s5
	global_load_lds_dwordx4 v134, s[98:99]
	s_mov_b32 m0, s72
	s_nop 0
	global_load_lds_dwordx4 v130, s[70:71]
	s_add_i32 m0, s72, 0x2000
	s_nop 0
	global_load_lds_dwordx4 v134, s[70:71]
	s_mov_b32 m0, s74
	s_nop 0
	global_load_lds_dwordx4 v128, s[100:101]
	s_mov_b32 m0, s75
	s_nop 0
	global_load_lds_dwordx4 v132, s[100:101]
	s_add_i32 s83, s83, 2
	s_add_u32 s68, s68, 0x100
	s_addc_u32 s69, s69, 0
	s_add_u32 s81, s81, 0x100
	s_addc_u32 s82, s82, 0
	s_cmp_gt_u32 s83, 29
	s_waitcnt vmcnt(8)
	s_waitcnt lgkmcnt(0)
	s_setprio 1
	s_barrier
	v_mfma_f32_16x16x32_bf16 v[60:63], v[152:155], v[184:187], v[60:63]
	v_mfma_f32_16x16x32_bf16 v[56:59], v[160:163], v[184:187], v[56:59]
	v_mfma_f32_16x16x32_bf16 v[52:55], v[152:155], v[192:195], v[52:55]
	v_mfma_f32_16x16x32_bf16 v[44:47], v[160:163], v[192:195], v[44:47]
	v_mfma_f32_16x16x32_bf16 v[36:39], v[152:155], v[204:207], v[36:39]
	v_mfma_f32_16x16x32_bf16 v[28:31], v[160:163], v[204:207], v[28:31]
	v_mfma_f32_16x16x32_bf16 v[20:23], v[152:155], v[212:215], v[20:23]
	v_mfma_f32_16x16x32_bf16 v[12:15], v[160:163], v[212:215], v[12:15]
	v_mfma_f32_16x16x32_bf16 v[60:63], v[156:159], v[188:191], v[60:63]
	v_mfma_f32_16x16x32_bf16 v[56:59], v[164:167], v[188:191], v[56:59]
	v_mfma_f32_16x16x32_bf16 v[52:55], v[156:159], v[200:203], v[52:55]
	v_mfma_f32_16x16x32_bf16 v[44:47], v[164:167], v[200:203], v[44:47]
	v_mfma_f32_16x16x32_bf16 v[36:39], v[156:159], v[208:211], v[36:39]
	v_mfma_f32_16x16x32_bf16 v[28:31], v[164:167], v[208:211], v[28:31]
	v_mfma_f32_16x16x32_bf16 v[20:23], v[156:159], v[216:219], v[20:23]
	v_mfma_f32_16x16x32_bf16 v[12:15], v[164:167], v[216:219], v[12:15]
	v_mfma_f32_16x16x32_bf16 v[48:51], v[168:171], v[184:187], v[48:51]
	v_mfma_f32_16x16x32_bf16 v[40:43], v[176:179], v[184:187], v[40:43]
	v_mfma_f32_16x16x32_bf16 v[32:35], v[168:171], v[192:195], v[32:35]
	v_mfma_f32_16x16x32_bf16 v[24:27], v[176:179], v[192:195], v[24:27]
	v_mfma_f32_16x16x32_bf16 v[16:19], v[168:171], v[204:207], v[16:19]
	v_mfma_f32_16x16x32_bf16 v[8:11], v[176:179], v[204:207], v[8:11]
	v_mfma_f32_16x16x32_bf16 v[4:7], v[168:171], v[212:215], v[4:7]
	v_mfma_f32_16x16x32_bf16 v[0:3], v[176:179], v[212:215], v[0:3]
	v_mfma_f32_16x16x32_bf16 v[48:51], v[172:175], v[188:191], v[48:51]
	v_mfma_f32_16x16x32_bf16 v[40:43], v[180:183], v[188:191], v[40:43]
	v_mfma_f32_16x16x32_bf16 v[32:35], v[172:175], v[200:203], v[32:35]
	v_mfma_f32_16x16x32_bf16 v[24:27], v[180:183], v[200:203], v[24:27]
	v_mfma_f32_16x16x32_bf16 v[16:19], v[172:175], v[208:211], v[16:19]
	v_mfma_f32_16x16x32_bf16 v[8:11], v[180:183], v[208:211], v[8:11]
	v_mfma_f32_16x16x32_bf16 v[4:7], v[172:175], v[216:219], v[4:7]
	v_mfma_f32_16x16x32_bf16 v[0:3], v[180:183], v[216:219], v[0:3]
	s_setprio 0
	s_barrier
	s_cbranch_scc0 .LBB0_759
	s_and_b64 vcc, exec, s[46:47]
	s_cbranch_vccz .LBB0_762
	s_barrier

; #define PG8_STAGE(bufoff, gbase, voff) do { _Pragma("unroll") for (int _i = 0; _i < 2; ++_i) \
;         __builtin_amdgcn_global_load_lds((const unsigned*)((const char*)(gbase) + (voff)[_i]), (PG8_LAS unsigned*)(lds + (bufoff) + ldsw + _i * 8192), 16, 0, 0); } while (0)
; #define PG8_LDA(dst, b, h) do { _Pragma("unroll") for (int m = 0; m < 4; ++m) _Pragma("unroll") for (int k = 0; k < 2; ++k) dst[m][k] = *(const PG8_LAS bf16x8*)(lds + PG8_SA(b, h) + aoff + m * 2048 + k * 1024); } while (0)
; #define PG8_LDB(dst, b, h) do { _Pragma("unroll") for (int n = 0; n < 2; ++n) _Pragma("unroll") for (int k = 0; k < 2; ++k) dst[n][k] = *(const PG8_LAS bf16x8*)(lds + PG8_SB(b, h) + boff + n * 2048 + k * 1024); } while (0)
; #define PG8_MMA(ai, bj, At, Bt) do { __builtin_amdgcn_s_setprio(1); _Pragma("unroll") for (int m = 0; m < 4; ++m) _Pragma("unroll") for (int n = 0; n < 2; ++n) _Pragma("unroll") for (int k = 0; k < 2; ++k) \
;         acc[ai][bj][m][n] = __builtin_amdgcn_mfma_f32_16x16x32_bf16(Bt[n][k], At[m][k], acc[ai][bj][m][n], 0, 0, 0); __builtin_amdgcn_s_setprio(0); } while (0)
; #define PG8_WAIT_V(n) asm volatile("s_waitcnt vmcnt(" #n ")" ::: "memory")
; #define PG8_WAIT_L(n) asm volatile("s_waitcnt lgkmcnt(" #n ")" ::: "memory")
; template <class Epi, class Sched, bool ALIGN_EPI = false, bool SP2 = false>
; __device__ __forceinline__ void gemm_phase(PG8_LAS unsigned char* lds, const Gemm g, const Sched& S, const Epi& E) {
;     ...
;             const bool last = (t == nt - 2);
;             const char* a1 = cA + (size_t)(t + 1) * kstep;
;             const char* a2 = last ? nA : cA + (size_t)(t + 2) * kstep; const char* b2 = last ? nB : cB + (size_t)(t + 2) * kstep;
;             const char* a3 = a2 + kstep; const char* b3 = b2 + kstep;
;             if (last && has_next) S.a_ready(nxt);
;             if constexpr (SP2) {
;             PG8_LDB(B0, 0, 0); PG8_LDB(B1, 0, 1); PG8_SCHED; PG8_LDA(At, 0, 0); PG8_STAGE(PG8_SA(1, 1), a1 + hstep, voffA);
;             PG8_WAIT_V(8); PG8_WAIT_L(0); PG8_BAR; PG8_MMA(0, 0, At, B0); PG8_MMA(0, 1, At, B1); PG8_BAR; PG8_SCHED;
;             PG8_LDA(At, 0, 1); PG8_STAGE(PG8_SB(0, 0), b2, voffB); PG8_STAGE(PG8_SB(0, 1), b2 + hstep, voffB); PG8_STAGE(PG8_SA(0, 0), a2, voffA);
;             PG8_WAIT_V(8); PG8_WAIT_L(0); PG8_BAR; PG8_MMA(1, 0, At, B0); PG8_MMA(1, 1, At, B1); PG8_BAR; PG8_SCHED;
.LBB0_1053:
	ds_read_b128 v[128:131], v202
	ds_read_b128 v[132:135], v202 offset:1024
	ds_read_b128 v[136:139], v202 offset:2048
	ds_read_b128 v[140:143], v202 offset:3072
	ds_read_b128 v[144:147], v203
	ds_read_b128 v[148:151], v203 offset:1024
	ds_read_b128 v[152:155], v203 offset:2048
	ds_read_b128 v[156:159], v203 offset:3072
	s_add_i32 m0, s3, 0xc000
	ds_read_b128 v[160:163], v204
	ds_read_b128 v[164:167], v204 offset:1024
	ds_read_b128 v[184:187], v204 offset:2048
	ds_read_b128 v[188:191], v204 offset:3072
	ds_read_b128 v[192:195], v204 offset:4096
	ds_read_b128 v[206:209], v204 offset:5120
	ds_read_b128 v[210:213], v204 offset:6144
	ds_read_b128 v[214:217], v204 offset:7168
	global_load_lds_dwordx4 v176, s[60:61]
	s_add_i32 m0, s3, 0xe000
	s_nop 0
	global_load_lds_dwordx4 v178, s[60:61]
	s_add_u32 s62, s60, 0xfff80080
	s_addc_u32 s63, s61, -1
	s_cmp_eq_u32 s72, 28
	s_cselect_b32 s65, s25, s63
	s_cselect_b32 s64, s43, s62
	s_cselect_b32 s63, s39, s71
	s_cselect_b32 s62, s69, s70
	s_add_i32 s73, s67, s1
	s_mov_b32 m0, s73
	s_waitcnt vmcnt(8)
	s_waitcnt lgkmcnt(0)
	s_setprio 1
	s_barrier
	v_mfma_f32_16x16x32_bf16 v[124:127], v[128:131], v[160:163], v[124:127]
	v_mfma_f32_16x16x32_bf16 v[120:123], v[136:139], v[160:163], v[120:123]
	v_mfma_f32_16x16x32_bf16 v[116:119], v[128:131], v[184:187], v[116:119]
	v_mfma_f32_16x16x32_bf16 v[108:111], v[136:139], v[184:187], v[108:111]
	v_mfma_f32_16x16x32_bf16 v[92:95], v[128:131], v[192:195], v[92:95]
	v_mfma_f32_16x16x32_bf16 v[88:91], v[136:139], v[192:195], v[88:91]
	v_mfma_f32_16x16x32_bf16 v[76:79], v[128:131], v[210:213], v[76:79]
	v_mfma_f32_16x16x32_bf16 v[72:75], v[136:139], v[210:213], v[72:75]
	v_mfma_f32_16x16x32_bf16 v[124:127], v[132:135], v[164:167], v[124:127]
	v_mfma_f32_16x16x32_bf16 v[120:123], v[140:143], v[164:167], v[120:123]
	v_mfma_f32_16x16x32_bf16 v[116:119], v[132:135], v[188:191], v[116:119]
	v_mfma_f32_16x16x32_bf16 v[108:111], v[140:143], v[188:191], v[108:111]
	v_mfma_f32_16x16x32_bf16 v[92:95], v[132:135], v[206:209], v[92:95]
	v_mfma_f32_16x16x32_bf16 v[88:91], v[140:143], v[206:209], v[88:91]
	v_mfma_f32_16x16x32_bf16 v[76:79], v[132:135], v[214:217], v[76:79]
	v_mfma_f32_16x16x32_bf16 v[72:75], v[140:143], v[214:217], v[72:75]
	v_mfma_f32_16x16x32_bf16 v[112:115], v[144:147], v[160:163], v[112:115]
	v_mfma_f32_16x16x32_bf16 v[104:107], v[152:155], v[160:163], v[104:107]
	v_mfma_f32_16x16x32_bf16 v[100:103], v[144:147], v[184:187], v[100:103]
	v_mfma_f32_16x16x32_bf16 v[96:99], v[152:155], v[184:187], v[96:99]
	v_mfma_f32_16x16x32_bf16 v[84:87], v[144:147], v[192:195], v[84:87]
	v_mfma_f32_16x16x32_bf16 v[80:83], v[152:155], v[192:195], v[80:83]
	v_mfma_f32_16x16x32_bf16 v[68:71], v[144:147], v[210:213], v[68:71]
	v_mfma_f32_16x16x32_bf16 v[64:67], v[152:155], v[210:213], v[64:67]
	v_mfma_f32_16x16x32_bf16 v[112:115], v[148:151], v[164:167], v[112:115]
	v_mfma_f32_16x16x32_bf16 v[104:107], v[156:159], v[164:167], v[104:107]
	v_mfma_f32_16x16x32_bf16 v[100:103], v[148:151], v[188:191], v[100:103]
	v_mfma_f32_16x16x32_bf16 v[96:99], v[156:159], v[188:191], v[96:99]
	v_mfma_f32_16x16x32_bf16 v[84:87], v[148:151], v[206:209], v[84:87]
	v_mfma_f32_16x16x32_bf16 v[80:83], v[156:159], v[206:209], v[80:83]
	v_mfma_f32_16x16x32_bf16 v[68:71], v[148:151], v[214:217], v[68:71]
	v_mfma_f32_16x16x32_bf16 v[64:67], v[156:159], v[214:217], v[64:67]
	s_setprio 0
	s_barrier
	ds_read_b128 v[160:163], v204 offset:16384
	ds_read_b128 v[164:167], v204 offset:17408
	ds_read_b128 v[184:187], v204 offset:18432
	ds_read_b128 v[188:191], v204 offset:19456
	ds_read_b128 v[192:195], v204 offset:20480
	ds_read_b128 v[206:209], v204 offset:21504
	ds_read_b128 v[210:213], v204 offset:22528
	ds_read_b128 v[214:217], v204 offset:23552
	global_load_lds_dwordx4 v170, s[62:63]
	s_add_i32 m0, s73, 0x2000
	s_add_u32 s74, s62, 0x80000
	s_addc_u32 s75, s63, 0
	s_add_i32 s73, s68, s1
	global_load_lds_dwordx4 v174, s[62:63]
	s_mov_b32 m0, s73
	s_nop 0
	global_load_lds_dwordx4 v170, s[74:75]
	s_add_i32 m0, s73, 0x2000
	s_nop 0
	global_load_lds_dwordx4 v174, s[74:75]
	s_mov_b32 m0, s3
	s_nop 0
	global_load_lds_dwordx4 v168, s[64:65]
	s_mov_b32 m0, s4
	s_nop 0
	global_load_lds_dwordx4 v172, s[64:65]
	s_waitcnt vmcnt(8)
	s_waitcnt lgkmcnt(0)
	s_setprio 1
	s_barrier
	v_mfma_f32_16x16x32_bf16 v[60:63], v[128:131], v[160:163], v[60:63]
	v_mfma_f32_16x16x32_bf16 v[56:59], v[136:139], v[160:163], v[56:59]
	v_mfma_f32_16x16x32_bf16 v[44:47], v[128:131], v[184:187], v[44:47]
	v_mfma_f32_16x16x32_bf16 v[40:43], v[136:139], v[184:187], v[40:43]
	v_mfma_f32_16x16x32_bf16 v[28:31], v[128:131], v[192:195], v[28:31]
	v_mfma_f32_16x16x32_bf16 v[24:27], v[136:139], v[192:195], v[24:27]
	v_mfma_f32_16x16x32_bf16 v[12:15], v[128:131], v[210:213], v[12:15]
	v_mfma_f32_16x16x32_bf16 v[8:11], v[136:139], v[210:213], v[8:11]
	v_mfma_f32_16x16x32_bf16 v[60:63], v[132:135], v[164:167], v[60:63]
	v_mfma_f32_16x16x32_bf16 v[56:59], v[140:143], v[164:167], v[56:59]
	v_mfma_f32_16x16x32_bf16 v[44:47], v[132:135], v[188:191], v[44:47]
	v_mfma_f32_16x16x32_bf16 v[40:43], v[140:143], v[188:191], v[40:43]
	v_mfma_f32_16x16x32_bf16 v[28:31], v[132:135], v[206:209], v[28:31]
	v_mfma_f32_16x16x32_bf16 v[24:27], v[140:143], v[206:209], v[24:27]
	v_mfma_f32_16x16x32_bf16 v[12:15], v[132:135], v[214:217], v[12:15]
	v_mfma_f32_16x16x32_bf16 v[8:11], v[140:143], v[214:217], v[8:11]
	v_mfma_f32_16x16x32_bf16 v[52:55], v[144:147], v[160:163], v[52:55]
	v_mfma_f32_16x16x32_bf16 v[48:51], v[152:155], v[160:163], v[48:51]
	v_mfma_f32_16x16x32_bf16 v[36:39], v[144:147], v[184:187], v[36:39]
	v_mfma_f32_16x16x32_bf16 v[32:35], v[152:155], v[184:187], v[32:35]
	v_mfma_f32_16x16x32_bf16 v[20:23], v[144:147], v[192:195], v[20:23]
	v_mfma_f32_16x16x32_bf16 v[16:19], v[152:155], v[192:195], v[16:19]
	v_mfma_f32_16x16x32_bf16 v[4:7], v[144:147], v[210:213], v[4:7]
	v_mfma_f32_16x16x32_bf16 v[0:3], v[152:155], v[210:213], v[0:3]
	v_mfma_f32_16x16x32_bf16 v[52:55], v[148:151], v[164:167], v[52:55]
	v_mfma_f32_16x16x32_bf16 v[48:51], v[156:159], v[164:167], v[48:51]
	v_mfma_f32_16x16x32_bf16 v[36:39], v[148:151], v[188:191], v[36:39]
	v_mfma_f32_16x16x32_bf16 v[32:35], v[156:159], v[188:191], v[32:35]
	v_mfma_f32_16x16x32_bf16 v[20:23], v[148:151], v[206:209], v[20:23]
	v_mfma_f32_16x16x32_bf16 v[16:19], v[156:159], v[206:209], v[16:19]
	v_mfma_f32_16x16x32_bf16 v[4:7], v[148:151], v[214:217], v[4:7]
	v_mfma_f32_16x16x32_bf16 v[0:3], v[156:159], v[214:217], v[0:3]
	s_setprio 0
	s_barrier
; #define PG8_STAGE(bufoff, gbase, voff) do { _Pragma("unroll") for (int _i = 0; _i < 2; ++_i) \
;         __builtin_amdgcn_global_load_lds((const unsigned*)((const char*)(gbase) + (voff)[_i]), (PG8_LAS unsigned*)(lds + (bufoff) + ldsw + _i * 8192), 16, 0, 0); } while (0)
; #define PG8_LDA(dst, b, h) do { _Pragma("unroll") for (int m = 0; m < 4; ++m) _Pragma("unroll") for (int k = 0; k < 2; ++k) dst[m][k] = *(const PG8_LAS bf16x8*)(lds + PG8_SA(b, h) + aoff + m * 2048 + k * 1024); } while (0)
; #define PG8_LDB(dst, b, h) do { _Pragma("unroll") for (int n = 0; n < 2; ++n) _Pragma("unroll") for (int k = 0; k < 2; ++k) dst[n][k] = *(const PG8_LAS bf16x8*)(lds + PG8_SB(b, h) + boff + n * 2048 + k * 1024); } while (0)
; #define PG8_MMA(ai, bj, At, Bt) do { __builtin_amdgcn_s_setprio(1); _Pragma("unroll") for (int m = 0; m < 4; ++m) _Pragma("unroll") for (int n = 0; n < 2; ++n) _Pragma("unroll") for (int k = 0; k < 2; ++k) \
;         acc[ai][bj][m][n] = __builtin_amdgcn_mfma_f32_16x16x32_bf16(Bt[n][k], At[m][k], acc[ai][bj][m][n], 0, 0, 0); __builtin_amdgcn_s_setprio(0); } while (0)
; #define PG8_WAIT_V(n) asm volatile("s_waitcnt vmcnt(" #n ")" ::: "memory")
; #define PG8_WAIT_L(n) asm volatile("s_waitcnt lgkmcnt(" #n ")" ::: "memory")
; #define PG8_BAR __builtin_amdgcn_s_barrier()
; #define PG8_SCHED __builtin_amdgcn_sched_barrier(0)
; template <class Epi, class Sched, bool ALIGN_EPI = false, bool SP2 = false>
; __device__ __forceinline__ void gemm_phase(PG8_LAS unsigned char* lds, const Gemm g, const Sched& S, const Epi& E) {
;     ...
;             PG8_LDB(B0, 1, 0); PG8_LDB(B1, 1, 1); PG8_SCHED; PG8_LDA(At, 1, 0); PG8_STAGE(PG8_SA(0, 1), a2 + hstep, voffA);
;             PG8_WAIT_V(8); PG8_WAIT_L(0); PG8_BAR; PG8_MMA(0, 0, At, B0); PG8_MMA(0, 1, At, B1); PG8_BAR; PG8_SCHED;
;             PG8_LDA(At, 1, 1); PG8_STAGE(PG8_SB(1, 0), b3, voffB); PG8_STAGE(PG8_SB(1, 1), b3 + hstep, voffB); PG8_STAGE(PG8_SA(1, 0), a3, voffA);
;             PG8_WAIT_V(8); PG8_WAIT_L(0); PG8_BAR; PG8_MMA(1, 0, At, B0); PG8_MMA(1, 1, At, B1); PG8_BAR; PG8_SCHED;
	ds_read_b128 v[128:131], v218
	ds_read_b128 v[132:135], v218 offset:1024
	ds_read_b128 v[136:139], v218 offset:2048
	ds_read_b128 v[140:143], v218 offset:3072
	ds_read_b128 v[144:147], v219
	ds_read_b128 v[148:151], v219 offset:1024
	ds_read_b128 v[152:155], v219 offset:2048
	ds_read_b128 v[156:159], v219 offset:3072
	ds_read_b128 v[160:163], v204 offset:32768
	ds_read_b128 v[164:167], v204 offset:33792
	ds_read_b128 v[184:187], v204 offset:34816
	ds_read_b128 v[188:191], v204 offset:35840
	ds_read_b128 v[192:195], v204 offset:36864
	ds_read_b128 v[206:209], v204 offset:37888
	ds_read_b128 v[210:213], v204 offset:38912
	ds_read_b128 v[214:217], v204 offset:39936
	s_add_u32 s98, s64, 0x80000
	s_addc_u32 s99, s65, 0
	s_mov_b32 m0, s5
	s_add_u32 s100, s64, 0x80
	s_addc_u32 s101, s65, 0
	global_load_lds_dwordx4 v168, s[98:99]
	s_mov_b32 m0, s14
	s_nop 0
	global_load_lds_dwordx4 v172, s[98:99]
	s_add_i32 s73, 0, 0x18000
	s_add_i32 s74, 0, 0x1c000
	s_add_u32 s98, s62, 0x80
	s_addc_u32 s99, s63, 0
	s_add_i32 s64, s73, s1
	s_mov_b32 m0, s64
	s_waitcnt vmcnt(8)
	s_waitcnt lgkmcnt(0)
	s_setprio 1
	s_barrier
	v_mfma_f32_16x16x32_bf16 v[124:127], v[128:131], v[160:163], v[124:127]
	v_mfma_f32_16x16x32_bf16 v[120:123], v[136:139], v[160:163], v[120:123]
	v_mfma_f32_16x16x32_bf16 v[116:119], v[128:131], v[184:187], v[116:119]
	v_mfma_f32_16x16x32_bf16 v[108:111], v[136:139], v[184:187], v[108:111]
	v_mfma_f32_16x16x32_bf16 v[92:95], v[128:131], v[192:195], v[92:95]
	v_mfma_f32_16x16x32_bf16 v[88:91], v[136:139], v[192:195], v[88:91]
	v_mfma_f32_16x16x32_bf16 v[76:79], v[128:131], v[210:213], v[76:79]
	v_mfma_f32_16x16x32_bf16 v[72:75], v[136:139], v[210:213], v[72:75]
	v_mfma_f32_16x16x32_bf16 v[124:127], v[132:135], v[164:167], v[124:127]
	v_mfma_f32_16x16x32_bf16 v[120:123], v[140:143], v[164:167], v[120:123]
	v_mfma_f32_16x16x32_bf16 v[116:119], v[132:135], v[188:191], v[116:119]
	v_mfma_f32_16x16x32_bf16 v[108:111], v[140:143], v[188:191], v[108:111]
	v_mfma_f32_16x16x32_bf16 v[92:95], v[132:135], v[206:209], v[92:95]
	v_mfma_f32_16x16x32_bf16 v[88:91], v[140:143], v[206:209], v[88:91]
	v_mfma_f32_16x16x32_bf16 v[76:79], v[132:135], v[214:217], v[76:79]
	v_mfma_f32_16x16x32_bf16 v[72:75], v[140:143], v[214:217], v[72:75]
	v_mfma_f32_16x16x32_bf16 v[112:115], v[144:147], v[160:163], v[112:115]
	v_mfma_f32_16x16x32_bf16 v[104:107], v[152:155], v[160:163], v[104:107]
	v_mfma_f32_16x16x32_bf16 v[100:103], v[144:147], v[184:187], v[100:103]
	v_mfma_f32_16x16x32_bf16 v[96:99], v[152:155], v[184:187], v[96:99]
	v_mfma_f32_16x16x32_bf16 v[84:87], v[144:147], v[192:195], v[84:87]
	v_mfma_f32_16x16x32_bf16 v[80:83], v[152:155], v[192:195], v[80:83]
	v_mfma_f32_16x16x32_bf16 v[68:71], v[144:147], v[210:213], v[68:71]
	v_mfma_f32_16x16x32_bf16 v[64:67], v[152:155], v[210:213], v[64:67]
	v_mfma_f32_16x16x32_bf16 v[112:115], v[148:151], v[164:167], v[112:115]
	v_mfma_f32_16x16x32_bf16 v[104:107], v[156:159], v[164:167], v[104:107]
	v_mfma_f32_16x16x32_bf16 v[100:103], v[148:151], v[188:191], v[100:103]
	v_mfma_f32_16x16x32_bf16 v[96:99], v[156:159], v[188:191], v[96:99]
	v_mfma_f32_16x16x32_bf16 v[84:87], v[148:151], v[206:209], v[84:87]
	v_mfma_f32_16x16x32_bf16 v[80:83], v[156:159], v[206:209], v[80:83]
	v_mfma_f32_16x16x32_bf16 v[68:71], v[148:151], v[214:217], v[68:71]
	v_mfma_f32_16x16x32_bf16 v[64:67], v[156:159], v[214:217], v[64:67]
	s_setprio 0
	s_barrier
	ds_read_b128 v[160:163], v204 offset:49152
	ds_read_b128 v[164:167], v204 offset:50176
	ds_read_b128 v[184:187], v204 offset:51200
	ds_read_b128 v[188:191], v204 offset:52224
	ds_read_b128 v[192:195], v204 offset:53248
	ds_read_b128 v[206:209], v204 offset:54272
	ds_read_b128 v[210:213], v204 offset:55296
	ds_read_b128 v[214:217], v204 offset:56320
	global_load_lds_dwordx4 v170, s[98:99]
	s_add_i32 m0, s64, 0x2000
	s_add_u32 s62, s62, 0x80080
	s_addc_u32 s63, s63, 0
	s_add_i32 s64, s74, s1
	global_load_lds_dwordx4 v174, s[98:99]
	s_mov_b32 m0, s64
	s_nop 0
	global_load_lds_dwordx4 v170, s[62:63]
	s_add_i32 m0, s64, 0x2000
	s_nop 0
	global_load_lds_dwordx4 v174, s[62:63]
	s_mov_b32 m0, s33
	s_nop 0
	global_load_lds_dwordx4 v168, s[100:101]
	s_mov_b32 m0, s35
	s_nop 0
	global_load_lds_dwordx4 v172, s[100:101]
	s_add_i32 s72, s72, 2
	s_add_u32 s60, s60, 0x100
	s_addc_u32 s61, s61, 0
	s_add_u32 s70, s70, 0x100
	s_addc_u32 s71, s71, 0
	s_cmp_gt_u32 s72, 29
	s_waitcnt vmcnt(8)
	s_waitcnt lgkmcnt(0)
	s_setprio 1
	s_barrier
	v_mfma_f32_16x16x32_bf16 v[60:63], v[128:131], v[160:163], v[60:63]
	v_mfma_f32_16x16x32_bf16 v[56:59], v[136:139], v[160:163], v[56:59]
	v_mfma_f32_16x16x32_bf16 v[44:47], v[128:131], v[184:187], v[44:47]
	v_mfma_f32_16x16x32_bf16 v[40:43], v[136:139], v[184:187], v[40:43]
	v_mfma_f32_16x16x32_bf16 v[28:31], v[128:131], v[192:195], v[28:31]
	v_mfma_f32_16x16x32_bf16 v[24:27], v[136:139], v[192:195], v[24:27]
	v_mfma_f32_16x16x32_bf16 v[12:15], v[128:131], v[210:213], v[12:15]
	v_mfma_f32_16x16x32_bf16 v[8:11], v[136:139], v[210:213], v[8:11]
	v_mfma_f32_16x16x32_bf16 v[60:63], v[132:135], v[164:167], v[60:63]
	v_mfma_f32_16x16x32_bf16 v[56:59], v[140:143], v[164:167], v[56:59]
	v_mfma_f32_16x16x32_bf16 v[44:47], v[132:135], v[188:191], v[44:47]
	v_mfma_f32_16x16x32_bf16 v[40:43], v[140:143], v[188:191], v[40:43]
	v_mfma_f32_16x16x32_bf16 v[28:31], v[132:135], v[206:209], v[28:31]
	v_mfma_f32_16x16x32_bf16 v[24:27], v[140:143], v[206:209], v[24:27]
	v_mfma_f32_16x16x32_bf16 v[12:15], v[132:135], v[214:217], v[12:15]
	v_mfma_f32_16x16x32_bf16 v[8:11], v[140:143], v[214:217], v[8:11]
	v_mfma_f32_16x16x32_bf16 v[52:55], v[144:147], v[160:163], v[52:55]
	v_mfma_f32_16x16x32_bf16 v[48:51], v[152:155], v[160:163], v[48:51]
	v_mfma_f32_16x16x32_bf16 v[36:39], v[144:147], v[184:187], v[36:39]
	v_mfma_f32_16x16x32_bf16 v[32:35], v[152:155], v[184:187], v[32:35]
	v_mfma_f32_16x16x32_bf16 v[20:23], v[144:147], v[192:195], v[20:23]
	v_mfma_f32_16x16x32_bf16 v[16:19], v[152:155], v[192:195], v[16:19]
	v_mfma_f32_16x16x32_bf16 v[4:7], v[144:147], v[210:213], v[4:7]
	v_mfma_f32_16x16x32_bf16 v[0:3], v[152:155], v[210:213], v[0:3]
	v_mfma_f32_16x16x32_bf16 v[52:55], v[148:151], v[164:167], v[52:55]
	v_mfma_f32_16x16x32_bf16 v[48:51], v[156:159], v[164:167], v[48:51]
	v_mfma_f32_16x16x32_bf16 v[36:39], v[148:151], v[188:191], v[36:39]
	v_mfma_f32_16x16x32_bf16 v[32:35], v[156:159], v[188:191], v[32:35]
	v_mfma_f32_16x16x32_bf16 v[20:23], v[148:151], v[206:209], v[20:23]
	v_mfma_f32_16x16x32_bf16 v[16:19], v[156:159], v[206:209], v[16:19]
	v_mfma_f32_16x16x32_bf16 v[4:7], v[148:151], v[214:217], v[4:7]
	v_mfma_f32_16x16x32_bf16 v[0:3], v[156:159], v[214:217], v[0:3]
	s_setprio 0
	s_barrier
	s_cbranch_scc0 .LBB0_1053
	s_and_b64 vcc, exec, s[16:17]
	s_cbranch_vccz .LBB0_1056
	s_barrier

; #define PG8_STAGE(bufoff, gbase, voff) do { _Pragma("unroll") for (int _i = 0; _i < 2; ++_i) \
;         __builtin_amdgcn_global_load_lds((const unsigned*)((const char*)(gbase) + (voff)[_i]), (PG8_LAS unsigned*)(lds + (bufoff) + ldsw + _i * 8192), 16, 0, 0); } while (0)
; #define PG8_LDA(dst, b, h) do { _Pragma("unroll") for (int m = 0; m < 4; ++m) _Pragma("unroll") for (int k = 0; k < 2; ++k) dst[m][k] = *(const PG8_LAS bf16x8*)(lds + PG8_SA(b, h) + aoff + m * 2048 + k * 1024); } while (0)
; #define PG8_LDB(dst, b, h) do { _Pragma("unroll") for (int n = 0; n < 2; ++n) _Pragma("unroll") for (int k = 0; k < 2; ++k) dst[n][k] = *(const PG8_LAS bf16x8*)(lds + PG8_SB(b, h) + boff + n * 2048 + k * 1024); } while (0)
; #define PG8_MMA(ai, bj, At, Bt) do { __builtin_amdgcn_s_setprio(1); _Pragma("unroll") for (int m = 0; m < 4; ++m) _Pragma("unroll") for (int n = 0; n < 2; ++n) _Pragma("unroll") for (int k = 0; k < 2; ++k) \
;         acc[ai][bj][m][n] = __builtin_amdgcn_mfma_f32_16x16x32_bf16(Bt[n][k], At[m][k], acc[ai][bj][m][n], 0, 0, 0); __builtin_amdgcn_s_setprio(0); } while (0)
; #define PG8_WAIT_V(n) asm volatile("s_waitcnt vmcnt(" #n ")" ::: "memory")
; #define PG8_WAIT_L(n) asm volatile("s_waitcnt lgkmcnt(" #n ")" ::: "memory")
; template <class Epi, class Sched, bool ALIGN_EPI = false, bool SP2 = false>
; __device__ __forceinline__ void gemm_phase(PG8_LAS unsigned char* lds, const Gemm g, const Sched& S, const Epi& E) {
;     ...
;             const bool last = (t == nt - 2);
;             const char* a1 = cA + (size_t)(t + 1) * kstep;
;             const char* a2 = last ? nA : cA + (size_t)(t + 2) * kstep; const char* b2 = last ? nB : cB + (size_t)(t + 2) * kstep;
;             const char* a3 = a2 + kstep; const char* b3 = b2 + kstep;
;             if (last && has_next) S.a_ready(nxt);
;             if constexpr (SP2) {
;             PG8_LDB(B0, 0, 0); PG8_LDB(B1, 0, 1); PG8_SCHED; PG8_LDA(At, 0, 0); PG8_STAGE(PG8_SA(1, 1), a1 + hstep, voffA);
;             PG8_WAIT_V(8); PG8_WAIT_L(0); PG8_BAR; PG8_MMA(0, 0, At, B0); PG8_MMA(0, 1, At, B1); PG8_BAR; PG8_SCHED;
;             PG8_LDA(At, 0, 1); PG8_STAGE(PG8_SB(0, 0), b2, voffB); PG8_STAGE(PG8_SB(0, 1), b2 + hstep, voffB); PG8_STAGE(PG8_SA(0, 0), a2, voffA);
;             PG8_WAIT_V(8); PG8_WAIT_L(0); PG8_BAR; PG8_MMA(1, 0, At, B0); PG8_MMA(1, 1, At, B1); PG8_BAR; PG8_SCHED;
.LBB0_1184:
	ds_read_b128 v[152:155], v149
	ds_read_b128 v[156:159], v149 offset:1024
	ds_read_b128 v[160:163], v149 offset:2048
	ds_read_b128 v[164:167], v149 offset:3072
	ds_read_b128 v[168:171], v150
	ds_read_b128 v[172:175], v150 offset:1024
	ds_read_b128 v[176:179], v150 offset:2048
	ds_read_b128 v[180:183], v150 offset:3072
	s_add_i32 m0, s3, 0xc000
	ds_read_b128 v[184:187], v151
	ds_read_b128 v[188:191], v151 offset:1024
	ds_read_b128 v[192:195], v151 offset:2048
	ds_read_b128 v[196:199], v151 offset:3072
	ds_read_b128 v[200:203], v151 offset:4096
	ds_read_b128 v[204:207], v151 offset:5120
	ds_read_b128 v[208:211], v151 offset:6144
	ds_read_b128 v[212:215], v151 offset:7168
	global_load_lds_dwordx4 v136, s[50:51]
	s_add_i32 m0, s3, 0xe000
	s_nop 0
	global_load_lds_dwordx4 v138, s[50:51]
	s_add_u32 s58, s50, 0xfff80080
	s_addc_u32 s59, s51, -1
	s_cmp_eq_u32 s74, 28
	s_cselect_b32 s61, s25, s59
	s_cselect_b32 s60, s41, s58
	s_cselect_b32 s59, s39, s73
	s_cselect_b32 s58, s71, s72
	s_add_i32 s75, s65, s1
	s_mov_b32 m0, s75
	s_waitcnt vmcnt(8)
	s_waitcnt lgkmcnt(0)
	s_setprio 1
	s_barrier
	v_mfma_f32_16x16x32_bf16 v[124:127], v[152:155], v[184:187], v[124:127]
	v_mfma_f32_16x16x32_bf16 v[120:123], v[160:163], v[184:187], v[120:123]
	v_mfma_f32_16x16x32_bf16 v[108:111], v[152:155], v[192:195], v[108:111]
	v_mfma_f32_16x16x32_bf16 v[104:107], v[160:163], v[192:195], v[104:107]
	v_mfma_f32_16x16x32_bf16 v[92:95], v[152:155], v[200:203], v[92:95]
	v_mfma_f32_16x16x32_bf16 v[88:91], v[160:163], v[200:203], v[88:91]
	v_mfma_f32_16x16x32_bf16 v[76:79], v[152:155], v[208:211], v[76:79]
	v_mfma_f32_16x16x32_bf16 v[72:75], v[160:163], v[208:211], v[72:75]
	v_mfma_f32_16x16x32_bf16 v[124:127], v[156:159], v[188:191], v[124:127]
	v_mfma_f32_16x16x32_bf16 v[120:123], v[164:167], v[188:191], v[120:123]
	v_mfma_f32_16x16x32_bf16 v[108:111], v[156:159], v[196:199], v[108:111]
	v_mfma_f32_16x16x32_bf16 v[104:107], v[164:167], v[196:199], v[104:107]
	v_mfma_f32_16x16x32_bf16 v[92:95], v[156:159], v[204:207], v[92:95]
	v_mfma_f32_16x16x32_bf16 v[88:91], v[164:167], v[204:207], v[88:91]
	v_mfma_f32_16x16x32_bf16 v[76:79], v[156:159], v[212:215], v[76:79]
	v_mfma_f32_16x16x32_bf16 v[72:75], v[164:167], v[212:215], v[72:75]
	v_mfma_f32_16x16x32_bf16 v[116:119], v[168:171], v[184:187], v[116:119]
	v_mfma_f32_16x16x32_bf16 v[112:115], v[176:179], v[184:187], v[112:115]
	v_mfma_f32_16x16x32_bf16 v[100:103], v[168:171], v[192:195], v[100:103]
	v_mfma_f32_16x16x32_bf16 v[96:99], v[176:179], v[192:195], v[96:99]
	v_mfma_f32_16x16x32_bf16 v[84:87], v[168:171], v[200:203], v[84:87]
	v_mfma_f32_16x16x32_bf16 v[80:83], v[176:179], v[200:203], v[80:83]
	v_mfma_f32_16x16x32_bf16 v[68:71], v[168:171], v[208:211], v[68:71]
	v_mfma_f32_16x16x32_bf16 v[64:67], v[176:179], v[208:211], v[64:67]
	v_mfma_f32_16x16x32_bf16 v[116:119], v[172:175], v[188:191], v[116:119]
	v_mfma_f32_16x16x32_bf16 v[112:115], v[180:183], v[188:191], v[112:115]
	v_mfma_f32_16x16x32_bf16 v[100:103], v[172:175], v[196:199], v[100:103]
	v_mfma_f32_16x16x32_bf16 v[96:99], v[180:183], v[196:199], v[96:99]
	v_mfma_f32_16x16x32_bf16 v[84:87], v[172:175], v[204:207], v[84:87]
	v_mfma_f32_16x16x32_bf16 v[80:83], v[180:183], v[204:207], v[80:83]
	v_mfma_f32_16x16x32_bf16 v[68:71], v[172:175], v[212:215], v[68:71]
	v_mfma_f32_16x16x32_bf16 v[64:67], v[180:183], v[212:215], v[64:67]
	s_setprio 0
	s_barrier
	ds_read_b128 v[184:187], v151 offset:16384
	ds_read_b128 v[188:191], v151 offset:17408
	ds_read_b128 v[192:195], v151 offset:18432
	ds_read_b128 v[196:199], v151 offset:19456
	ds_read_b128 v[200:203], v151 offset:20480
	ds_read_b128 v[204:207], v151 offset:21504
	ds_read_b128 v[208:211], v151 offset:22528
	ds_read_b128 v[212:215], v151 offset:23552
	global_load_lds_dwordx4 v130, s[58:59]
	s_add_i32 m0, s75, 0x2000
	s_add_u32 s76, s58, 0x80000
	s_addc_u32 s77, s59, 0
	s_add_i32 s75, s66, s1
	global_load_lds_dwordx4 v134, s[58:59]
	s_mov_b32 m0, s75
	s_nop 0
	global_load_lds_dwordx4 v130, s[76:77]
	s_add_i32 m0, s75, 0x2000
	s_nop 0
	global_load_lds_dwordx4 v134, s[76:77]
	s_mov_b32 m0, s3
	s_nop 0
	global_load_lds_dwordx4 v128, s[60:61]
	s_mov_b32 m0, s14
	s_nop 0
	global_load_lds_dwordx4 v132, s[60:61]
	s_waitcnt vmcnt(8)
	s_waitcnt lgkmcnt(0)
	s_setprio 1
	s_barrier
	v_mfma_f32_16x16x32_bf16 v[60:63], v[152:155], v[184:187], v[60:63]
	v_mfma_f32_16x16x32_bf16 v[56:59], v[160:163], v[184:187], v[56:59]
	v_mfma_f32_16x16x32_bf16 v[44:47], v[152:155], v[192:195], v[44:47]
	v_mfma_f32_16x16x32_bf16 v[40:43], v[160:163], v[192:195], v[40:43]
	v_mfma_f32_16x16x32_bf16 v[28:31], v[152:155], v[200:203], v[28:31]
	v_mfma_f32_16x16x32_bf16 v[24:27], v[160:163], v[200:203], v[24:27]
	v_mfma_f32_16x16x32_bf16 v[12:15], v[152:155], v[208:211], v[12:15]
	v_mfma_f32_16x16x32_bf16 v[8:11], v[160:163], v[208:211], v[8:11]
	v_mfma_f32_16x16x32_bf16 v[60:63], v[156:159], v[188:191], v[60:63]
	v_mfma_f32_16x16x32_bf16 v[56:59], v[164:167], v[188:191], v[56:59]
	v_mfma_f32_16x16x32_bf16 v[44:47], v[156:159], v[196:199], v[44:47]
	v_mfma_f32_16x16x32_bf16 v[40:43], v[164:167], v[196:199], v[40:43]
	v_mfma_f32_16x16x32_bf16 v[28:31], v[156:159], v[204:207], v[28:31]
	v_mfma_f32_16x16x32_bf16 v[24:27], v[164:167], v[204:207], v[24:27]
	v_mfma_f32_16x16x32_bf16 v[12:15], v[156:159], v[212:215], v[12:15]
	v_mfma_f32_16x16x32_bf16 v[8:11], v[164:167], v[212:215], v[8:11]
	v_mfma_f32_16x16x32_bf16 v[52:55], v[168:171], v[184:187], v[52:55]
	v_mfma_f32_16x16x32_bf16 v[48:51], v[176:179], v[184:187], v[48:51]
	v_mfma_f32_16x16x32_bf16 v[36:39], v[168:171], v[192:195], v[36:39]
	v_mfma_f32_16x16x32_bf16 v[32:35], v[176:179], v[192:195], v[32:35]
	v_mfma_f32_16x16x32_bf16 v[20:23], v[168:171], v[200:203], v[20:23]
	v_mfma_f32_16x16x32_bf16 v[16:19], v[176:179], v[200:203], v[16:19]
	v_mfma_f32_16x16x32_bf16 v[4:7], v[168:171], v[208:211], v[4:7]
	v_mfma_f32_16x16x32_bf16 v[0:3], v[176:179], v[208:211], v[0:3]
	v_mfma_f32_16x16x32_bf16 v[52:55], v[172:175], v[188:191], v[52:55]
	v_mfma_f32_16x16x32_bf16 v[48:51], v[180:183], v[188:191], v[48:51]
	v_mfma_f32_16x16x32_bf16 v[36:39], v[172:175], v[196:199], v[36:39]
	v_mfma_f32_16x16x32_bf16 v[32:35], v[180:183], v[196:199], v[32:35]
	v_mfma_f32_16x16x32_bf16 v[20:23], v[172:175], v[204:207], v[20:23]
	v_mfma_f32_16x16x32_bf16 v[16:19], v[180:183], v[204:207], v[16:19]
	v_mfma_f32_16x16x32_bf16 v[4:7], v[172:175], v[212:215], v[4:7]
	v_mfma_f32_16x16x32_bf16 v[0:3], v[180:183], v[212:215], v[0:3]
	s_setprio 0
	s_barrier
; #define PG8_STAGE(bufoff, gbase, voff) do { _Pragma("unroll") for (int _i = 0; _i < 2; ++_i) \
;         __builtin_amdgcn_global_load_lds((const unsigned*)((const char*)(gbase) + (voff)[_i]), (PG8_LAS unsigned*)(lds + (bufoff) + ldsw + _i * 8192), 16, 0, 0); } while (0)
; #define PG8_LDA(dst, b, h) do { _Pragma("unroll") for (int m = 0; m < 4; ++m) _Pragma("unroll") for (int k = 0; k < 2; ++k) dst[m][k] = *(const PG8_LAS bf16x8*)(lds + PG8_SA(b, h) + aoff + m * 2048 + k * 1024); } while (0)
; #define PG8_LDB(dst, b, h) do { _Pragma("unroll") for (int n = 0; n < 2; ++n) _Pragma("unroll") for (int k = 0; k < 2; ++k) dst[n][k] = *(const PG8_LAS bf16x8*)(lds + PG8_SB(b, h) + boff + n * 2048 + k * 1024); } while (0)
; #define PG8_MMA(ai, bj, At, Bt) do { __builtin_amdgcn_s_setprio(1); _Pragma("unroll") for (int m = 0; m < 4; ++m) _Pragma("unroll") for (int n = 0; n < 2; ++n) _Pragma("unroll") for (int k = 0; k < 2; ++k) \
;         acc[ai][bj][m][n] = __builtin_amdgcn_mfma_f32_16x16x32_bf16(Bt[n][k], At[m][k], acc[ai][bj][m][n], 0, 0, 0); __builtin_amdgcn_s_setprio(0); } while (0)
; #define PG8_WAIT_V(n) asm volatile("s_waitcnt vmcnt(" #n ")" ::: "memory")
; #define PG8_WAIT_L(n) asm volatile("s_waitcnt lgkmcnt(" #n ")" ::: "memory")
; #define PG8_BAR __builtin_amdgcn_s_barrier()
; #define PG8_SCHED __builtin_amdgcn_sched_barrier(0)
; template <class Epi, class Sched, bool ALIGN_EPI = false, bool SP2 = false>
; __device__ __forceinline__ void gemm_phase(PG8_LAS unsigned char* lds, const Gemm g, const Sched& S, const Epi& E) {
;     ...
;             PG8_LDB(B0, 1, 0); PG8_LDB(B1, 1, 1); PG8_SCHED; PG8_LDA(At, 1, 0); PG8_STAGE(PG8_SA(0, 1), a2 + hstep, voffA);
;             PG8_WAIT_V(8); PG8_WAIT_L(0); PG8_BAR; PG8_MMA(0, 0, At, B0); PG8_MMA(0, 1, At, B1); PG8_BAR; PG8_SCHED;
;             PG8_LDA(At, 1, 1); PG8_STAGE(PG8_SB(1, 0), b3, voffB); PG8_STAGE(PG8_SB(1, 1), b3 + hstep, voffB); PG8_STAGE(PG8_SA(1, 0), a3, voffA);
;             PG8_WAIT_V(8); PG8_WAIT_L(0); PG8_BAR; PG8_MMA(1, 0, At, B0); PG8_MMA(1, 1, At, B1); PG8_BAR; PG8_SCHED;
	ds_read_b128 v[152:155], v216
	ds_read_b128 v[156:159], v216 offset:1024
	ds_read_b128 v[160:163], v216 offset:2048
	ds_read_b128 v[164:167], v216 offset:3072
	ds_read_b128 v[168:171], v217
	ds_read_b128 v[172:175], v217 offset:1024
	ds_read_b128 v[176:179], v217 offset:2048
	ds_read_b128 v[180:183], v217 offset:3072
	ds_read_b128 v[184:187], v151 offset:32768
	ds_read_b128 v[188:191], v151 offset:33792
	ds_read_b128 v[192:195], v151 offset:34816
	ds_read_b128 v[196:199], v151 offset:35840
	ds_read_b128 v[200:203], v151 offset:36864
	ds_read_b128 v[204:207], v151 offset:37888
	ds_read_b128 v[208:211], v151 offset:38912
	ds_read_b128 v[212:215], v151 offset:39936
	s_add_u32 s98, s60, 0x80000
	s_addc_u32 s99, s61, 0
	s_mov_b32 m0, s15
	s_add_u32 s100, s60, 0x80
	s_addc_u32 s101, s61, 0
	global_load_lds_dwordx4 v128, s[98:99]
	s_mov_b32 m0, s33
	s_nop 0
	global_load_lds_dwordx4 v132, s[98:99]
	s_add_i32 s75, 0, 0x18000
	s_add_i32 s76, 0, 0x1c000
	s_add_u32 s98, s58, 0x80
	s_addc_u32 s99, s59, 0
	s_add_i32 s60, s75, s1
	s_mov_b32 m0, s60
	s_waitcnt vmcnt(8)
	s_waitcnt lgkmcnt(0)
	s_setprio 1
	s_barrier
	v_mfma_f32_16x16x32_bf16 v[124:127], v[152:155], v[184:187], v[124:127]
	v_mfma_f32_16x16x32_bf16 v[120:123], v[160:163], v[184:187], v[120:123]
	v_mfma_f32_16x16x32_bf16 v[108:111], v[152:155], v[192:195], v[108:111]
	v_mfma_f32_16x16x32_bf16 v[104:107], v[160:163], v[192:195], v[104:107]
	v_mfma_f32_16x16x32_bf16 v[92:95], v[152:155], v[200:203], v[92:95]
	v_mfma_f32_16x16x32_bf16 v[88:91], v[160:163], v[200:203], v[88:91]
	v_mfma_f32_16x16x32_bf16 v[76:79], v[152:155], v[208:211], v[76:79]
	v_mfma_f32_16x16x32_bf16 v[72:75], v[160:163], v[208:211], v[72:75]
	v_mfma_f32_16x16x32_bf16 v[124:127], v[156:159], v[188:191], v[124:127]
	v_mfma_f32_16x16x32_bf16 v[120:123], v[164:167], v[188:191], v[120:123]
	v_mfma_f32_16x16x32_bf16 v[108:111], v[156:159], v[196:199], v[108:111]
	v_mfma_f32_16x16x32_bf16 v[104:107], v[164:167], v[196:199], v[104:107]
	v_mfma_f32_16x16x32_bf16 v[92:95], v[156:159], v[204:207], v[92:95]
	v_mfma_f32_16x16x32_bf16 v[88:91], v[164:167], v[204:207], v[88:91]
	v_mfma_f32_16x16x32_bf16 v[76:79], v[156:159], v[212:215], v[76:79]
	v_mfma_f32_16x16x32_bf16 v[72:75], v[164:167], v[212:215], v[72:75]
	v_mfma_f32_16x16x32_bf16 v[116:119], v[168:171], v[184:187], v[116:119]
	v_mfma_f32_16x16x32_bf16 v[112:115], v[176:179], v[184:187], v[112:115]
	v_mfma_f32_16x16x32_bf16 v[100:103], v[168:171], v[192:195], v[100:103]
	v_mfma_f32_16x16x32_bf16 v[96:99], v[176:179], v[192:195], v[96:99]
	v_mfma_f32_16x16x32_bf16 v[84:87], v[168:171], v[200:203], v[84:87]
	v_mfma_f32_16x16x32_bf16 v[80:83], v[176:179], v[200:203], v[80:83]
	v_mfma_f32_16x16x32_bf16 v[68:71], v[168:171], v[208:211], v[68:71]
	v_mfma_f32_16x16x32_bf16 v[64:67], v[176:179], v[208:211], v[64:67]
	v_mfma_f32_16x16x32_bf16 v[116:119], v[172:175], v[188:191], v[116:119]
	v_mfma_f32_16x16x32_bf16 v[112:115], v[180:183], v[188:191], v[112:115]
	v_mfma_f32_16x16x32_bf16 v[100:103], v[172:175], v[196:199], v[100:103]
	v_mfma_f32_16x16x32_bf16 v[96:99], v[180:183], v[196:199], v[96:99]
	v_mfma_f32_16x16x32_bf16 v[84:87], v[172:175], v[204:207], v[84:87]
	v_mfma_f32_16x16x32_bf16 v[80:83], v[180:183], v[204:207], v[80:83]
	v_mfma_f32_16x16x32_bf16 v[68:71], v[172:175], v[212:215], v[68:71]
	v_mfma_f32_16x16x32_bf16 v[64:67], v[180:183], v[212:215], v[64:67]
	s_setprio 0
	s_barrier
	ds_read_b128 v[184:187], v151 offset:49152
	ds_read_b128 v[188:191], v151 offset:50176
	ds_read_b128 v[192:195], v151 offset:51200
	ds_read_b128 v[196:199], v151 offset:52224
	ds_read_b128 v[200:203], v151 offset:53248
	ds_read_b128 v[204:207], v151 offset:54272
	ds_read_b128 v[208:211], v151 offset:55296
	ds_read_b128 v[212:215], v151 offset:56320
	global_load_lds_dwordx4 v130, s[98:99]
	s_add_i32 m0, s60, 0x2000
	s_add_u32 s58, s58, 0x80080
	s_addc_u32 s59, s59, 0
	s_add_i32 s60, s76, s1
	global_load_lds_dwordx4 v134, s[98:99]
	s_mov_b32 m0, s60
	s_nop 0
	global_load_lds_dwordx4 v130, s[58:59]
	s_add_i32 m0, s60, 0x2000
	s_nop 0
	global_load_lds_dwordx4 v134, s[58:59]
	s_mov_b32 m0, s49
	s_nop 0
	global_load_lds_dwordx4 v128, s[100:101]
	s_mov_b32 m0, s62
	s_nop 0
	global_load_lds_dwordx4 v132, s[100:101]
	s_add_i32 s74, s74, 2
	s_add_u32 s50, s50, 0x100
	s_addc_u32 s51, s51, 0
	s_add_u32 s72, s72, 0x100
	s_addc_u32 s73, s73, 0
	s_cmp_gt_u32 s74, 29
	s_waitcnt vmcnt(8)
	s_waitcnt lgkmcnt(0)
	s_setprio 1
	s_barrier
	v_mfma_f32_16x16x32_bf16 v[60:63], v[152:155], v[184:187], v[60:63]
	v_mfma_f32_16x16x32_bf16 v[56:59], v[160:163], v[184:187], v[56:59]
	v_mfma_f32_16x16x32_bf16 v[44:47], v[152:155], v[192:195], v[44:47]
	v_mfma_f32_16x16x32_bf16 v[40:43], v[160:163], v[192:195], v[40:43]
	v_mfma_f32_16x16x32_bf16 v[28:31], v[152:155], v[200:203], v[28:31]
	v_mfma_f32_16x16x32_bf16 v[24:27], v[160:163], v[200:203], v[24:27]
	v_mfma_f32_16x16x32_bf16 v[12:15], v[152:155], v[208:211], v[12:15]
	v_mfma_f32_16x16x32_bf16 v[8:11], v[160:163], v[208:211], v[8:11]
	v_mfma_f32_16x16x32_bf16 v[60:63], v[156:159], v[188:191], v[60:63]
	v_mfma_f32_16x16x32_bf16 v[56:59], v[164:167], v[188:191], v[56:59]
	v_mfma_f32_16x16x32_bf16 v[44:47], v[156:159], v[196:199], v[44:47]
	v_mfma_f32_16x16x32_bf16 v[40:43], v[164:167], v[196:199], v[40:43]
	v_mfma_f32_16x16x32_bf16 v[28:31], v[156:159], v[204:207], v[28:31]
	v_mfma_f32_16x16x32_bf16 v[24:27], v[164:167], v[204:207], v[24:27]
	v_mfma_f32_16x16x32_bf16 v[12:15], v[156:159], v[212:215], v[12:15]
	v_mfma_f32_16x16x32_bf16 v[8:11], v[164:167], v[212:215], v[8:11]
	v_mfma_f32_16x16x32_bf16 v[52:55], v[168:171], v[184:187], v[52:55]
	v_mfma_f32_16x16x32_bf16 v[48:51], v[176:179], v[184:187], v[48:51]
	v_mfma_f32_16x16x32_bf16 v[36:39], v[168:171], v[192:195], v[36:39]
	v_mfma_f32_16x16x32_bf16 v[32:35], v[176:179], v[192:195], v[32:35]
	v_mfma_f32_16x16x32_bf16 v[20:23], v[168:171], v[200:203], v[20:23]
	v_mfma_f32_16x16x32_bf16 v[16:19], v[176:179], v[200:203], v[16:19]
	v_mfma_f32_16x16x32_bf16 v[4:7], v[168:171], v[208:211], v[4:7]
	v_mfma_f32_16x16x32_bf16 v[0:3], v[176:179], v[208:211], v[0:3]
	v_mfma_f32_16x16x32_bf16 v[52:55], v[172:175], v[188:191], v[52:55]
	v_mfma_f32_16x16x32_bf16 v[48:51], v[180:183], v[188:191], v[48:51]
	v_mfma_f32_16x16x32_bf16 v[36:39], v[172:175], v[196:199], v[36:39]
	v_mfma_f32_16x16x32_bf16 v[32:35], v[180:183], v[196:199], v[32:35]
	v_mfma_f32_16x16x32_bf16 v[20:23], v[172:175], v[204:207], v[20:23]
	v_mfma_f32_16x16x32_bf16 v[16:19], v[180:183], v[204:207], v[16:19]
	v_mfma_f32_16x16x32_bf16 v[4:7], v[172:175], v[212:215], v[4:7]
	v_mfma_f32_16x16x32_bf16 v[0:3], v[180:183], v[212:215], v[0:3]
	s_setprio 0
	s_barrier
	s_cbranch_scc0 .LBB0_1184
	s_and_b64 vcc, exec, s[12:13]
	s_cbranch_vccz .LBB0_1187
	s_barrier

; #define PG8_STAGE(bufoff, gbase, voff) do { _Pragma("unroll") for (int _i = 0; _i < 2; ++_i) \
;         __builtin_amdgcn_global_load_lds((const unsigned*)((const char*)(gbase) + (voff)[_i]), (PG8_LAS unsigned*)(lds + (bufoff) + ldsw + _i * 8192), 16, 0, 0); } while (0)
; #define PG8_LDA(dst, b, h) do { _Pragma("unroll") for (int m = 0; m < 4; ++m) _Pragma("unroll") for (int k = 0; k < 2; ++k) dst[m][k] = *(const PG8_LAS bf16x8*)(lds + PG8_SA(b, h) + aoff + m * 2048 + k * 1024); } while (0)
; #define PG8_LDB(dst, b, h) do { _Pragma("unroll") for (int n = 0; n < 2; ++n) _Pragma("unroll") for (int k = 0; k < 2; ++k) dst[n][k] = *(const PG8_LAS bf16x8*)(lds + PG8_SB(b, h) + boff + n * 2048 + k * 1024); } while (0)
; #define PG8_MMA(ai, bj, At, Bt) do { __builtin_amdgcn_s_setprio(1); _Pragma("unroll") for (int m = 0; m < 4; ++m) _Pragma("unroll") for (int n = 0; n < 2; ++n) _Pragma("unroll") for (int k = 0; k < 2; ++k) \
;         acc[ai][bj][m][n] = __builtin_amdgcn_mfma_f32_16x16x32_bf16(Bt[n][k], At[m][k], acc[ai][bj][m][n], 0, 0, 0); __builtin_amdgcn_s_setprio(0); } while (0)
; #define PG8_WAIT_V(n) asm volatile("s_waitcnt vmcnt(" #n ")" ::: "memory")
; #define PG8_WAIT_L(n) asm volatile("s_waitcnt lgkmcnt(" #n ")" ::: "memory")
; template <class Epi, class Sched, bool ALIGN_EPI = false, bool SP2 = false>
; __device__ __forceinline__ void gemm_phase(PG8_LAS unsigned char* lds, const Gemm g, const Sched& S, const Epi& E) {
;     ...
;             const bool last = (t == nt - 2);
;             const char* a1 = cA + (size_t)(t + 1) * kstep;
;             const char* a2 = last ? nA : cA + (size_t)(t + 2) * kstep; const char* b2 = last ? nB : cB + (size_t)(t + 2) * kstep;
;             const char* a3 = a2 + kstep; const char* b3 = b2 + kstep;
;             if (last && has_next) S.a_ready(nxt);
;             if constexpr (SP2) {
;             PG8_LDB(B0, 0, 0); PG8_LDB(B1, 0, 1); PG8_SCHED; PG8_LDA(At, 0, 0); PG8_STAGE(PG8_SA(1, 1), a1 + hstep, voffA);
;             PG8_WAIT_V(8); PG8_WAIT_L(0); PG8_BAR; PG8_MMA(0, 0, At, B0); PG8_MMA(0, 1, At, B1); PG8_BAR; PG8_SCHED;
;             PG8_LDA(At, 0, 1); PG8_STAGE(PG8_SB(0, 0), b2, voffB); PG8_STAGE(PG8_SB(0, 1), b2 + hstep, voffB); PG8_STAGE(PG8_SA(0, 0), a2, voffA);
;             PG8_WAIT_V(8); PG8_WAIT_L(0); PG8_BAR; PG8_MMA(1, 0, At, B0); PG8_MMA(1, 1, At, B1); PG8_BAR; PG8_SCHED;
.LBB0_1260:
	ds_read_b128 v[128:131], v202
	ds_read_b128 v[132:135], v202 offset:1024
	ds_read_b128 v[136:139], v202 offset:2048
	ds_read_b128 v[140:143], v202 offset:3072
	ds_read_b128 v[144:147], v203
	ds_read_b128 v[148:151], v203 offset:1024
	ds_read_b128 v[152:155], v203 offset:2048
	ds_read_b128 v[156:159], v203 offset:3072
	s_add_i32 m0, s14, 0xc000
	ds_read_b128 v[160:163], v204
	ds_read_b128 v[164:167], v204 offset:1024
	ds_read_b128 v[184:187], v204 offset:2048
	ds_read_b128 v[188:191], v204 offset:3072
	ds_read_b128 v[192:195], v204 offset:4096
	ds_read_b128 v[206:209], v204 offset:5120
	ds_read_b128 v[210:213], v204 offset:6144
	ds_read_b128 v[214:217], v204 offset:7168
	global_load_lds_dwordx4 v176, s[50:51]
	s_add_i32 m0, s14, 0xe000
	s_nop 0
	global_load_lds_dwordx4 v178, s[50:51]
	s_add_u32 s58, s50, 0xffe00080
	s_addc_u32 s59, s51, -1
	s_cmpk_eq_i32 s72, 0x7c
	s_cselect_b32 s61, s25, s59
	s_cselect_b32 s60, s41, s58
	s_cselect_b32 s59, s39, s71
	s_cselect_b32 s58, s69, s70
	s_add_i32 s73, s67, s1
	s_mov_b32 m0, s73
	s_waitcnt vmcnt(8)
	s_waitcnt lgkmcnt(0)
	s_setprio 1
	s_barrier
	v_mfma_f32_16x16x32_bf16 v[124:127], v[128:131], v[160:163], v[124:127]
	v_mfma_f32_16x16x32_bf16 v[120:123], v[136:139], v[160:163], v[120:123]
	v_mfma_f32_16x16x32_bf16 v[116:119], v[128:131], v[184:187], v[116:119]
	v_mfma_f32_16x16x32_bf16 v[108:111], v[136:139], v[184:187], v[108:111]
	v_mfma_f32_16x16x32_bf16 v[92:95], v[128:131], v[192:195], v[92:95]
	v_mfma_f32_16x16x32_bf16 v[88:91], v[136:139], v[192:195], v[88:91]
	v_mfma_f32_16x16x32_bf16 v[76:79], v[128:131], v[210:213], v[76:79]
	v_mfma_f32_16x16x32_bf16 v[72:75], v[136:139], v[210:213], v[72:75]
	v_mfma_f32_16x16x32_bf16 v[124:127], v[132:135], v[164:167], v[124:127]
	v_mfma_f32_16x16x32_bf16 v[120:123], v[140:143], v[164:167], v[120:123]
	v_mfma_f32_16x16x32_bf16 v[116:119], v[132:135], v[188:191], v[116:119]
	v_mfma_f32_16x16x32_bf16 v[108:111], v[140:143], v[188:191], v[108:111]
	v_mfma_f32_16x16x32_bf16 v[92:95], v[132:135], v[206:209], v[92:95]
	v_mfma_f32_16x16x32_bf16 v[88:91], v[140:143], v[206:209], v[88:91]
	v_mfma_f32_16x16x32_bf16 v[76:79], v[132:135], v[214:217], v[76:79]
	v_mfma_f32_16x16x32_bf16 v[72:75], v[140:143], v[214:217], v[72:75]
	v_mfma_f32_16x16x32_bf16 v[112:115], v[144:147], v[160:163], v[112:115]
	v_mfma_f32_16x16x32_bf16 v[104:107], v[152:155], v[160:163], v[104:107]
	v_mfma_f32_16x16x32_bf16 v[100:103], v[144:147], v[184:187], v[100:103]
	v_mfma_f32_16x16x32_bf16 v[96:99], v[152:155], v[184:187], v[96:99]
	v_mfma_f32_16x16x32_bf16 v[84:87], v[144:147], v[192:195], v[84:87]
	v_mfma_f32_16x16x32_bf16 v[80:83], v[152:155], v[192:195], v[80:83]
	v_mfma_f32_16x16x32_bf16 v[68:71], v[144:147], v[210:213], v[68:71]
	v_mfma_f32_16x16x32_bf16 v[64:67], v[152:155], v[210:213], v[64:67]
	v_mfma_f32_16x16x32_bf16 v[112:115], v[148:151], v[164:167], v[112:115]
	v_mfma_f32_16x16x32_bf16 v[104:107], v[156:159], v[164:167], v[104:107]
	v_mfma_f32_16x16x32_bf16 v[100:103], v[148:151], v[188:191], v[100:103]
	v_mfma_f32_16x16x32_bf16 v[96:99], v[156:159], v[188:191], v[96:99]
	v_mfma_f32_16x16x32_bf16 v[84:87], v[148:151], v[206:209], v[84:87]
	v_mfma_f32_16x16x32_bf16 v[80:83], v[156:159], v[206:209], v[80:83]
	v_mfma_f32_16x16x32_bf16 v[68:71], v[148:151], v[214:217], v[68:71]
	v_mfma_f32_16x16x32_bf16 v[64:67], v[156:159], v[214:217], v[64:67]
	s_setprio 0
	s_barrier
	ds_read_b128 v[160:163], v204 offset:16384
	ds_read_b128 v[164:167], v204 offset:17408
	ds_read_b128 v[184:187], v204 offset:18432
	ds_read_b128 v[188:191], v204 offset:19456
	ds_read_b128 v[192:195], v204 offset:20480
	ds_read_b128 v[206:209], v204 offset:21504
	ds_read_b128 v[210:213], v204 offset:22528
	ds_read_b128 v[214:217], v204 offset:23552
	global_load_lds_dwordx4 v170, s[58:59]
	s_add_i32 m0, s73, 0x2000
	s_add_u32 s74, s58, 0x200000
	s_addc_u32 s75, s59, 0
	s_add_i32 s73, s68, s1
	global_load_lds_dwordx4 v174, s[58:59]
	s_mov_b32 m0, s73
	s_nop 0
	global_load_lds_dwordx4 v170, s[74:75]
	s_add_i32 m0, s73, 0x2000
	s_nop 0
	global_load_lds_dwordx4 v174, s[74:75]
	s_mov_b32 m0, s14
	s_nop 0
	global_load_lds_dwordx4 v168, s[60:61]
	s_mov_b32 m0, s15
	s_nop 0
	global_load_lds_dwordx4 v172, s[60:61]
	s_waitcnt vmcnt(8)
	s_waitcnt lgkmcnt(0)
	s_setprio 1
	s_barrier
	v_mfma_f32_16x16x32_bf16 v[60:63], v[128:131], v[160:163], v[60:63]
	v_mfma_f32_16x16x32_bf16 v[56:59], v[136:139], v[160:163], v[56:59]
	v_mfma_f32_16x16x32_bf16 v[44:47], v[128:131], v[184:187], v[44:47]
	v_mfma_f32_16x16x32_bf16 v[40:43], v[136:139], v[184:187], v[40:43]
	v_mfma_f32_16x16x32_bf16 v[28:31], v[128:131], v[192:195], v[28:31]
	v_mfma_f32_16x16x32_bf16 v[24:27], v[136:139], v[192:195], v[24:27]
	v_mfma_f32_16x16x32_bf16 v[12:15], v[128:131], v[210:213], v[12:15]
	v_mfma_f32_16x16x32_bf16 v[8:11], v[136:139], v[210:213], v[8:11]
	v_mfma_f32_16x16x32_bf16 v[60:63], v[132:135], v[164:167], v[60:63]
	v_mfma_f32_16x16x32_bf16 v[56:59], v[140:143], v[164:167], v[56:59]
	v_mfma_f32_16x16x32_bf16 v[44:47], v[132:135], v[188:191], v[44:47]
	v_mfma_f32_16x16x32_bf16 v[40:43], v[140:143], v[188:191], v[40:43]
	v_mfma_f32_16x16x32_bf16 v[28:31], v[132:135], v[206:209], v[28:31]
	v_mfma_f32_16x16x32_bf16 v[24:27], v[140:143], v[206:209], v[24:27]
	v_mfma_f32_16x16x32_bf16 v[12:15], v[132:135], v[214:217], v[12:15]
	v_mfma_f32_16x16x32_bf16 v[8:11], v[140:143], v[214:217], v[8:11]
	v_mfma_f32_16x16x32_bf16 v[52:55], v[144:147], v[160:163], v[52:55]
	v_mfma_f32_16x16x32_bf16 v[48:51], v[152:155], v[160:163], v[48:51]
	v_mfma_f32_16x16x32_bf16 v[36:39], v[144:147], v[184:187], v[36:39]
	v_mfma_f32_16x16x32_bf16 v[32:35], v[152:155], v[184:187], v[32:35]
	v_mfma_f32_16x16x32_bf16 v[20:23], v[144:147], v[192:195], v[20:23]
	v_mfma_f32_16x16x32_bf16 v[16:19], v[152:155], v[192:195], v[16:19]
	v_mfma_f32_16x16x32_bf16 v[4:7], v[144:147], v[210:213], v[4:7]
	v_mfma_f32_16x16x32_bf16 v[0:3], v[152:155], v[210:213], v[0:3]
	v_mfma_f32_16x16x32_bf16 v[52:55], v[148:151], v[164:167], v[52:55]
	v_mfma_f32_16x16x32_bf16 v[48:51], v[156:159], v[164:167], v[48:51]
	v_mfma_f32_16x16x32_bf16 v[36:39], v[148:151], v[188:191], v[36:39]
	v_mfma_f32_16x16x32_bf16 v[32:35], v[156:159], v[188:191], v[32:35]
	v_mfma_f32_16x16x32_bf16 v[20:23], v[148:151], v[206:209], v[20:23]
	v_mfma_f32_16x16x32_bf16 v[16:19], v[156:159], v[206:209], v[16:19]
	v_mfma_f32_16x16x32_bf16 v[4:7], v[148:151], v[214:217], v[4:7]
	v_mfma_f32_16x16x32_bf16 v[0:3], v[156:159], v[214:217], v[0:3]
	s_setprio 0
	s_barrier
; #define PG8_STAGE(bufoff, gbase, voff) do { _Pragma("unroll") for (int _i = 0; _i < 2; ++_i) \
;         __builtin_amdgcn_global_load_lds((const unsigned*)((const char*)(gbase) + (voff)[_i]), (PG8_LAS unsigned*)(lds + (bufoff) + ldsw + _i * 8192), 16, 0, 0); } while (0)
; #define PG8_LDA(dst, b, h) do { _Pragma("unroll") for (int m = 0; m < 4; ++m) _Pragma("unroll") for (int k = 0; k < 2; ++k) dst[m][k] = *(const PG8_LAS bf16x8*)(lds + PG8_SA(b, h) + aoff + m * 2048 + k * 1024); } while (0)
; #define PG8_LDB(dst, b, h) do { _Pragma("unroll") for (int n = 0; n < 2; ++n) _Pragma("unroll") for (int k = 0; k < 2; ++k) dst[n][k] = *(const PG8_LAS bf16x8*)(lds + PG8_SB(b, h) + boff + n * 2048 + k * 1024); } while (0)
; #define PG8_MMA(ai, bj, At, Bt) do { __builtin_amdgcn_s_setprio(1); _Pragma("unroll") for (int m = 0; m < 4; ++m) _Pragma("unroll") for (int n = 0; n < 2; ++n) _Pragma("unroll") for (int k = 0; k < 2; ++k) \
;         acc[ai][bj][m][n] = __builtin_amdgcn_mfma_f32_16x16x32_bf16(Bt[n][k], At[m][k], acc[ai][bj][m][n], 0, 0, 0); __builtin_amdgcn_s_setprio(0); } while (0)
; #define PG8_WAIT_V(n) asm volatile("s_waitcnt vmcnt(" #n ")" ::: "memory")
; #define PG8_WAIT_L(n) asm volatile("s_waitcnt lgkmcnt(" #n ")" ::: "memory")
; #define PG8_BAR __builtin_amdgcn_s_barrier()
; #define PG8_SCHED __builtin_amdgcn_sched_barrier(0)
; template <class Epi, class Sched, bool ALIGN_EPI = false, bool SP2 = false>
; __device__ __forceinline__ void gemm_phase(PG8_LAS unsigned char* lds, const Gemm g, const Sched& S, const Epi& E) {
;     ...
;             PG8_LDB(B0, 1, 0); PG8_LDB(B1, 1, 1); PG8_SCHED; PG8_LDA(At, 1, 0); PG8_STAGE(PG8_SA(0, 1), a2 + hstep, voffA);
;             PG8_WAIT_V(8); PG8_WAIT_L(0); PG8_BAR; PG8_MMA(0, 0, At, B0); PG8_MMA(0, 1, At, B1); PG8_BAR; PG8_SCHED;
;             PG8_LDA(At, 1, 1); PG8_STAGE(PG8_SB(1, 0), b3, voffB); PG8_STAGE(PG8_SB(1, 1), b3 + hstep, voffB); PG8_STAGE(PG8_SA(1, 0), a3, voffA);
;             PG8_WAIT_V(8); PG8_WAIT_L(0); PG8_BAR; PG8_MMA(1, 0, At, B0); PG8_MMA(1, 1, At, B1); PG8_BAR; PG8_SCHED;
	ds_read_b128 v[128:131], v218
	ds_read_b128 v[132:135], v218 offset:1024
	ds_read_b128 v[136:139], v218 offset:2048
	ds_read_b128 v[140:143], v218 offset:3072
	ds_read_b128 v[144:147], v219
	ds_read_b128 v[148:151], v219 offset:1024
	ds_read_b128 v[152:155], v219 offset:2048
	ds_read_b128 v[156:159], v219 offset:3072
	ds_read_b128 v[160:163], v204 offset:32768
	ds_read_b128 v[164:167], v204 offset:33792
	ds_read_b128 v[184:187], v204 offset:34816
	ds_read_b128 v[188:191], v204 offset:35840
	ds_read_b128 v[192:195], v204 offset:36864
	ds_read_b128 v[206:209], v204 offset:37888
	ds_read_b128 v[210:213], v204 offset:38912
	ds_read_b128 v[214:217], v204 offset:39936
	s_add_u32 s98, s60, 0x200000
	s_addc_u32 s99, s61, 0
	s_mov_b32 m0, s33
	s_add_u32 s100, s60, 0x80
	s_addc_u32 s101, s61, 0
	global_load_lds_dwordx4 v168, s[98:99]
	s_mov_b32 m0, s49
	s_nop 0
	global_load_lds_dwordx4 v172, s[98:99]
	s_add_i32 s73, 0, 0x18000
	s_add_i32 s74, 0, 0x1c000
	s_add_u32 s98, s58, 0x80
	s_addc_u32 s99, s59, 0
	s_add_i32 s60, s73, s1
	s_mov_b32 m0, s60
	s_waitcnt vmcnt(8)
	s_waitcnt lgkmcnt(0)
	s_setprio 1
	s_barrier
	v_mfma_f32_16x16x32_bf16 v[124:127], v[128:131], v[160:163], v[124:127]
	v_mfma_f32_16x16x32_bf16 v[120:123], v[136:139], v[160:163], v[120:123]
	v_mfma_f32_16x16x32_bf16 v[116:119], v[128:131], v[184:187], v[116:119]
	v_mfma_f32_16x16x32_bf16 v[108:111], v[136:139], v[184:187], v[108:111]
	v_mfma_f32_16x16x32_bf16 v[92:95], v[128:131], v[192:195], v[92:95]
	v_mfma_f32_16x16x32_bf16 v[88:91], v[136:139], v[192:195], v[88:91]
	v_mfma_f32_16x16x32_bf16 v[76:79], v[128:131], v[210:213], v[76:79]
	v_mfma_f32_16x16x32_bf16 v[72:75], v[136:139], v[210:213], v[72:75]
	v_mfma_f32_16x16x32_bf16 v[124:127], v[132:135], v[164:167], v[124:127]
	v_mfma_f32_16x16x32_bf16 v[120:123], v[140:143], v[164:167], v[120:123]
	v_mfma_f32_16x16x32_bf16 v[116:119], v[132:135], v[188:191], v[116:119]
	v_mfma_f32_16x16x32_bf16 v[108:111], v[140:143], v[188:191], v[108:111]
	v_mfma_f32_16x16x32_bf16 v[92:95], v[132:135], v[206:209], v[92:95]
	v_mfma_f32_16x16x32_bf16 v[88:91], v[140:143], v[206:209], v[88:91]
	v_mfma_f32_16x16x32_bf16 v[76:79], v[132:135], v[214:217], v[76:79]
	v_mfma_f32_16x16x32_bf16 v[72:75], v[140:143], v[214:217], v[72:75]
	v_mfma_f32_16x16x32_bf16 v[112:115], v[144:147], v[160:163], v[112:115]
	v_mfma_f32_16x16x32_bf16 v[104:107], v[152:155], v[160:163], v[104:107]
	v_mfma_f32_16x16x32_bf16 v[100:103], v[144:147], v[184:187], v[100:103]
	v_mfma_f32_16x16x32_bf16 v[96:99], v[152:155], v[184:187], v[96:99]
	v_mfma_f32_16x16x32_bf16 v[84:87], v[144:147], v[192:195], v[84:87]
	v_mfma_f32_16x16x32_bf16 v[80:83], v[152:155], v[192:195], v[80:83]
	v_mfma_f32_16x16x32_bf16 v[68:71], v[144:147], v[210:213], v[68:71]
	v_mfma_f32_16x16x32_bf16 v[64:67], v[152:155], v[210:213], v[64:67]
	v_mfma_f32_16x16x32_bf16 v[112:115], v[148:151], v[164:167], v[112:115]
	v_mfma_f32_16x16x32_bf16 v[104:107], v[156:159], v[164:167], v[104:107]
	v_mfma_f32_16x16x32_bf16 v[100:103], v[148:151], v[188:191], v[100:103]
	v_mfma_f32_16x16x32_bf16 v[96:99], v[156:159], v[188:191], v[96:99]
	v_mfma_f32_16x16x32_bf16 v[84:87], v[148:151], v[206:209], v[84:87]
	v_mfma_f32_16x16x32_bf16 v[80:83], v[156:159], v[206:209], v[80:83]
	v_mfma_f32_16x16x32_bf16 v[68:71], v[148:151], v[214:217], v[68:71]
	v_mfma_f32_16x16x32_bf16 v[64:67], v[156:159], v[214:217], v[64:67]
	s_setprio 0
	s_barrier
	ds_read_b128 v[160:163], v204 offset:49152
	ds_read_b128 v[164:167], v204 offset:50176
	ds_read_b128 v[184:187], v204 offset:51200
	ds_read_b128 v[188:191], v204 offset:52224
	ds_read_b128 v[192:195], v204 offset:53248
	ds_read_b128 v[206:209], v204 offset:54272
	ds_read_b128 v[210:213], v204 offset:55296
	ds_read_b128 v[214:217], v204 offset:56320
	global_load_lds_dwordx4 v170, s[98:99]
	s_add_i32 m0, s60, 0x2000
	s_add_u32 s58, s58, 0x200080
	s_addc_u32 s59, s59, 0
	s_add_i32 s60, s74, s1
	global_load_lds_dwordx4 v174, s[98:99]
	s_mov_b32 m0, s60
	s_nop 0
	global_load_lds_dwordx4 v170, s[58:59]
	s_add_i32 m0, s60, 0x2000
	s_nop 0
	global_load_lds_dwordx4 v174, s[58:59]
	s_mov_b32 m0, s63
	s_nop 0
	global_load_lds_dwordx4 v168, s[100:101]
	s_mov_b32 m0, s64
	s_nop 0
	global_load_lds_dwordx4 v172, s[100:101]
	s_add_i32 s72, s72, 2
	s_add_u32 s50, s50, 0x100
	s_addc_u32 s51, s51, 0
	s_add_u32 s70, s70, 0x100
	s_addc_u32 s71, s71, 0
	s_cmpk_gt_u32 s72, 0x7d
	s_waitcnt vmcnt(8)
	s_waitcnt lgkmcnt(0)
	s_setprio 1
	s_barrier
	v_mfma_f32_16x16x32_bf16 v[60:63], v[128:131], v[160:163], v[60:63]
	v_mfma_f32_16x16x32_bf16 v[56:59], v[136:139], v[160:163], v[56:59]
	v_mfma_f32_16x16x32_bf16 v[44:47], v[128:131], v[184:187], v[44:47]
	v_mfma_f32_16x16x32_bf16 v[40:43], v[136:139], v[184:187], v[40:43]
	v_mfma_f32_16x16x32_bf16 v[28:31], v[128:131], v[192:195], v[28:31]
	v_mfma_f32_16x16x32_bf16 v[24:27], v[136:139], v[192:195], v[24:27]
	v_mfma_f32_16x16x32_bf16 v[12:15], v[128:131], v[210:213], v[12:15]
	v_mfma_f32_16x16x32_bf16 v[8:11], v[136:139], v[210:213], v[8:11]
	v_mfma_f32_16x16x32_bf16 v[60:63], v[132:135], v[164:167], v[60:63]
	v_mfma_f32_16x16x32_bf16 v[56:59], v[140:143], v[164:167], v[56:59]
	v_mfma_f32_16x16x32_bf16 v[44:47], v[132:135], v[188:191], v[44:47]
	v_mfma_f32_16x16x32_bf16 v[40:43], v[140:143], v[188:191], v[40:43]
	v_mfma_f32_16x16x32_bf16 v[28:31], v[132:135], v[206:209], v[28:31]
	v_mfma_f32_16x16x32_bf16 v[24:27], v[140:143], v[206:209], v[24:27]
	v_mfma_f32_16x16x32_bf16 v[12:15], v[132:135], v[214:217], v[12:15]
	v_mfma_f32_16x16x32_bf16 v[8:11], v[140:143], v[214:217], v[8:11]
	v_mfma_f32_16x16x32_bf16 v[52:55], v[144:147], v[160:163], v[52:55]
	v_mfma_f32_16x16x32_bf16 v[48:51], v[152:155], v[160:163], v[48:51]
	v_mfma_f32_16x16x32_bf16 v[36:39], v[144:147], v[184:187], v[36:39]
	v_mfma_f32_16x16x32_bf16 v[32:35], v[152:155], v[184:187], v[32:35]
	v_mfma_f32_16x16x32_bf16 v[20:23], v[144:147], v[192:195], v[20:23]
	v_mfma_f32_16x16x32_bf16 v[16:19], v[152:155], v[192:195], v[16:19]
	v_mfma_f32_16x16x32_bf16 v[4:7], v[144:147], v[210:213], v[4:7]
	v_mfma_f32_16x16x32_bf16 v[0:3], v[152:155], v[210:213], v[0:3]
	v_mfma_f32_16x16x32_bf16 v[52:55], v[148:151], v[164:167], v[52:55]
	v_mfma_f32_16x16x32_bf16 v[48:51], v[156:159], v[164:167], v[48:51]
	v_mfma_f32_16x16x32_bf16 v[36:39], v[148:151], v[188:191], v[36:39]
	v_mfma_f32_16x16x32_bf16 v[32:35], v[156:159], v[188:191], v[32:35]
	v_mfma_f32_16x16x32_bf16 v[20:23], v[148:151], v[206:209], v[20:23]
	v_mfma_f32_16x16x32_bf16 v[16:19], v[156:159], v[206:209], v[16:19]
	v_mfma_f32_16x16x32_bf16 v[4:7], v[148:151], v[214:217], v[4:7]
	v_mfma_f32_16x16x32_bf16 v[0:3], v[156:159], v[214:217], v[0:3]
	s_setprio 0
	s_barrier
	s_cbranch_scc0 .LBB0_1260
	s_and_b64 vcc, exec, s[12:13]
	s_cbranch_vccz .LBB0_1263
	s_barrier

; #define PG8_STAGE(bufoff, gbase, voff) do { _Pragma("unroll") for (int _i = 0; _i < 2; ++_i) \
;         __builtin_amdgcn_global_load_lds((const unsigned*)((const char*)(gbase) + (voff)[_i]), (PG8_LAS unsigned*)(lds + (bufoff) + ldsw + _i * 8192), 16, 0, 0); } while (0)
; #define PG8_LDA(dst, b, h) do { _Pragma("unroll") for (int m = 0; m < 4; ++m) _Pragma("unroll") for (int k = 0; k < 2; ++k) dst[m][k] = *(const PG8_LAS bf16x8*)(lds + PG8_SA(b, h) + aoff + m * 2048 + k * 1024); } while (0)
; #define PG8_LDB(dst, b, h) do { _Pragma("unroll") for (int n = 0; n < 2; ++n) _Pragma("unroll") for (int k = 0; k < 2; ++k) dst[n][k] = *(const PG8_LAS bf16x8*)(lds + PG8_SB(b, h) + boff + n * 2048 + k * 1024); } while (0)
; #define PG8_MMA(ai, bj, At, Bt) do { __builtin_amdgcn_s_setprio(1); _Pragma("unroll") for (int m = 0; m < 4; ++m) _Pragma("unroll") for (int n = 0; n < 2; ++n) _Pragma("unroll") for (int k = 0; k < 2; ++k) \
;         acc[ai][bj][m][n] = __builtin_amdgcn_mfma_f32_16x16x32_bf16(Bt[n][k], At[m][k], acc[ai][bj][m][n], 0, 0, 0); __builtin_amdgcn_s_setprio(0); } while (0)
; #define PG8_WAIT_V(n) asm volatile("s_waitcnt vmcnt(" #n ")" ::: "memory")
; #define PG8_WAIT_L(n) asm volatile("s_waitcnt lgkmcnt(" #n ")" ::: "memory")
; template <class Epi, class Sched, bool ALIGN_EPI = false, bool SP2 = false>
; __device__ __forceinline__ void gemm_phase(PG8_LAS unsigned char* lds, const Gemm g, const Sched& S, const Epi& E) {
;     ...
;             const bool last = (t == nt - 2);
;             const char* a1 = cA + (size_t)(t + 1) * kstep;
;             const char* a2 = last ? nA : cA + (size_t)(t + 2) * kstep; const char* b2 = last ? nB : cB + (size_t)(t + 2) * kstep;
;             const char* a3 = a2 + kstep; const char* b3 = b2 + kstep;
;             if (last && has_next) S.a_ready(nxt);
;             if constexpr (SP2) {
;             PG8_LDB(B0, 0, 0); PG8_LDB(B1, 0, 1); PG8_SCHED; PG8_LDA(At, 0, 0); PG8_STAGE(PG8_SA(1, 1), a1 + hstep, voffA);
;             PG8_WAIT_V(8); PG8_WAIT_L(0); PG8_BAR; PG8_MMA(0, 0, At, B0); PG8_MMA(0, 1, At, B1); PG8_BAR; PG8_SCHED;
;             PG8_LDA(At, 0, 1); PG8_STAGE(PG8_SB(0, 0), b2, voffB); PG8_STAGE(PG8_SB(0, 1), b2 + hstep, voffB); PG8_STAGE(PG8_SA(0, 0), a2, voffA);
;             PG8_WAIT_V(8); PG8_WAIT_L(0); PG8_BAR; PG8_MMA(1, 0, At, B0); PG8_MMA(1, 1, At, B1); PG8_BAR; PG8_SCHED;
.LBB0_1336:
	ds_read_b128 v[152:155], v149
	ds_read_b128 v[156:159], v149 offset:1024
	ds_read_b128 v[160:163], v149 offset:2048
	ds_read_b128 v[164:167], v149 offset:3072
	ds_read_b128 v[168:171], v150
	ds_read_b128 v[172:175], v150 offset:1024
	ds_read_b128 v[176:179], v150 offset:2048
	ds_read_b128 v[180:183], v150 offset:3072
	s_add_i32 m0, s33, 0xc000
	ds_read_b128 v[184:187], v151
	ds_read_b128 v[188:191], v151 offset:1024
	ds_read_b128 v[192:195], v151 offset:2048
	ds_read_b128 v[196:199], v151 offset:3072
	ds_read_b128 v[200:203], v151 offset:4096
	ds_read_b128 v[204:207], v151 offset:5120
	ds_read_b128 v[208:211], v151 offset:6144
	ds_read_b128 v[212:215], v151 offset:7168
	global_load_lds_dwordx4 v136, s[46:47]
	s_add_i32 m0, s33, 0xe000
	s_nop 0
	global_load_lds_dwordx4 v138, s[46:47]
	s_add_u32 s48, s46, 0xfff80080
	s_addc_u32 s49, s47, -1
	s_cmp_eq_u32 s74, 28
	s_cselect_b32 s51, s25, s49
	s_cselect_b32 s50, s29, s48
	s_cselect_b32 s49, s23, s73
	s_cselect_b32 s48, s71, s72
	s_add_i32 s75, s65, s1
	s_mov_b32 m0, s75
	s_waitcnt vmcnt(8)
	s_waitcnt lgkmcnt(0)
	s_setprio 1
	s_barrier
	v_mfma_f32_16x16x32_bf16 v[124:127], v[152:155], v[184:187], v[124:127]
	v_mfma_f32_16x16x32_bf16 v[120:123], v[160:163], v[184:187], v[120:123]
	v_mfma_f32_16x16x32_bf16 v[108:111], v[152:155], v[192:195], v[108:111]
	v_mfma_f32_16x16x32_bf16 v[104:107], v[160:163], v[192:195], v[104:107]
	v_mfma_f32_16x16x32_bf16 v[92:95], v[152:155], v[200:203], v[92:95]
	v_mfma_f32_16x16x32_bf16 v[88:91], v[160:163], v[200:203], v[88:91]
	v_mfma_f32_16x16x32_bf16 v[76:79], v[152:155], v[208:211], v[76:79]
	v_mfma_f32_16x16x32_bf16 v[72:75], v[160:163], v[208:211], v[72:75]
	v_mfma_f32_16x16x32_bf16 v[124:127], v[156:159], v[188:191], v[124:127]
	v_mfma_f32_16x16x32_bf16 v[120:123], v[164:167], v[188:191], v[120:123]
	v_mfma_f32_16x16x32_bf16 v[108:111], v[156:159], v[196:199], v[108:111]
	v_mfma_f32_16x16x32_bf16 v[104:107], v[164:167], v[196:199], v[104:107]
	v_mfma_f32_16x16x32_bf16 v[92:95], v[156:159], v[204:207], v[92:95]
	v_mfma_f32_16x16x32_bf16 v[88:91], v[164:167], v[204:207], v[88:91]
	v_mfma_f32_16x16x32_bf16 v[76:79], v[156:159], v[212:215], v[76:79]
	v_mfma_f32_16x16x32_bf16 v[72:75], v[164:167], v[212:215], v[72:75]
	v_mfma_f32_16x16x32_bf16 v[116:119], v[168:171], v[184:187], v[116:119]
	v_mfma_f32_16x16x32_bf16 v[112:115], v[176:179], v[184:187], v[112:115]
	v_mfma_f32_16x16x32_bf16 v[100:103], v[168:171], v[192:195], v[100:103]
	v_mfma_f32_16x16x32_bf16 v[96:99], v[176:179], v[192:195], v[96:99]
	v_mfma_f32_16x16x32_bf16 v[84:87], v[168:171], v[200:203], v[84:87]
	v_mfma_f32_16x16x32_bf16 v[80:83], v[176:179], v[200:203], v[80:83]
	v_mfma_f32_16x16x32_bf16 v[68:71], v[168:171], v[208:211], v[68:71]
	v_mfma_f32_16x16x32_bf16 v[64:67], v[176:179], v[208:211], v[64:67]
	v_mfma_f32_16x16x32_bf16 v[116:119], v[172:175], v[188:191], v[116:119]
	v_mfma_f32_16x16x32_bf16 v[112:115], v[180:183], v[188:191], v[112:115]
	v_mfma_f32_16x16x32_bf16 v[100:103], v[172:175], v[196:199], v[100:103]
	v_mfma_f32_16x16x32_bf16 v[96:99], v[180:183], v[196:199], v[96:99]
	v_mfma_f32_16x16x32_bf16 v[84:87], v[172:175], v[204:207], v[84:87]
	v_mfma_f32_16x16x32_bf16 v[80:83], v[180:183], v[204:207], v[80:83]
	v_mfma_f32_16x16x32_bf16 v[68:71], v[172:175], v[212:215], v[68:71]
	v_mfma_f32_16x16x32_bf16 v[64:67], v[180:183], v[212:215], v[64:67]
	s_setprio 0
	s_barrier
	ds_read_b128 v[184:187], v151 offset:16384
	ds_read_b128 v[188:191], v151 offset:17408
	ds_read_b128 v[192:195], v151 offset:18432
	ds_read_b128 v[196:199], v151 offset:19456
	ds_read_b128 v[200:203], v151 offset:20480
	ds_read_b128 v[204:207], v151 offset:21504
	ds_read_b128 v[208:211], v151 offset:22528
	ds_read_b128 v[212:215], v151 offset:23552
	global_load_lds_dwordx4 v130, s[48:49]
	s_add_i32 m0, s75, 0x2000
	s_add_u32 s76, s48, 0x80000
	s_addc_u32 s77, s49, 0
	s_add_i32 s75, s66, s1
	global_load_lds_dwordx4 v134, s[48:49]
	s_mov_b32 m0, s75
	s_nop 0
	global_load_lds_dwordx4 v130, s[76:77]
	s_add_i32 m0, s75, 0x2000
	s_nop 0
	global_load_lds_dwordx4 v134, s[76:77]
	s_mov_b32 m0, s33
	s_nop 0
	global_load_lds_dwordx4 v128, s[50:51]
	s_mov_b32 m0, s43
	s_nop 0
	global_load_lds_dwordx4 v132, s[50:51]
	s_waitcnt vmcnt(8)
	s_waitcnt lgkmcnt(0)
	s_setprio 1
	s_barrier
	v_mfma_f32_16x16x32_bf16 v[60:63], v[152:155], v[184:187], v[60:63]
	v_mfma_f32_16x16x32_bf16 v[56:59], v[160:163], v[184:187], v[56:59]
	v_mfma_f32_16x16x32_bf16 v[44:47], v[152:155], v[192:195], v[44:47]
	v_mfma_f32_16x16x32_bf16 v[40:43], v[160:163], v[192:195], v[40:43]
	v_mfma_f32_16x16x32_bf16 v[28:31], v[152:155], v[200:203], v[28:31]
	v_mfma_f32_16x16x32_bf16 v[24:27], v[160:163], v[200:203], v[24:27]
	v_mfma_f32_16x16x32_bf16 v[12:15], v[152:155], v[208:211], v[12:15]
	v_mfma_f32_16x16x32_bf16 v[8:11], v[160:163], v[208:211], v[8:11]
	v_mfma_f32_16x16x32_bf16 v[60:63], v[156:159], v[188:191], v[60:63]
	v_mfma_f32_16x16x32_bf16 v[56:59], v[164:167], v[188:191], v[56:59]
	v_mfma_f32_16x16x32_bf16 v[44:47], v[156:159], v[196:199], v[44:47]
	v_mfma_f32_16x16x32_bf16 v[40:43], v[164:167], v[196:199], v[40:43]
	v_mfma_f32_16x16x32_bf16 v[28:31], v[156:159], v[204:207], v[28:31]
	v_mfma_f32_16x16x32_bf16 v[24:27], v[164:167], v[204:207], v[24:27]
	v_mfma_f32_16x16x32_bf16 v[12:15], v[156:159], v[212:215], v[12:15]
	v_mfma_f32_16x16x32_bf16 v[8:11], v[164:167], v[212:215], v[8:11]
	v_mfma_f32_16x16x32_bf16 v[52:55], v[168:171], v[184:187], v[52:55]
	v_mfma_f32_16x16x32_bf16 v[48:51], v[176:179], v[184:187], v[48:51]
	v_mfma_f32_16x16x32_bf16 v[36:39], v[168:171], v[192:195], v[36:39]
	v_mfma_f32_16x16x32_bf16 v[32:35], v[176:179], v[192:195], v[32:35]
	v_mfma_f32_16x16x32_bf16 v[20:23], v[168:171], v[200:203], v[20:23]
	v_mfma_f32_16x16x32_bf16 v[16:19], v[176:179], v[200:203], v[16:19]
	v_mfma_f32_16x16x32_bf16 v[4:7], v[168:171], v[208:211], v[4:7]
	v_mfma_f32_16x16x32_bf16 v[0:3], v[176:179], v[208:211], v[0:3]
	v_mfma_f32_16x16x32_bf16 v[52:55], v[172:175], v[188:191], v[52:55]
	v_mfma_f32_16x16x32_bf16 v[48:51], v[180:183], v[188:191], v[48:51]
	v_mfma_f32_16x16x32_bf16 v[36:39], v[172:175], v[196:199], v[36:39]
	v_mfma_f32_16x16x32_bf16 v[32:35], v[180:183], v[196:199], v[32:35]
	v_mfma_f32_16x16x32_bf16 v[20:23], v[172:175], v[204:207], v[20:23]
	v_mfma_f32_16x16x32_bf16 v[16:19], v[180:183], v[204:207], v[16:19]
	v_mfma_f32_16x16x32_bf16 v[4:7], v[172:175], v[212:215], v[4:7]
	v_mfma_f32_16x16x32_bf16 v[0:3], v[180:183], v[212:215], v[0:3]
	s_setprio 0
	s_barrier
; #define PG8_STAGE(bufoff, gbase, voff) do { _Pragma("unroll") for (int _i = 0; _i < 2; ++_i) \
;         __builtin_amdgcn_global_load_lds((const unsigned*)((const char*)(gbase) + (voff)[_i]), (PG8_LAS unsigned*)(lds + (bufoff) + ldsw + _i * 8192), 16, 0, 0); } while (0)
; #define PG8_LDA(dst, b, h) do { _Pragma("unroll") for (int m = 0; m < 4; ++m) _Pragma("unroll") for (int k = 0; k < 2; ++k) dst[m][k] = *(const PG8_LAS bf16x8*)(lds + PG8_SA(b, h) + aoff + m * 2048 + k * 1024); } while (0)
; #define PG8_LDB(dst, b, h) do { _Pragma("unroll") for (int n = 0; n < 2; ++n) _Pragma("unroll") for (int k = 0; k < 2; ++k) dst[n][k] = *(const PG8_LAS bf16x8*)(lds + PG8_SB(b, h) + boff + n * 2048 + k * 1024); } while (0)
; #define PG8_MMA(ai, bj, At, Bt) do { __builtin_amdgcn_s_setprio(1); _Pragma("unroll") for (int m = 0; m < 4; ++m) _Pragma("unroll") for (int n = 0; n < 2; ++n) _Pragma("unroll") for (int k = 0; k < 2; ++k) \
;         acc[ai][bj][m][n] = __builtin_amdgcn_mfma_f32_16x16x32_bf16(Bt[n][k], At[m][k], acc[ai][bj][m][n], 0, 0, 0); __builtin_amdgcn_s_setprio(0); } while (0)
; #define PG8_WAIT_V(n) asm volatile("s_waitcnt vmcnt(" #n ")" ::: "memory")
; #define PG8_WAIT_L(n) asm volatile("s_waitcnt lgkmcnt(" #n ")" ::: "memory")
; #define PG8_BAR __builtin_amdgcn_s_barrier()
; #define PG8_SCHED __builtin_amdgcn_sched_barrier(0)
; template <class Epi, class Sched, bool ALIGN_EPI = false, bool SP2 = false>
; __device__ __forceinline__ void gemm_phase(PG8_LAS unsigned char* lds, const Gemm g, const Sched& S, const Epi& E) {
;     ...
;             PG8_LDB(B0, 1, 0); PG8_LDB(B1, 1, 1); PG8_SCHED; PG8_LDA(At, 1, 0); PG8_STAGE(PG8_SA(0, 1), a2 + hstep, voffA);
;             PG8_WAIT_V(8); PG8_WAIT_L(0); PG8_BAR; PG8_MMA(0, 0, At, B0); PG8_MMA(0, 1, At, B1); PG8_BAR; PG8_SCHED;
;             PG8_LDA(At, 1, 1); PG8_STAGE(PG8_SB(1, 0), b3, voffB); PG8_STAGE(PG8_SB(1, 1), b3 + hstep, voffB); PG8_STAGE(PG8_SA(1, 0), a3, voffA);
;             PG8_WAIT_V(8); PG8_WAIT_L(0); PG8_BAR; PG8_MMA(1, 0, At, B0); PG8_MMA(1, 1, At, B1); PG8_BAR; PG8_SCHED;
	ds_read_b128 v[152:155], v216
	ds_read_b128 v[156:159], v216 offset:1024
	ds_read_b128 v[160:163], v216 offset:2048
	ds_read_b128 v[164:167], v216 offset:3072
	ds_read_b128 v[168:171], v217
	ds_read_b128 v[172:175], v217 offset:1024
	ds_read_b128 v[176:179], v217 offset:2048
	ds_read_b128 v[180:183], v217 offset:3072
	ds_read_b128 v[184:187], v151 offset:32768
	ds_read_b128 v[188:191], v151 offset:33792
	ds_read_b128 v[192:195], v151 offset:34816
	ds_read_b128 v[196:199], v151 offset:35840
	ds_read_b128 v[200:203], v151 offset:36864
	ds_read_b128 v[204:207], v151 offset:37888
	ds_read_b128 v[208:211], v151 offset:38912
	ds_read_b128 v[212:215], v151 offset:39936
	s_add_u32 s98, s50, 0x80000
	s_addc_u32 s99, s51, 0
	s_mov_b32 m0, s58
	s_add_u32 s100, s50, 0x80
	s_addc_u32 s101, s51, 0
	global_load_lds_dwordx4 v128, s[98:99]
	s_mov_b32 m0, s59
	s_nop 0
	global_load_lds_dwordx4 v132, s[98:99]
	s_add_i32 s75, 0, 0x18000
	s_add_i32 s76, 0, 0x1c000
	s_add_u32 s98, s48, 0x80
	s_addc_u32 s99, s49, 0
	s_add_i32 s50, s75, s1
	s_mov_b32 m0, s50
	s_waitcnt vmcnt(8)
	s_waitcnt lgkmcnt(0)
	s_setprio 1
	s_barrier
	v_mfma_f32_16x16x32_bf16 v[124:127], v[152:155], v[184:187], v[124:127]
	v_mfma_f32_16x16x32_bf16 v[120:123], v[160:163], v[184:187], v[120:123]
	v_mfma_f32_16x16x32_bf16 v[108:111], v[152:155], v[192:195], v[108:111]
	v_mfma_f32_16x16x32_bf16 v[104:107], v[160:163], v[192:195], v[104:107]
	v_mfma_f32_16x16x32_bf16 v[92:95], v[152:155], v[200:203], v[92:95]
	v_mfma_f32_16x16x32_bf16 v[88:91], v[160:163], v[200:203], v[88:91]
	v_mfma_f32_16x16x32_bf16 v[76:79], v[152:155], v[208:211], v[76:79]
	v_mfma_f32_16x16x32_bf16 v[72:75], v[160:163], v[208:211], v[72:75]
	v_mfma_f32_16x16x32_bf16 v[124:127], v[156:159], v[188:191], v[124:127]
	v_mfma_f32_16x16x32_bf16 v[120:123], v[164:167], v[188:191], v[120:123]
	v_mfma_f32_16x16x32_bf16 v[108:111], v[156:159], v[196:199], v[108:111]
	v_mfma_f32_16x16x32_bf16 v[104:107], v[164:167], v[196:199], v[104:107]
	v_mfma_f32_16x16x32_bf16 v[92:95], v[156:159], v[204:207], v[92:95]
	v_mfma_f32_16x16x32_bf16 v[88:91], v[164:167], v[204:207], v[88:91]
	v_mfma_f32_16x16x32_bf16 v[76:79], v[156:159], v[212:215], v[76:79]
	v_mfma_f32_16x16x32_bf16 v[72:75], v[164:167], v[212:215], v[72:75]
	v_mfma_f32_16x16x32_bf16 v[116:119], v[168:171], v[184:187], v[116:119]
	v_mfma_f32_16x16x32_bf16 v[112:115], v[176:179], v[184:187], v[112:115]
	v_mfma_f32_16x16x32_bf16 v[100:103], v[168:171], v[192:195], v[100:103]
	v_mfma_f32_16x16x32_bf16 v[96:99], v[176:179], v[192:195], v[96:99]
	v_mfma_f32_16x16x32_bf16 v[84:87], v[168:171], v[200:203], v[84:87]
	v_mfma_f32_16x16x32_bf16 v[80:83], v[176:179], v[200:203], v[80:83]
	v_mfma_f32_16x16x32_bf16 v[68:71], v[168:171], v[208:211], v[68:71]
	v_mfma_f32_16x16x32_bf16 v[64:67], v[176:179], v[208:211], v[64:67]
	v_mfma_f32_16x16x32_bf16 v[116:119], v[172:175], v[188:191], v[116:119]
	v_mfma_f32_16x16x32_bf16 v[112:115], v[180:183], v[188:191], v[112:115]
	v_mfma_f32_16x16x32_bf16 v[100:103], v[172:175], v[196:199], v[100:103]
	v_mfma_f32_16x16x32_bf16 v[96:99], v[180:183], v[196:199], v[96:99]
	v_mfma_f32_16x16x32_bf16 v[84:87], v[172:175], v[204:207], v[84:87]
	v_mfma_f32_16x16x32_bf16 v[80:83], v[180:183], v[204:207], v[80:83]
	v_mfma_f32_16x16x32_bf16 v[68:71], v[172:175], v[212:215], v[68:71]
	v_mfma_f32_16x16x32_bf16 v[64:67], v[180:183], v[212:215], v[64:67]
	s_setprio 0
	s_barrier
	ds_read_b128 v[184:187], v151 offset:49152
	ds_read_b128 v[188:191], v151 offset:50176
	ds_read_b128 v[192:195], v151 offset:51200
	ds_read_b128 v[196:199], v151 offset:52224
	ds_read_b128 v[200:203], v151 offset:53248
	ds_read_b128 v[204:207], v151 offset:54272
	ds_read_b128 v[208:211], v151 offset:55296
	ds_read_b128 v[212:215], v151 offset:56320
	global_load_lds_dwordx4 v130, s[98:99]
	s_add_i32 m0, s50, 0x2000
	s_add_u32 s48, s48, 0x80080
	s_addc_u32 s49, s49, 0
	s_add_i32 s50, s76, s1
	global_load_lds_dwordx4 v134, s[98:99]
	s_mov_b32 m0, s50
	s_nop 0
	global_load_lds_dwordx4 v130, s[48:49]
	s_add_i32 m0, s50, 0x2000
	s_nop 0
	global_load_lds_dwordx4 v134, s[48:49]
	s_mov_b32 m0, s61
	s_nop 0
	global_load_lds_dwordx4 v128, s[100:101]
	s_mov_b32 m0, s62
	s_nop 0
	global_load_lds_dwordx4 v132, s[100:101]
	s_add_i32 s74, s74, 2
	s_add_u32 s46, s46, 0x100
	s_addc_u32 s47, s47, 0
	s_add_u32 s72, s72, 0x100
	s_addc_u32 s73, s73, 0
	s_cmp_gt_u32 s74, 29
	s_waitcnt vmcnt(8)
	s_waitcnt lgkmcnt(0)
	s_setprio 1
	s_barrier
	v_mfma_f32_16x16x32_bf16 v[60:63], v[152:155], v[184:187], v[60:63]
	v_mfma_f32_16x16x32_bf16 v[56:59], v[160:163], v[184:187], v[56:59]
	v_mfma_f32_16x16x32_bf16 v[44:47], v[152:155], v[192:195], v[44:47]
	v_mfma_f32_16x16x32_bf16 v[40:43], v[160:163], v[192:195], v[40:43]
	v_mfma_f32_16x16x32_bf16 v[28:31], v[152:155], v[200:203], v[28:31]
	v_mfma_f32_16x16x32_bf16 v[24:27], v[160:163], v[200:203], v[24:27]
	v_mfma_f32_16x16x32_bf16 v[12:15], v[152:155], v[208:211], v[12:15]
	v_mfma_f32_16x16x32_bf16 v[8:11], v[160:163], v[208:211], v[8:11]
	v_mfma_f32_16x16x32_bf16 v[60:63], v[156:159], v[188:191], v[60:63]
	v_mfma_f32_16x16x32_bf16 v[56:59], v[164:167], v[188:191], v[56:59]
	v_mfma_f32_16x16x32_bf16 v[44:47], v[156:159], v[196:199], v[44:47]
	v_mfma_f32_16x16x32_bf16 v[40:43], v[164:167], v[196:199], v[40:43]
	v_mfma_f32_16x16x32_bf16 v[28:31], v[156:159], v[204:207], v[28:31]
	v_mfma_f32_16x16x32_bf16 v[24:27], v[164:167], v[204:207], v[24:27]
	v_mfma_f32_16x16x32_bf16 v[12:15], v[156:159], v[212:215], v[12:15]
	v_mfma_f32_16x16x32_bf16 v[8:11], v[164:167], v[212:215], v[8:11]
	v_mfma_f32_16x16x32_bf16 v[52:55], v[168:171], v[184:187], v[52:55]
	v_mfma_f32_16x16x32_bf16 v[48:51], v[176:179], v[184:187], v[48:51]
	v_mfma_f32_16x16x32_bf16 v[36:39], v[168:171], v[192:195], v[36:39]
	v_mfma_f32_16x16x32_bf16 v[32:35], v[176:179], v[192:195], v[32:35]
	v_mfma_f32_16x16x32_bf16 v[20:23], v[168:171], v[200:203], v[20:23]
	v_mfma_f32_16x16x32_bf16 v[16:19], v[176:179], v[200:203], v[16:19]
	v_mfma_f32_16x16x32_bf16 v[4:7], v[168:171], v[208:211], v[4:7]
	v_mfma_f32_16x16x32_bf16 v[0:3], v[176:179], v[208:211], v[0:3]
	v_mfma_f32_16x16x32_bf16 v[52:55], v[172:175], v[188:191], v[52:55]
	v_mfma_f32_16x16x32_bf16 v[48:51], v[180:183], v[188:191], v[48:51]
	v_mfma_f32_16x16x32_bf16 v[36:39], v[172:175], v[196:199], v[36:39]
	v_mfma_f32_16x16x32_bf16 v[32:35], v[180:183], v[196:199], v[32:35]
	v_mfma_f32_16x16x32_bf16 v[20:23], v[172:175], v[204:207], v[20:23]
	v_mfma_f32_16x16x32_bf16 v[16:19], v[180:183], v[204:207], v[16:19]
	v_mfma_f32_16x16x32_bf16 v[4:7], v[172:175], v[212:215], v[4:7]
	v_mfma_f32_16x16x32_bf16 v[0:3], v[180:183], v[212:215], v[0:3]
	s_setprio 0
	s_barrier
	s_cbranch_scc0 .LBB0_1336
	s_and_b64 vcc, exec, s[12:13]
	s_cbranch_vccz .LBB0_1339
	s_barrier

; #define PG8_STAGE(bufoff, gbase, voff) do { _Pragma("unroll") for (int _i = 0; _i < 2; ++_i) \
;         __builtin_amdgcn_global_load_lds((const unsigned*)((const char*)(gbase) + (voff)[_i]), (PG8_LAS unsigned*)(lds + (bufoff) + ldsw + _i * 8192), 16, 0, 0); } while (0)
; #define PG8_LDA(dst, b, h) do { _Pragma("unroll") for (int m = 0; m < 4; ++m) _Pragma("unroll") for (int k = 0; k < 2; ++k) dst[m][k] = *(const PG8_LAS bf16x8*)(lds + PG8_SA(b, h) + aoff + m * 2048 + k * 1024); } while (0)
; #define PG8_LDB(dst, b, h) do { _Pragma("unroll") for (int n = 0; n < 2; ++n) _Pragma("unroll") for (int k = 0; k < 2; ++k) dst[n][k] = *(const PG8_LAS bf16x8*)(lds + PG8_SB(b, h) + boff + n * 2048 + k * 1024); } while (0)
; #define PG8_MMA(ai, bj, At, Bt) do { __builtin_amdgcn_s_setprio(1); _Pragma("unroll") for (int m = 0; m < 4; ++m) _Pragma("unroll") for (int n = 0; n < 2; ++n) _Pragma("unroll") for (int k = 0; k < 2; ++k) \
;         acc[ai][bj][m][n] = __builtin_amdgcn_mfma_f32_16x16x32_bf16(Bt[n][k], At[m][k], acc[ai][bj][m][n], 0, 0, 0); __builtin_amdgcn_s_setprio(0); } while (0)
; #define PG8_WAIT_V(n) asm volatile("s_waitcnt vmcnt(" #n ")" ::: "memory")
; #define PG8_WAIT_L(n) asm volatile("s_waitcnt lgkmcnt(" #n ")" ::: "memory")
; template <class Epi, class Sched, bool ALIGN_EPI = false, bool SP2 = false>
; __device__ __forceinline__ void gemm_phase(PG8_LAS unsigned char* lds, const Gemm g, const Sched& S, const Epi& E) {
;     ...
;             const bool last = (t == nt - 2);
;             const char* a1 = cA + (size_t)(t + 1) * kstep;
;             const char* a2 = last ? nA : cA + (size_t)(t + 2) * kstep; const char* b2 = last ? nB : cB + (size_t)(t + 2) * kstep;
;             const char* a3 = a2 + kstep; const char* b3 = b2 + kstep;
;             if (last && has_next) S.a_ready(nxt);
;             if constexpr (SP2) {
;             PG8_LDB(B0, 0, 0); PG8_LDB(B1, 0, 1); PG8_SCHED; PG8_LDA(At, 0, 0); PG8_STAGE(PG8_SA(1, 1), a1 + hstep, voffA);
;             PG8_WAIT_V(8); PG8_WAIT_L(0); PG8_BAR; PG8_MMA(0, 0, At, B0); PG8_MMA(0, 1, At, B1); PG8_BAR; PG8_SCHED;
;             PG8_LDA(At, 0, 1); PG8_STAGE(PG8_SB(0, 0), b2, voffB); PG8_STAGE(PG8_SB(0, 1), b2 + hstep, voffB); PG8_STAGE(PG8_SA(0, 0), a2, voffA);
;             PG8_WAIT_V(8); PG8_WAIT_L(0); PG8_BAR; PG8_MMA(1, 0, At, B0); PG8_MMA(1, 1, At, B1); PG8_BAR; PG8_SCHED;
.LBB0_1412:
	ds_read_b128 v[128:131], v202
	ds_read_b128 v[132:135], v202 offset:1024
	ds_read_b128 v[136:139], v202 offset:2048
	ds_read_b128 v[140:143], v202 offset:3072
	ds_read_b128 v[144:147], v203
	ds_read_b128 v[148:151], v203 offset:1024
	ds_read_b128 v[152:155], v203 offset:2048
	ds_read_b128 v[156:159], v203 offset:3072
	s_add_i32 m0, s33, 0xc000
	ds_read_b128 v[160:163], v204
	ds_read_b128 v[164:167], v204 offset:1024
	ds_read_b128 v[184:187], v204 offset:2048
	ds_read_b128 v[188:191], v204 offset:3072
	ds_read_b128 v[192:195], v204 offset:4096
	ds_read_b128 v[206:209], v204 offset:5120
	ds_read_b128 v[210:213], v204 offset:6144
	ds_read_b128 v[214:217], v204 offset:7168
	global_load_lds_dwordx4 v176, s[42:43]
	s_add_i32 m0, s33, 0xe000
	s_nop 0
	global_load_lds_dwordx4 v178, s[42:43]
	s_add_u32 s46, s42, 0xffe00080
	s_addc_u32 s47, s43, -1
	s_cmpk_eq_i32 s68, 0x7c
	s_cselect_b32 s49, s23, s47
	s_cselect_b32 s48, s25, s46
	s_cselect_b32 s47, s21, s67
	s_cselect_b32 s46, s65, s66
	s_add_i32 s69, s63, s1
	s_mov_b32 m0, s69
	s_waitcnt vmcnt(8)
	s_waitcnt lgkmcnt(0)
	s_setprio 1
	s_barrier
	v_mfma_f32_16x16x32_bf16 v[124:127], v[128:131], v[160:163], v[124:127]
	v_mfma_f32_16x16x32_bf16 v[120:123], v[136:139], v[160:163], v[120:123]
	v_mfma_f32_16x16x32_bf16 v[116:119], v[128:131], v[184:187], v[116:119]
	v_mfma_f32_16x16x32_bf16 v[108:111], v[136:139], v[184:187], v[108:111]
	v_mfma_f32_16x16x32_bf16 v[92:95], v[128:131], v[192:195], v[92:95]
	v_mfma_f32_16x16x32_bf16 v[88:91], v[136:139], v[192:195], v[88:91]
	v_mfma_f32_16x16x32_bf16 v[76:79], v[128:131], v[210:213], v[76:79]
	v_mfma_f32_16x16x32_bf16 v[72:75], v[136:139], v[210:213], v[72:75]
	v_mfma_f32_16x16x32_bf16 v[124:127], v[132:135], v[164:167], v[124:127]
	v_mfma_f32_16x16x32_bf16 v[120:123], v[140:143], v[164:167], v[120:123]
	v_mfma_f32_16x16x32_bf16 v[116:119], v[132:135], v[188:191], v[116:119]
	v_mfma_f32_16x16x32_bf16 v[108:111], v[140:143], v[188:191], v[108:111]
	v_mfma_f32_16x16x32_bf16 v[92:95], v[132:135], v[206:209], v[92:95]
	v_mfma_f32_16x16x32_bf16 v[88:91], v[140:143], v[206:209], v[88:91]
	v_mfma_f32_16x16x32_bf16 v[76:79], v[132:135], v[214:217], v[76:79]
	v_mfma_f32_16x16x32_bf16 v[72:75], v[140:143], v[214:217], v[72:75]
	v_mfma_f32_16x16x32_bf16 v[112:115], v[144:147], v[160:163], v[112:115]
	v_mfma_f32_16x16x32_bf16 v[104:107], v[152:155], v[160:163], v[104:107]
	v_mfma_f32_16x16x32_bf16 v[100:103], v[144:147], v[184:187], v[100:103]
	v_mfma_f32_16x16x32_bf16 v[96:99], v[152:155], v[184:187], v[96:99]
	v_mfma_f32_16x16x32_bf16 v[84:87], v[144:147], v[192:195], v[84:87]
	v_mfma_f32_16x16x32_bf16 v[80:83], v[152:155], v[192:195], v[80:83]
	v_mfma_f32_16x16x32_bf16 v[68:71], v[144:147], v[210:213], v[68:71]
	v_mfma_f32_16x16x32_bf16 v[64:67], v[152:155], v[210:213], v[64:67]
	v_mfma_f32_16x16x32_bf16 v[112:115], v[148:151], v[164:167], v[112:115]
	v_mfma_f32_16x16x32_bf16 v[104:107], v[156:159], v[164:167], v[104:107]
	v_mfma_f32_16x16x32_bf16 v[100:103], v[148:151], v[188:191], v[100:103]
	v_mfma_f32_16x16x32_bf16 v[96:99], v[156:159], v[188:191], v[96:99]
	v_mfma_f32_16x16x32_bf16 v[84:87], v[148:151], v[206:209], v[84:87]
	v_mfma_f32_16x16x32_bf16 v[80:83], v[156:159], v[206:209], v[80:83]
	v_mfma_f32_16x16x32_bf16 v[68:71], v[148:151], v[214:217], v[68:71]
	v_mfma_f32_16x16x32_bf16 v[64:67], v[156:159], v[214:217], v[64:67]
	s_setprio 0
	s_barrier
	ds_read_b128 v[160:163], v204 offset:16384
	ds_read_b128 v[164:167], v204 offset:17408
	ds_read_b128 v[184:187], v204 offset:18432
	ds_read_b128 v[188:191], v204 offset:19456
	ds_read_b128 v[192:195], v204 offset:20480
	ds_read_b128 v[206:209], v204 offset:21504
	ds_read_b128 v[210:213], v204 offset:22528
	ds_read_b128 v[214:217], v204 offset:23552
	global_load_lds_dwordx4 v170, s[46:47]
	s_add_i32 m0, s69, 0x2000
	s_add_u32 s70, s46, 0x200000
	s_addc_u32 s71, s47, 0
	s_add_i32 s69, s64, s1
	global_load_lds_dwordx4 v174, s[46:47]
	s_mov_b32 m0, s69
	s_nop 0
	global_load_lds_dwordx4 v170, s[70:71]
	s_add_i32 m0, s69, 0x2000
	s_nop 0
	global_load_lds_dwordx4 v174, s[70:71]
	s_mov_b32 m0, s33
	s_nop 0
	global_load_lds_dwordx4 v168, s[48:49]
	s_mov_b32 m0, s41
	s_nop 0
	global_load_lds_dwordx4 v172, s[48:49]
	s_waitcnt vmcnt(8)
	s_waitcnt lgkmcnt(0)
	s_setprio 1
	s_barrier
	v_mfma_f32_16x16x32_bf16 v[60:63], v[128:131], v[160:163], v[60:63]
	v_mfma_f32_16x16x32_bf16 v[56:59], v[136:139], v[160:163], v[56:59]
	v_mfma_f32_16x16x32_bf16 v[44:47], v[128:131], v[184:187], v[44:47]
	v_mfma_f32_16x16x32_bf16 v[40:43], v[136:139], v[184:187], v[40:43]
	v_mfma_f32_16x16x32_bf16 v[28:31], v[128:131], v[192:195], v[28:31]
	v_mfma_f32_16x16x32_bf16 v[24:27], v[136:139], v[192:195], v[24:27]
	v_mfma_f32_16x16x32_bf16 v[12:15], v[128:131], v[210:213], v[12:15]
	v_mfma_f32_16x16x32_bf16 v[8:11], v[136:139], v[210:213], v[8:11]
	v_mfma_f32_16x16x32_bf16 v[60:63], v[132:135], v[164:167], v[60:63]
	v_mfma_f32_16x16x32_bf16 v[56:59], v[140:143], v[164:167], v[56:59]
	v_mfma_f32_16x16x32_bf16 v[44:47], v[132:135], v[188:191], v[44:47]
	v_mfma_f32_16x16x32_bf16 v[40:43], v[140:143], v[188:191], v[40:43]
	v_mfma_f32_16x16x32_bf16 v[28:31], v[132:135], v[206:209], v[28:31]
	v_mfma_f32_16x16x32_bf16 v[24:27], v[140:143], v[206:209], v[24:27]
	v_mfma_f32_16x16x32_bf16 v[12:15], v[132:135], v[214:217], v[12:15]
	v_mfma_f32_16x16x32_bf16 v[8:11], v[140:143], v[214:217], v[8:11]
	v_mfma_f32_16x16x32_bf16 v[52:55], v[144:147], v[160:163], v[52:55]
	v_mfma_f32_16x16x32_bf16 v[48:51], v[152:155], v[160:163], v[48:51]
	v_mfma_f32_16x16x32_bf16 v[36:39], v[144:147], v[184:187], v[36:39]
	v_mfma_f32_16x16x32_bf16 v[32:35], v[152:155], v[184:187], v[32:35]
	v_mfma_f32_16x16x32_bf16 v[20:23], v[144:147], v[192:195], v[20:23]
	v_mfma_f32_16x16x32_bf16 v[16:19], v[152:155], v[192:195], v[16:19]
	v_mfma_f32_16x16x32_bf16 v[4:7], v[144:147], v[210:213], v[4:7]
	v_mfma_f32_16x16x32_bf16 v[0:3], v[152:155], v[210:213], v[0:3]
	v_mfma_f32_16x16x32_bf16 v[52:55], v[148:151], v[164:167], v[52:55]
	v_mfma_f32_16x16x32_bf16 v[48:51], v[156:159], v[164:167], v[48:51]
	v_mfma_f32_16x16x32_bf16 v[36:39], v[148:151], v[188:191], v[36:39]
	v_mfma_f32_16x16x32_bf16 v[32:35], v[156:159], v[188:191], v[32:35]
	v_mfma_f32_16x16x32_bf16 v[20:23], v[148:151], v[206:209], v[20:23]
	v_mfma_f32_16x16x32_bf16 v[16:19], v[156:159], v[206:209], v[16:19]
	v_mfma_f32_16x16x32_bf16 v[4:7], v[148:151], v[214:217], v[4:7]
	v_mfma_f32_16x16x32_bf16 v[0:3], v[156:159], v[214:217], v[0:3]
	s_setprio 0
	s_barrier
; #define PG8_STAGE(bufoff, gbase, voff) do { _Pragma("unroll") for (int _i = 0; _i < 2; ++_i) \
;         __builtin_amdgcn_global_load_lds((const unsigned*)((const char*)(gbase) + (voff)[_i]), (PG8_LAS unsigned*)(lds + (bufoff) + ldsw + _i * 8192), 16, 0, 0); } while (0)
; #define PG8_LDA(dst, b, h) do { _Pragma("unroll") for (int m = 0; m < 4; ++m) _Pragma("unroll") for (int k = 0; k < 2; ++k) dst[m][k] = *(const PG8_LAS bf16x8*)(lds + PG8_SA(b, h) + aoff + m * 2048 + k * 1024); } while (0)
; #define PG8_LDB(dst, b, h) do { _Pragma("unroll") for (int n = 0; n < 2; ++n) _Pragma("unroll") for (int k = 0; k < 2; ++k) dst[n][k] = *(const PG8_LAS bf16x8*)(lds + PG8_SB(b, h) + boff + n * 2048 + k * 1024); } while (0)
; #define PG8_MMA(ai, bj, At, Bt) do { __builtin_amdgcn_s_setprio(1); _Pragma("unroll") for (int m = 0; m < 4; ++m) _Pragma("unroll") for (int n = 0; n < 2; ++n) _Pragma("unroll") for (int k = 0; k < 2; ++k) \
;         acc[ai][bj][m][n] = __builtin_amdgcn_mfma_f32_16x16x32_bf16(Bt[n][k], At[m][k], acc[ai][bj][m][n], 0, 0, 0); __builtin_amdgcn_s_setprio(0); } while (0)
; #define PG8_WAIT_V(n) asm volatile("s_waitcnt vmcnt(" #n ")" ::: "memory")
; #define PG8_WAIT_L(n) asm volatile("s_waitcnt lgkmcnt(" #n ")" ::: "memory")
; #define PG8_BAR __builtin_amdgcn_s_barrier()
; #define PG8_SCHED __builtin_amdgcn_sched_barrier(0)
; template <class Epi, class Sched, bool ALIGN_EPI = false, bool SP2 = false>
; __device__ __forceinline__ void gemm_phase(PG8_LAS unsigned char* lds, const Gemm g, const Sched& S, const Epi& E) {
;     ...
;             PG8_LDB(B0, 1, 0); PG8_LDB(B1, 1, 1); PG8_SCHED; PG8_LDA(At, 1, 0); PG8_STAGE(PG8_SA(0, 1), a2 + hstep, voffA);
;             PG8_WAIT_V(8); PG8_WAIT_L(0); PG8_BAR; PG8_MMA(0, 0, At, B0); PG8_MMA(0, 1, At, B1); PG8_BAR; PG8_SCHED;
;             PG8_LDA(At, 1, 1); PG8_STAGE(PG8_SB(1, 0), b3, voffB); PG8_STAGE(PG8_SB(1, 1), b3 + hstep, voffB); PG8_STAGE(PG8_SA(1, 0), a3, voffA);
;             PG8_WAIT_V(8); PG8_WAIT_L(0); PG8_BAR; PG8_MMA(1, 0, At, B0); PG8_MMA(1, 1, At, B1); PG8_BAR; PG8_SCHED;
	ds_read_b128 v[128:131], v218
	ds_read_b128 v[132:135], v218 offset:1024
	ds_read_b128 v[136:139], v218 offset:2048
	ds_read_b128 v[140:143], v218 offset:3072
	ds_read_b128 v[144:147], v219
	ds_read_b128 v[148:151], v219 offset:1024
	ds_read_b128 v[152:155], v219 offset:2048
	ds_read_b128 v[156:159], v219 offset:3072
	ds_read_b128 v[160:163], v204 offset:32768
	ds_read_b128 v[164:167], v204 offset:33792
	ds_read_b128 v[184:187], v204 offset:34816
	ds_read_b128 v[188:191], v204 offset:35840
	ds_read_b128 v[192:195], v204 offset:36864
	ds_read_b128 v[206:209], v204 offset:37888
	ds_read_b128 v[210:213], v204 offset:38912
	ds_read_b128 v[214:217], v204 offset:39936
	s_add_u32 s98, s48, 0x200000
	s_addc_u32 s99, s49, 0
	s_mov_b32 m0, s50
	s_add_u32 s100, s48, 0x80
	s_addc_u32 s101, s49, 0
	global_load_lds_dwordx4 v168, s[98:99]
	s_mov_b32 m0, s51
	s_nop 0
	global_load_lds_dwordx4 v172, s[98:99]
	s_add_i32 s69, 0, 0x18000
	s_add_i32 s70, 0, 0x1c000
	s_add_u32 s98, s46, 0x80
	s_addc_u32 s99, s47, 0
	s_add_i32 s48, s69, s1
	s_mov_b32 m0, s48
	s_waitcnt vmcnt(8)
	s_waitcnt lgkmcnt(0)
	s_setprio 1
	s_barrier
	v_mfma_f32_16x16x32_bf16 v[124:127], v[128:131], v[160:163], v[124:127]
	v_mfma_f32_16x16x32_bf16 v[120:123], v[136:139], v[160:163], v[120:123]
	v_mfma_f32_16x16x32_bf16 v[116:119], v[128:131], v[184:187], v[116:119]
	v_mfma_f32_16x16x32_bf16 v[108:111], v[136:139], v[184:187], v[108:111]
	v_mfma_f32_16x16x32_bf16 v[92:95], v[128:131], v[192:195], v[92:95]
	v_mfma_f32_16x16x32_bf16 v[88:91], v[136:139], v[192:195], v[88:91]
	v_mfma_f32_16x16x32_bf16 v[76:79], v[128:131], v[210:213], v[76:79]
	v_mfma_f32_16x16x32_bf16 v[72:75], v[136:139], v[210:213], v[72:75]
	v_mfma_f32_16x16x32_bf16 v[124:127], v[132:135], v[164:167], v[124:127]
	v_mfma_f32_16x16x32_bf16 v[120:123], v[140:143], v[164:167], v[120:123]
	v_mfma_f32_16x16x32_bf16 v[116:119], v[132:135], v[188:191], v[116:119]
	v_mfma_f32_16x16x32_bf16 v[108:111], v[140:143], v[188:191], v[108:111]
	v_mfma_f32_16x16x32_bf16 v[92:95], v[132:135], v[206:209], v[92:95]
	v_mfma_f32_16x16x32_bf16 v[88:91], v[140:143], v[206:209], v[88:91]
	v_mfma_f32_16x16x32_bf16 v[76:79], v[132:135], v[214:217], v[76:79]
	v_mfma_f32_16x16x32_bf16 v[72:75], v[140:143], v[214:217], v[72:75]
	v_mfma_f32_16x16x32_bf16 v[112:115], v[144:147], v[160:163], v[112:115]
	v_mfma_f32_16x16x32_bf16 v[104:107], v[152:155], v[160:163], v[104:107]
	v_mfma_f32_16x16x32_bf16 v[100:103], v[144:147], v[184:187], v[100:103]
	v_mfma_f32_16x16x32_bf16 v[96:99], v[152:155], v[184:187], v[96:99]
	v_mfma_f32_16x16x32_bf16 v[84:87], v[144:147], v[192:195], v[84:87]
	v_mfma_f32_16x16x32_bf16 v[80:83], v[152:155], v[192:195], v[80:83]
	v_mfma_f32_16x16x32_bf16 v[68:71], v[144:147], v[210:213], v[68:71]
	v_mfma_f32_16x16x32_bf16 v[64:67], v[152:155], v[210:213], v[64:67]
	v_mfma_f32_16x16x32_bf16 v[112:115], v[148:151], v[164:167], v[112:115]
	v_mfma_f32_16x16x32_bf16 v[104:107], v[156:159], v[164:167], v[104:107]
	v_mfma_f32_16x16x32_bf16 v[100:103], v[148:151], v[188:191], v[100:103]
	v_mfma_f32_16x16x32_bf16 v[96:99], v[156:159], v[188:191], v[96:99]
	v_mfma_f32_16x16x32_bf16 v[84:87], v[148:151], v[206:209], v[84:87]
	v_mfma_f32_16x16x32_bf16 v[80:83], v[156:159], v[206:209], v[80:83]
	v_mfma_f32_16x16x32_bf16 v[68:71], v[148:151], v[214:217], v[68:71]
	v_mfma_f32_16x16x32_bf16 v[64:67], v[156:159], v[214:217], v[64:67]
	s_setprio 0
	s_barrier
	ds_read_b128 v[160:163], v204 offset:49152
	ds_read_b128 v[164:167], v204 offset:50176
	ds_read_b128 v[184:187], v204 offset:51200
	ds_read_b128 v[188:191], v204 offset:52224
	ds_read_b128 v[192:195], v204 offset:53248
	ds_read_b128 v[206:209], v204 offset:54272
	ds_read_b128 v[210:213], v204 offset:55296
	ds_read_b128 v[214:217], v204 offset:56320
	global_load_lds_dwordx4 v170, s[98:99]
	s_add_i32 m0, s48, 0x2000
	s_add_u32 s46, s46, 0x200080
	s_addc_u32 s47, s47, 0
	s_add_i32 s48, s70, s1
	global_load_lds_dwordx4 v174, s[98:99]
	s_mov_b32 m0, s48
	s_nop 0
	global_load_lds_dwordx4 v170, s[46:47]
	s_add_i32 m0, s48, 0x2000
	s_nop 0
	global_load_lds_dwordx4 v174, s[46:47]
	s_mov_b32 m0, s59
	s_nop 0
	global_load_lds_dwordx4 v168, s[100:101]
	s_mov_b32 m0, s60
	s_nop 0
	global_load_lds_dwordx4 v172, s[100:101]
	s_add_i32 s68, s68, 2
	s_add_u32 s42, s42, 0x100
	s_addc_u32 s43, s43, 0
	s_add_u32 s66, s66, 0x100
	s_addc_u32 s67, s67, 0
	s_cmpk_gt_u32 s68, 0x7d
	s_waitcnt vmcnt(8)
	s_waitcnt lgkmcnt(0)
	s_setprio 1
	s_barrier
	v_mfma_f32_16x16x32_bf16 v[60:63], v[128:131], v[160:163], v[60:63]
	v_mfma_f32_16x16x32_bf16 v[56:59], v[136:139], v[160:163], v[56:59]
	v_mfma_f32_16x16x32_bf16 v[44:47], v[128:131], v[184:187], v[44:47]
	v_mfma_f32_16x16x32_bf16 v[40:43], v[136:139], v[184:187], v[40:43]
	v_mfma_f32_16x16x32_bf16 v[28:31], v[128:131], v[192:195], v[28:31]
	v_mfma_f32_16x16x32_bf16 v[24:27], v[136:139], v[192:195], v[24:27]
	v_mfma_f32_16x16x32_bf16 v[12:15], v[128:131], v[210:213], v[12:15]
	v_mfma_f32_16x16x32_bf16 v[8:11], v[136:139], v[210:213], v[8:11]
	v_mfma_f32_16x16x32_bf16 v[60:63], v[132:135], v[164:167], v[60:63]
	v_mfma_f32_16x16x32_bf16 v[56:59], v[140:143], v[164:167], v[56:59]
	v_mfma_f32_16x16x32_bf16 v[44:47], v[132:135], v[188:191], v[44:47]
	v_mfma_f32_16x16x32_bf16 v[40:43], v[140:143], v[188:191], v[40:43]
	v_mfma_f32_16x16x32_bf16 v[28:31], v[132:135], v[206:209], v[28:31]
	v_mfma_f32_16x16x32_bf16 v[24:27], v[140:143], v[206:209], v[24:27]
	v_mfma_f32_16x16x32_bf16 v[12:15], v[132:135], v[214:217], v[12:15]
	v_mfma_f32_16x16x32_bf16 v[8:11], v[140:143], v[214:217], v[8:11]
	v_mfma_f32_16x16x32_bf16 v[52:55], v[144:147], v[160:163], v[52:55]
	v_mfma_f32_16x16x32_bf16 v[48:51], v[152:155], v[160:163], v[48:51]
	v_mfma_f32_16x16x32_bf16 v[36:39], v[144:147], v[184:187], v[36:39]
	v_mfma_f32_16x16x32_bf16 v[32:35], v[152:155], v[184:187], v[32:35]
	v_mfma_f32_16x16x32_bf16 v[20:23], v[144:147], v[192:195], v[20:23]
	v_mfma_f32_16x16x32_bf16 v[16:19], v[152:155], v[192:195], v[16:19]
	v_mfma_f32_16x16x32_bf16 v[4:7], v[144:147], v[210:213], v[4:7]
	v_mfma_f32_16x16x32_bf16 v[0:3], v[152:155], v[210:213], v[0:3]
	v_mfma_f32_16x16x32_bf16 v[52:55], v[148:151], v[164:167], v[52:55]
	v_mfma_f32_16x16x32_bf16 v[48:51], v[156:159], v[164:167], v[48:51]
	v_mfma_f32_16x16x32_bf16 v[36:39], v[148:151], v[188:191], v[36:39]
	v_mfma_f32_16x16x32_bf16 v[32:35], v[156:159], v[188:191], v[32:35]
	v_mfma_f32_16x16x32_bf16 v[20:23], v[148:151], v[206:209], v[20:23]
	v_mfma_f32_16x16x32_bf16 v[16:19], v[156:159], v[206:209], v[16:19]
	v_mfma_f32_16x16x32_bf16 v[4:7], v[148:151], v[214:217], v[4:7]
	v_mfma_f32_16x16x32_bf16 v[0:3], v[156:159], v[214:217], v[0:3]
	s_setprio 0
	s_barrier
	s_cbranch_scc0 .LBB0_1412
	s_and_b64 vcc, exec, s[10:11]
	s_cbranch_vccz .LBB0_1415
	s_barrier
